# P9 last round: every workgroup computes half a unit (128 of 256 tile rows) and shares the w_down transposes, instead of 128 full units + 128 filler workgroups
# baseline (speedup 1.0000x reference)
;     __device__ __forceinline__ bool next(int i, Unit& u) const { return decode(i * G + c, u); }
; #define PG8_STAGE(bufoff, gbase, voff) do { _Pragma("unroll") for (int _i = 0; _i < 2; ++_i) \
;         __builtin_amdgcn_global_load_lds((const unsigned*)((const char*)(gbase) + (voff)[_i]), (LAS unsigned*)(lds + (bufoff) + ldsw + _i * 8192), 16, 0, 0); } while (0)
; #define PG8_WAIT_V(n) asm volatile("s_waitcnt vmcnt(" #n ")" ::: "memory")
; #define PG8_BAR __builtin_amdgcn_s_barrier()
; template <class Epi, class Sched, bool DEFER>
; __device__ __forceinline__ void gemm_fast_core(LAS unsigned char* lds, const GemmP g, const Sched& S, const Epi& E, f32x4 (&acc)[2][2][4][2], Unit& cur) {
;     ...
;     const int wid = __builtin_amdgcn_readfirstlane(tid >> 6), lane = tid & 63, wr = wid >> 2, wc = wid & 3, fr = lane & 15, fq = lane >> 4;
;     const int K = g.K, nt = K / BK;
;     unsigned voffA[2], voffB[2];
; #pragma unroll
;     for (int i = 0; i < 2; ++i) { int R, C; stage_rc(tid * 16 + i * 8192, R, C); voffA[i] = (unsigned)(R * g.lda + C) * 2u; voffB[i] = (unsigned)(R * g.ldb + C) * 2u; }
;     const size_t kstep = (size_t)(BK * 2);
;     const size_t hstepA = (size_t)HALF * g.lda * 2, hstepB = (size_t)HALF * g.ldb * 2;
;     const unsigned ldsw = (unsigned)wid * 1024u;
;     const int aoff = lds_byte(wr * 64 + fr, fq * 8), boff = lds_byte(wc * 32 + fr, fq * 8);
;     ...
;     Unit nxt; int ui = 0;
;     if (!S.next(0, cur)) return;
; #pragma unroll
;     for (int a = 0; a < 2; ++a)
; #pragma unroll
;         for (int b = 0; b < 2; ++b)
; #pragma unroll
;             for (int m = 0; m < 4; ++m)
; #pragma unroll
;                 for (int n = 0; n < 2; ++n) acc[a][b][m][n] = (f32x4){0.f, 0.f, 0.f, 0.f};
;     bf16x8 At[4][2], B0[2][2], B1[2][2];
;     const char* cA = (const char*)g.aptr(cur); const char* cB = (const char*)g.bptr(cur);
;     PG8_STAGE(PG8_SB(0, 0), cB, voffB); PG8_STAGE(PG8_SB(0, 1), cB + hstepB, voffB); PG8_STAGE(PG8_SA(0, 0), cA, voffA); PG8_STAGE(PG8_SA(0, 1), cA + hstepA, voffA);
;     if (wr == 1) PG8_BAR;
;     PG8_WAIT_V(2); PG8_BAR;
;     PG8_STAGE(PG8_SB(1, 0), cB + kstep, voffB); PG8_STAGE(PG8_SA(1, 0), cA + kstep, voffA); PG8_STAGE(PG8_SB(1, 1), cB + hstepB + kstep, voffB);
;     PG8_WAIT_V(6); PG8_BAR;
.LBB0_1793:
	s_lshl_b32 s7, s7, 5
	s_mov_b64 s[8:9], 0x80
	s_and_b32 s16, s7, 0x60
	s_add_i32 m0, s27, 0x18000
	v_lshl_add_u64 v[6:7], v[6:7], 0, s[8:9]
	s_lshl_b32 s12, s6, 13
	s_lshl_b32 s7, s16, 7
	s_waitcnt vmcnt(2)
	s_barrier
	global_load_lds_dwordx4 v[6:7], off
	v_lshl_add_u64 v[4:5], v[4:5], 0, s[8:9]
	s_add_i32 m0, s27, 0x1a000
	s_add_i32 s42, s27, 0x8000
	s_add_i32 s43, s27, 0xa000
	global_load_lds_dwordx4 v[4:5], off
	v_lshl_add_u64 v[0:1], v[0:1], 0, s[8:9]
	s_mov_b32 m0, s42
	s_add_u32 s10, s30, 0x80080
	global_load_lds_dwordx4 v[0:1], off
	v_lshl_add_u64 v[0:1], v[2:3], 0, s[8:9]
	s_mov_b32 m0, s43
	s_addc_u32 s11, s31, 0
	global_load_lds_dwordx4 v[0:1], off
	s_add_i32 m0, s27, 0x1c000
	v_lshl_add_u64 v[0:1], s[10:11], 0, v[162:163]
	global_load_lds_dwordx4 v[0:1], off
	v_lshl_add_u64 v[0:1], s[10:11], 0, v[160:161]
	s_add_i32 m0, s27, 0x1e000
	v_lshlrev_b32_e32 v3, 2, v11
	global_load_lds_dwordx4 v[0:1], off
	v_bfe_u32 v1, v11, 4, 2
	v_and_b32_e32 v0, 15, v11
	v_lshlrev_b32_e32 v2, 4, v1
	v_lshl_or_b32 v2, v0, 6, v2
	v_and_b32_e32 v3, 32, v3
	s_sext_i32_i16 s33, s4
	v_lshl_or_b32 v195, s6, 6, v0
	v_bitop3_b32 v196, v2, s7, v3 bitop3:0xde
	s_cmpk_lt_u32 s5, 0x100
	v_cmp_eq_u32_e64 s[4:5], 15, v0
	v_cmp_eq_u32_e64 s[6:7], 0, v0
	v_lshlrev_b32_e32 v0, 15, v12
	v_and_b32_e32 v0, 0xffff0000, v0
	v_lshl_or_b32 v204, v1, 2, s16
	v_lshl_add_u32 v0, v13, 12, v0
	v_and_b32_e32 v1, 1, v12
	v_lshl_or_b32 v0, v1, 6, v0
	v_bitop3_b32 v4, v2, s12, v3 bitop3:0xde
	s_cselect_b64 s[10:11], -1, 0
	s_add_u32 s12, s56, 0xb000
	v_lshl_add_u32 v164, v14, 1, v0
	v_lshlrev_b32_e32 v0, 15, v8
	s_addc_u32 s13, s57, 0
	v_and_b32_e32 v0, 0xffff0000, v0
	s_waitcnt vmcnt(6)
	s_add_u32 s14, s56, 0x16000
	v_lshl_add_u32 v0, v9, 12, v0
	v_and_b32_e32 v1, 1, v8
	s_addc_u32 s15, s57, 0
	v_lshl_or_b32 v0, v1, 6, v0
	s_add_i32 s44, 0, 0x10000
	s_add_i32 s45, 0, 0x14000
	v_or_b32_e32 v197, 16, v195
	v_or_b32_e32 v198, 32, v195
	v_or_b32_e32 v199, 48, v195
	v_add_u32_e32 v200, 0x80, v195
	v_add_u32_e32 v201, 0x90, v195
	v_add_u32_e32 v202, 0xa0, v195
	v_add_u32_e32 v203, 0xb0, v195
	v_mov_b32_e32 v165, v163
	v_lshl_add_u32 v166, v10, 1, v0
	v_mov_b32_e32 v167, v163
	v_add_u32_e32 v205, s44, v196
	v_add_u32_e32 v206, s45, v196
	v_add_u32_e32 v207, 0, v4
	s_movk_i32 s46, 0x2c00
	s_barrier
	s_mov_b32 s98, 0
	s_mov_b32 s99, 0
	s_branch .LBB0_1796

;     __device__ __forceinline__ bool decode(int L, Unit& u) const {
;         const int nwg = nMt * nN; if (L >= nwg) return false;
;         int wgid = L; { const int q = nwg / NXCD, r = nwg % NXCD, xcd = wgid % NXCD, off = wgid / NXCD; wgid = (xcd < r ? xcd * (q + 1) : r * (q + 1) + (xcd - r) * q) + off; }
;         const int nig = WGM * nN, gid = wgid / nig, fm = gid * WGM, gsz = (nMt - fm) < WGM ? (nMt - fm) : WGM;
;         const int pmt = fm + ((wgid % nig) % gsz); u.pn = (wgid % nig) / gsz; u.bz = pmt / nMb; u.pm = pmt % nMb; return true;
;     }
;     __device__ __forceinline__ bool next(int i, Unit& u) const { return decode(i * G + c, u); }
; template <class Epi, class Sched, bool DEFER>
; __device__ __forceinline__ void gemm_fast_core(LAS unsigned char* lds, const GemmP g, const Sched& S, const Epi& E, f32x4 (&acc)[2][2][4][2], Unit& cur) {
;     ...
;         const bool has_next = S.next(ui + 1, nxt);
;         const char* nA = has_next ? (const char*)g.aptr(nxt) : cA; const char* nB = has_next ? (const char*)g.bptr(nxt) : cB;
.LBB0_1795:
	s_mov_b32 s98, s99
	s_andn2_b64 vcc, exec, s[20:21]
	s_mov_b32 s33, s16
	s_mov_b32 s26, s18
	s_mov_b64 s[30:31], s[24:25]
	s_mov_b64 s[28:29], s[22:23]
	s_cbranch_vccz .LBB0_1805
.LBB0_1796:
	s_add_i32 s41, s41, 1
	s_mul_i32 s17, s41, s68
	s_add_i32 s17, s17, s88
	s_mov_b32 s99, 0
	s_cmp_lg_u32 s41, 5
	s_cbranch_scc1 .Lp9h_nolast
	s_lshr_b32 s17, s88, 1
	s_add_i32 s17, s17, 0x500
	s_and_b32 s99, s88, 1
	s_add_i32 s99, s99, 1
.Lp9h_nolast:
	s_cmpk_lt_i32 s17, 0x580
	s_cselect_b64 s[20:21], -1, 0
	s_cmpk_gt_i32 s17, 0x57f
	s_cbranch_scc1 .LBB0_1798
	s_ashr_i32 s16, s17, 31
	s_lshr_b32 s16, s16, 29
	s_add_i32 s16, s17, s16
	s_ashr_i32 s18, s16, 3
	s_and_b32 s16, s16, -8
	s_sub_i32 s16, s17, s16
	s_cmp_lt_i32 s16, 0
	s_cselect_b32 s17, s37, 0xb0
	s_mul_i32 s16, s16, s17
	s_add_i32 s16, s16, s18
	s_mul_hi_i32 s17, s16, 0x2e8ba2e9
	s_lshr_b32 s18, s17, 31
	s_ashr_i32 s17, s17, 6
	s_add_i32 s17, s17, s18
	s_lshl_b32 s18, s17, 3
	s_mulk_i32 s17, 0x160
	s_sub_i32 s16, s16, s17
	s_bfe_u32 s17, s16, 0x3001c
	s_add_i32 s17, s16, s17
	s_sext_i32_i16 s19, s17
	s_and_b32 s17, s17, 0xfff8
	s_sub_i32 s16, s16, s17
	s_sext_i32_i16 s16, s16
	s_add_i32 s17, s18, s16
	s_ashr_i32 s18, s17, 31
	s_lshr_b32 s18, s18, 27
	s_add_i32 s18, s17, s18
	s_andn2_b32 s18, s18, 31
	s_ashr_i32 s16, s19, 3
	s_sub_i32 s18, s17, s18
.LBB0_1798:
	s_ashr_i32 s19, s18, 31
	s_lshl_b64 s[22:23], s[18:19], 20
	s_add_u32 s22, s90, s22
	s_addc_u32 s23, s91, s23
	s_and_b64 s[24:25], s[20:21], exec
	s_cselect_b32 s19, s23, s29
	s_cselect_b32 s47, s22, s28
	s_ashr_i32 s17, s16, 31
	s_lshl_b64 s[24:25], s[16:17], 20
	s_add_u32 s24, s96, s24
	s_addc_u32 s25, s97, s25
	s_and_b64 s[34:35], s[20:21], exec
	s_cselect_b32 s17, s25, s31
	s_cselect_b32 s48, s24, s30
	s_add_u32 s28, s28, 0x80080
	s_addc_u32 s29, s29, 0
	s_add_u32 s49, s30, 0x100
	v_mov_b32_e32 v0, 0
	s_addc_u32 s50, s31, 0
	s_mov_b32 s51, -2
	v_mov_b32_e32 v1, v0
	v_mov_b32_e32 v2, v0
	v_mov_b32_e32 v3, v0
	v_mov_b32_e32 v64, v0
	v_mov_b32_e32 v65, v0
	v_mov_b32_e32 v66, v0
	v_mov_b32_e32 v67, v0
	v_mov_b32_e32 v8, v0
	v_mov_b32_e32 v9, v0
	v_mov_b32_e32 v10, v0
	v_mov_b32_e32 v11, v0
	v_mov_b32_e32 v72, v0
	v_mov_b32_e32 v73, v0
	v_mov_b32_e32 v74, v0
	v_mov_b32_e32 v75, v0
	v_mov_b32_e32 v16, v0
	v_mov_b32_e32 v17, v0
	v_mov_b32_e32 v18, v0
	v_mov_b32_e32 v19, v0
	v_mov_b32_e32 v80, v0
	v_mov_b32_e32 v81, v0
	v_mov_b32_e32 v82, v0
	v_mov_b32_e32 v83, v0
	v_mov_b32_e32 v24, v0
	v_mov_b32_e32 v25, v0
	v_mov_b32_e32 v26, v0
	v_mov_b32_e32 v27, v0
	v_mov_b32_e32 v88, v0
	v_mov_b32_e32 v89, v0
	v_mov_b32_e32 v90, v0
	v_mov_b32_e32 v91, v0
	v_mov_b32_e32 v4, v0
	v_mov_b32_e32 v5, v0
	v_mov_b32_e32 v6, v0
	v_mov_b32_e32 v7, v0
	v_mov_b32_e32 v68, v0
	v_mov_b32_e32 v69, v0
	v_mov_b32_e32 v70, v0
	v_mov_b32_e32 v71, v0
	v_mov_b32_e32 v12, v0
	v_mov_b32_e32 v13, v0
	v_mov_b32_e32 v14, v0
	v_mov_b32_e32 v15, v0
	v_mov_b32_e32 v76, v0
	v_mov_b32_e32 v77, v0
	v_mov_b32_e32 v78, v0
	v_mov_b32_e32 v79, v0
	v_mov_b32_e32 v20, v0
	v_mov_b32_e32 v21, v0
	v_mov_b32_e32 v22, v0
	v_mov_b32_e32 v23, v0
	v_mov_b32_e32 v84, v0
	v_mov_b32_e32 v85, v0
	v_mov_b32_e32 v86, v0
	v_mov_b32_e32 v87, v0
	v_mov_b32_e32 v28, v0
	v_mov_b32_e32 v29, v0
	v_mov_b32_e32 v30, v0
	v_mov_b32_e32 v31, v0
	v_mov_b32_e32 v92, v0
	v_mov_b32_e32 v93, v0
	v_mov_b32_e32 v94, v0
	v_mov_b32_e32 v95, v0
	v_mov_b32_e32 v32, v0
	v_mov_b32_e32 v33, v0
	v_mov_b32_e32 v34, v0
	v_mov_b32_e32 v35, v0
	v_mov_b32_e32 v96, v0
	v_mov_b32_e32 v97, v0
	v_mov_b32_e32 v98, v0
	v_mov_b32_e32 v99, v0
	v_mov_b32_e32 v40, v0
	v_mov_b32_e32 v41, v0
	v_mov_b32_e32 v42, v0
	v_mov_b32_e32 v43, v0
	v_mov_b32_e32 v104, v0
	v_mov_b32_e32 v105, v0
	v_mov_b32_e32 v106, v0
	v_mov_b32_e32 v107, v0
	v_mov_b32_e32 v48, v0
	v_mov_b32_e32 v49, v0
	v_mov_b32_e32 v50, v0
	v_mov_b32_e32 v51, v0
	v_mov_b32_e32 v112, v0
	v_mov_b32_e32 v113, v0
	v_mov_b32_e32 v114, v0
	v_mov_b32_e32 v115, v0
	v_mov_b32_e32 v56, v0
	v_mov_b32_e32 v57, v0
	v_mov_b32_e32 v58, v0
	v_mov_b32_e32 v59, v0
	v_mov_b32_e32 v152, v0
	v_mov_b32_e32 v153, v0
	v_mov_b32_e32 v154, v0
	v_mov_b32_e32 v155, v0
	v_mov_b32_e32 v36, v0
	v_mov_b32_e32 v37, v0
	v_mov_b32_e32 v38, v0
	v_mov_b32_e32 v39, v0
	v_mov_b32_e32 v100, v0
	v_mov_b32_e32 v101, v0
	v_mov_b32_e32 v102, v0
	v_mov_b32_e32 v103, v0
	v_mov_b32_e32 v44, v0
	v_mov_b32_e32 v45, v0
	v_mov_b32_e32 v46, v0
	v_mov_b32_e32 v47, v0
	v_mov_b32_e32 v108, v0
	v_mov_b32_e32 v109, v0
	v_mov_b32_e32 v110, v0
	v_mov_b32_e32 v111, v0
	v_mov_b32_e32 v52, v0
	v_mov_b32_e32 v53, v0
	v_mov_b32_e32 v54, v0
	v_mov_b32_e32 v55, v0
	v_mov_b32_e32 v116, v0
	v_mov_b32_e32 v117, v0
	v_mov_b32_e32 v118, v0
	v_mov_b32_e32 v119, v0
	v_mov_b32_e32 v60, v0
	v_mov_b32_e32 v61, v0
	v_mov_b32_e32 v62, v0
	v_mov_b32_e32 v63, v0
	v_mov_b32_e32 v156, v0
	v_mov_b32_e32 v157, v0
	v_mov_b32_e32 v158, v0
	v_mov_b32_e32 v159, v0
	.p2align 6
	s_cmp_eq_u32 s98, 1
	s_cbranch_scc1 .Lp9h_A
	s_cmp_eq_u32 s98, 2
	s_cbranch_scc1 .Lp9h_B
	.p2align 6
; #define PG8_STAGE(bufoff, gbase, voff) do { _Pragma("unroll") for (int _i = 0; _i < 2; ++_i) \
;         __builtin_amdgcn_global_load_lds((const unsigned*)((const char*)(gbase) + (voff)[_i]), (LAS unsigned*)(lds + (bufoff) + ldsw + _i * 8192), 16, 0, 0); } while (0)
; #define PG8_LDA(dst, b, h) do { _Pragma("unroll") for (int m = 0; m < 4; ++m) _Pragma("unroll") for (int k = 0; k < 2; ++k) dst[m][k] = *(const LAS bf16x8*)(lds + PG8_SA(b, h) + aoff + m * 2048 + k * 1024); } while (0)
; #define PG8_LDB(dst, b, h) do { _Pragma("unroll") for (int n = 0; n < 2; ++n) _Pragma("unroll") for (int k = 0; k < 2; ++k) dst[n][k] = *(const LAS bf16x8*)(lds + PG8_SB(b, h) + boff + n * 2048 + k * 1024); } while (0)
; #define PG8_MMA(ai, bj, At, Bt) do { __builtin_amdgcn_s_setprio(1); _Pragma("unroll") for (int m = 0; m < 4; ++m) _Pragma("unroll") for (int n = 0; n < 2; ++n) _Pragma("unroll") for (int k = 0; k < 2; ++k) \
;         acc[ai][bj][m][n] = __builtin_amdgcn_mfma_f32_16x16x32_bf16(Bt[n][k], At[m][k], acc[ai][bj][m][n], 0, 0, 0); __builtin_amdgcn_s_setprio(0); } while (0)
; #define PG8_WAIT_V(n) asm volatile("s_waitcnt vmcnt(" #n ")" ::: "memory")
; #define PG8_WAIT_L(n) asm volatile("s_waitcnt lgkmcnt(" #n ")" ::: "memory")
; #define PG8_BAR __builtin_amdgcn_s_barrier()
; #define PG8_SCHED __builtin_amdgcn_sched_barrier(0)
; template <class Epi, class Sched, bool DEFER>
; __device__ __forceinline__ void gemm_fast_core(LAS unsigned char* lds, const GemmP g, const Sched& S, const Epi& E, f32x4 (&acc)[2][2][4][2], Unit& cur) {
;     ...
;             PG8_LDB(B0, 0, 0); PG8_LDB(B1, 0, 1); PG8_SCHED; PG8_LDA(At, 0, 0); PG8_STAGE(PG8_SA(1, 1), a1 + hstepA, voffA);
;             PG8_WAIT_V(8); PG8_WAIT_L(0); PG8_BAR; PG8_MMA(0, 0, At, B0); PG8_MMA(0, 1, At, B1); PG8_BAR; PG8_SCHED;
;             PG8_LDA(At, 0, 1); PG8_STAGE(PG8_SB(0, 0), b2, voffB); PG8_STAGE(PG8_SB(0, 1), b2 + hstepB, voffB); PG8_STAGE(PG8_SA(0, 0), a2, voffA);
;             PG8_WAIT_V(8); PG8_WAIT_L(0); PG8_BAR; PG8_MMA(1, 0, At, B0); PG8_MMA(1, 1, At, B1); PG8_BAR; PG8_SCHED;
.LBB0_1799:
	ds_read_b128 v[120:123], v205
	ds_read_b128 v[124:127], v205 offset:1024
	ds_read_b128 v[128:131], v205 offset:2048
	ds_read_b128 v[132:135], v205 offset:3072
	ds_read_b128 v[136:139], v206
	ds_read_b128 v[140:143], v206 offset:1024
	ds_read_b128 v[144:147], v206 offset:2048
	ds_read_b128 v[148:151], v206 offset:3072
	s_add_u32 s30, s28, 0xfff80080
	s_addc_u32 s31, s29, -1
	s_cmp_eq_u32 s51, 28
	s_cselect_b32 s35, s19, s31
	s_cselect_b32 s34, s47, s30
	s_cselect_b32 s31, s17, s50
	s_cselect_b32 s30, s48, s49
	v_lshl_add_u64 v[220:221], s[28:29], 0, v[164:165]
	s_add_i32 m0, s27, 0xc000
	ds_read_b128 v[168:171], v207
	ds_read_b128 v[172:175], v207 offset:1024
	ds_read_b128 v[176:179], v207 offset:2048
	ds_read_b128 v[180:183], v207 offset:3072
	ds_read_b128 v[184:187], v207 offset:4096
	ds_read_b128 v[208:211], v207 offset:5120
	ds_read_b128 v[212:215], v207 offset:6144
	ds_read_b128 v[216:219], v207 offset:7168
	global_load_lds_dwordx4 v[220:221], off
	v_lshl_add_u64 v[220:221], s[28:29], 0, v[166:167]
	s_add_i32 m0, s27, 0xe000
	s_nop 0
	global_load_lds_dwordx4 v[220:221], off
	s_waitcnt vmcnt(8)
	s_waitcnt lgkmcnt(0)
	s_barrier
	s_setprio 1
	s_waitcnt lgkmcnt(0)
	v_mfma_f32_16x16x32_bf16 v[156:159], v[120:123], v[168:171], v[156:159]
	v_mfma_f32_16x16x32_bf16 v[60:63], v[128:131], v[168:171], v[60:63]
	v_mfma_f32_16x16x32_bf16 v[116:119], v[120:123], v[176:179], v[116:119]
	v_mfma_f32_16x16x32_bf16 v[52:55], v[128:131], v[176:179], v[52:55]
	v_mfma_f32_16x16x32_bf16 v[108:111], v[120:123], v[184:187], v[108:111]
	v_mfma_f32_16x16x32_bf16 v[44:47], v[128:131], v[184:187], v[44:47]
	v_mfma_f32_16x16x32_bf16 v[100:103], v[120:123], v[212:215], v[100:103]
	v_mfma_f32_16x16x32_bf16 v[36:39], v[128:131], v[212:215], v[36:39]
	v_mfma_f32_16x16x32_bf16 v[156:159], v[124:127], v[172:175], v[156:159]
	v_mfma_f32_16x16x32_bf16 v[60:63], v[132:135], v[172:175], v[60:63]
	v_mfma_f32_16x16x32_bf16 v[116:119], v[124:127], v[180:183], v[116:119]
	v_mfma_f32_16x16x32_bf16 v[52:55], v[132:135], v[180:183], v[52:55]
	v_mfma_f32_16x16x32_bf16 v[108:111], v[124:127], v[208:211], v[108:111]
	v_mfma_f32_16x16x32_bf16 v[44:47], v[132:135], v[208:211], v[44:47]
	v_mfma_f32_16x16x32_bf16 v[100:103], v[124:127], v[216:219], v[100:103]
	v_mfma_f32_16x16x32_bf16 v[36:39], v[132:135], v[216:219], v[36:39]
	s_setprio 0
	s_setprio 1
	v_mfma_f32_16x16x32_bf16 v[152:155], v[136:139], v[168:171], v[152:155]
	v_mfma_f32_16x16x32_bf16 v[56:59], v[144:147], v[168:171], v[56:59]
	v_mfma_f32_16x16x32_bf16 v[112:115], v[136:139], v[176:179], v[112:115]
	v_mfma_f32_16x16x32_bf16 v[48:51], v[144:147], v[176:179], v[48:51]
	v_mfma_f32_16x16x32_bf16 v[104:107], v[136:139], v[184:187], v[104:107]
	v_mfma_f32_16x16x32_bf16 v[40:43], v[144:147], v[184:187], v[40:43]
	v_mfma_f32_16x16x32_bf16 v[96:99], v[136:139], v[212:215], v[96:99]
	v_mfma_f32_16x16x32_bf16 v[32:35], v[144:147], v[212:215], v[32:35]
	v_mfma_f32_16x16x32_bf16 v[152:155], v[140:143], v[172:175], v[152:155]
	v_mfma_f32_16x16x32_bf16 v[56:59], v[148:151], v[172:175], v[56:59]
	v_mfma_f32_16x16x32_bf16 v[112:115], v[140:143], v[180:183], v[112:115]
	v_mfma_f32_16x16x32_bf16 v[48:51], v[148:151], v[180:183], v[48:51]
	v_mfma_f32_16x16x32_bf16 v[104:107], v[140:143], v[208:211], v[104:107]
	v_mfma_f32_16x16x32_bf16 v[40:43], v[148:151], v[208:211], v[40:43]
	v_mfma_f32_16x16x32_bf16 v[96:99], v[140:143], v[216:219], v[96:99]
	v_mfma_f32_16x16x32_bf16 v[32:35], v[148:151], v[216:219], v[32:35]
	s_setprio 0
	s_barrier
	s_add_i32 s52, s44, s36
	v_lshl_add_u64 v[220:221], s[30:31], 0, v[162:163]
	s_mov_b32 m0, s52
	ds_read_b128 v[168:171], v207 offset:16384
	ds_read_b128 v[172:175], v207 offset:17408
	ds_read_b128 v[176:179], v207 offset:18432
	ds_read_b128 v[180:183], v207 offset:19456
	ds_read_b128 v[184:187], v207 offset:20480
	ds_read_b128 v[208:211], v207 offset:21504
	ds_read_b128 v[212:215], v207 offset:22528
	ds_read_b128 v[216:219], v207 offset:23552
	global_load_lds_dwordx4 v[220:221], off
	s_add_i32 m0, s52, 0x2000
	s_add_u32 s52, s30, 0x80000
	v_lshl_add_u64 v[222:223], s[30:31], 0, v[160:161]
	s_addc_u32 s53, s31, 0
	s_add_i32 s54, s45, s36
	global_load_lds_dwordx4 v[222:223], off
	v_lshl_add_u64 v[224:225], s[52:53], 0, v[162:163]
	s_mov_b32 m0, s54
	v_lshl_add_u64 v[226:227], s[34:35], 0, v[160:161]
	global_load_lds_dwordx4 v[224:225], off
	v_lshl_add_u64 v[224:225], s[52:53], 0, v[160:161]
	s_add_i32 m0, s54, 0x2000
	s_nop 0
	global_load_lds_dwordx4 v[224:225], off
	v_lshl_add_u64 v[224:225], s[34:35], 0, v[162:163]
	s_mov_b32 m0, s27
	s_nop 0
	global_load_lds_dwordx4 v[224:225], off
	s_mov_b32 m0, s38
	s_nop 0
	global_load_lds_dwordx4 v[226:227], off
	s_waitcnt vmcnt(8)
	s_waitcnt lgkmcnt(0)
	s_barrier
; #define PG8_STAGE(bufoff, gbase, voff) do { _Pragma("unroll") for (int _i = 0; _i < 2; ++_i) \
;         __builtin_amdgcn_global_load_lds((const unsigned*)((const char*)(gbase) + (voff)[_i]), (LAS unsigned*)(lds + (bufoff) + ldsw + _i * 8192), 16, 0, 0); } while (0)
; #define PG8_LDA(dst, b, h) do { _Pragma("unroll") for (int m = 0; m < 4; ++m) _Pragma("unroll") for (int k = 0; k < 2; ++k) dst[m][k] = *(const LAS bf16x8*)(lds + PG8_SA(b, h) + aoff + m * 2048 + k * 1024); } while (0)
; #define PG8_LDB(dst, b, h) do { _Pragma("unroll") for (int n = 0; n < 2; ++n) _Pragma("unroll") for (int k = 0; k < 2; ++k) dst[n][k] = *(const LAS bf16x8*)(lds + PG8_SB(b, h) + boff + n * 2048 + k * 1024); } while (0)
; #define PG8_MMA(ai, bj, At, Bt) do { __builtin_amdgcn_s_setprio(1); _Pragma("unroll") for (int m = 0; m < 4; ++m) _Pragma("unroll") for (int n = 0; n < 2; ++n) _Pragma("unroll") for (int k = 0; k < 2; ++k) \
;         acc[ai][bj][m][n] = __builtin_amdgcn_mfma_f32_16x16x32_bf16(Bt[n][k], At[m][k], acc[ai][bj][m][n], 0, 0, 0); __builtin_amdgcn_s_setprio(0); } while (0)
; #define PG8_WAIT_V(n) asm volatile("s_waitcnt vmcnt(" #n ")" ::: "memory")
; #define PG8_WAIT_L(n) asm volatile("s_waitcnt lgkmcnt(" #n ")" ::: "memory")
; #define PG8_BAR __builtin_amdgcn_s_barrier()
; #define PG8_SCHED __builtin_amdgcn_sched_barrier(0)
; template <class Epi, class Sched, bool DEFER>
; __device__ __forceinline__ void gemm_fast_core(LAS unsigned char* lds, const GemmP g, const Sched& S, const Epi& E, f32x4 (&acc)[2][2][4][2], Unit& cur) {
;     ...
;             PG8_WAIT_V(8); PG8_WAIT_L(0); PG8_BAR; PG8_MMA(1, 0, At, B0); PG8_MMA(1, 1, At, B1); PG8_BAR; PG8_SCHED;
;             PG8_LDB(B0, 1, 0); PG8_LDB(B1, 1, 1); PG8_SCHED; PG8_LDA(At, 1, 0); PG8_STAGE(PG8_SA(0, 1), a2 + hstepA, voffA);
;             PG8_WAIT_V(8); PG8_WAIT_L(0); PG8_BAR; PG8_MMA(0, 0, At, B0); PG8_MMA(0, 1, At, B1); PG8_BAR; PG8_SCHED;
	s_setprio 1
	s_waitcnt lgkmcnt(0)
	v_mfma_f32_16x16x32_bf16 v[92:95], v[120:123], v[168:171], v[92:95]
	v_mfma_f32_16x16x32_bf16 v[28:31], v[128:131], v[168:171], v[28:31]
	v_mfma_f32_16x16x32_bf16 v[84:87], v[120:123], v[176:179], v[84:87]
	v_mfma_f32_16x16x32_bf16 v[20:23], v[128:131], v[176:179], v[20:23]
	v_mfma_f32_16x16x32_bf16 v[76:79], v[120:123], v[184:187], v[76:79]
	v_mfma_f32_16x16x32_bf16 v[12:15], v[128:131], v[184:187], v[12:15]
	v_mfma_f32_16x16x32_bf16 v[68:71], v[120:123], v[212:215], v[68:71]
	v_mfma_f32_16x16x32_bf16 v[4:7], v[128:131], v[212:215], v[4:7]
	v_mfma_f32_16x16x32_bf16 v[92:95], v[124:127], v[172:175], v[92:95]
	v_mfma_f32_16x16x32_bf16 v[28:31], v[132:135], v[172:175], v[28:31]
	v_mfma_f32_16x16x32_bf16 v[84:87], v[124:127], v[180:183], v[84:87]
	v_mfma_f32_16x16x32_bf16 v[20:23], v[132:135], v[180:183], v[20:23]
	v_mfma_f32_16x16x32_bf16 v[76:79], v[124:127], v[208:211], v[76:79]
	v_mfma_f32_16x16x32_bf16 v[12:15], v[132:135], v[208:211], v[12:15]
	v_mfma_f32_16x16x32_bf16 v[68:71], v[124:127], v[216:219], v[68:71]
	v_mfma_f32_16x16x32_bf16 v[4:7], v[132:135], v[216:219], v[4:7]
	s_setprio 0
	s_setprio 1
	v_mfma_f32_16x16x32_bf16 v[88:91], v[136:139], v[168:171], v[88:91]
	v_mfma_f32_16x16x32_bf16 v[24:27], v[144:147], v[168:171], v[24:27]
	v_mfma_f32_16x16x32_bf16 v[80:83], v[136:139], v[176:179], v[80:83]
	v_mfma_f32_16x16x32_bf16 v[16:19], v[144:147], v[176:179], v[16:19]
	v_mfma_f32_16x16x32_bf16 v[72:75], v[136:139], v[184:187], v[72:75]
	v_mfma_f32_16x16x32_bf16 v[8:11], v[144:147], v[184:187], v[8:11]
	v_mfma_f32_16x16x32_bf16 v[64:67], v[136:139], v[212:215], v[64:67]
	v_mfma_f32_16x16x32_bf16 v[0:3], v[144:147], v[212:215], v[0:3]
	v_mfma_f32_16x16x32_bf16 v[88:91], v[140:143], v[172:175], v[88:91]
	v_mfma_f32_16x16x32_bf16 v[24:27], v[148:151], v[172:175], v[24:27]
	v_mfma_f32_16x16x32_bf16 v[80:83], v[140:143], v[180:183], v[80:83]
	v_mfma_f32_16x16x32_bf16 v[16:19], v[148:151], v[180:183], v[16:19]
	v_mfma_f32_16x16x32_bf16 v[72:75], v[140:143], v[208:211], v[72:75]
	v_mfma_f32_16x16x32_bf16 v[8:11], v[148:151], v[208:211], v[8:11]
	v_mfma_f32_16x16x32_bf16 v[64:67], v[140:143], v[216:219], v[64:67]
	v_mfma_f32_16x16x32_bf16 v[0:3], v[148:151], v[216:219], v[0:3]
	s_setprio 0
	s_barrier
	s_add_i32 s52, 0, 0x18000
	s_add_i32 s53, 0, 0x1c000
	v_add_u32_e32 v132, s52, v196
	v_add_u32_e32 v148, s53, v196
	ds_read_b128 v[120:123], v132
	ds_read_b128 v[124:127], v132 offset:1024
	ds_read_b128 v[128:131], v132 offset:2048
	ds_read_b128 v[132:135], v132 offset:3072
	ds_read_b128 v[136:139], v148
	ds_read_b128 v[140:143], v148 offset:1024
	ds_read_b128 v[144:147], v148 offset:2048
	ds_read_b128 v[148:151], v148 offset:3072
	s_add_u32 s34, s34, 0x80000
	s_addc_u32 s35, s35, 0
	s_mov_b32 m0, s39
	v_lshl_add_u64 v[228:229], s[34:35], 0, v[162:163]
	ds_read_b128 v[168:171], v207 offset:32768
	ds_read_b128 v[172:175], v207 offset:33792
	ds_read_b128 v[176:179], v207 offset:34816
	ds_read_b128 v[180:183], v207 offset:35840
	ds_read_b128 v[184:187], v207 offset:36864
	ds_read_b128 v[208:211], v207 offset:37888
	ds_read_b128 v[212:215], v207 offset:38912
	ds_read_b128 v[216:219], v207 offset:39936
	global_load_lds_dwordx4 v[228:229], off
	v_lshl_add_u64 v[228:229], s[34:35], 0, v[160:161]
	s_mov_b32 m0, s40
	s_nop 0
	global_load_lds_dwordx4 v[228:229], off
	s_waitcnt vmcnt(8)
	s_waitcnt lgkmcnt(0)
	s_barrier
	s_setprio 1
	s_waitcnt lgkmcnt(0)
	v_mfma_f32_16x16x32_bf16 v[156:159], v[120:123], v[168:171], v[156:159]
	v_mfma_f32_16x16x32_bf16 v[60:63], v[128:131], v[168:171], v[60:63]
	v_mfma_f32_16x16x32_bf16 v[116:119], v[120:123], v[176:179], v[116:119]
	v_mfma_f32_16x16x32_bf16 v[52:55], v[128:131], v[176:179], v[52:55]
	v_mfma_f32_16x16x32_bf16 v[108:111], v[120:123], v[184:187], v[108:111]
	v_mfma_f32_16x16x32_bf16 v[44:47], v[128:131], v[184:187], v[44:47]
	v_mfma_f32_16x16x32_bf16 v[100:103], v[120:123], v[212:215], v[100:103]
	v_mfma_f32_16x16x32_bf16 v[36:39], v[128:131], v[212:215], v[36:39]
	v_mfma_f32_16x16x32_bf16 v[156:159], v[124:127], v[172:175], v[156:159]
	v_mfma_f32_16x16x32_bf16 v[60:63], v[132:135], v[172:175], v[60:63]
	v_mfma_f32_16x16x32_bf16 v[116:119], v[124:127], v[180:183], v[116:119]
	v_mfma_f32_16x16x32_bf16 v[52:55], v[132:135], v[180:183], v[52:55]
	v_mfma_f32_16x16x32_bf16 v[108:111], v[124:127], v[208:211], v[108:111]
	v_mfma_f32_16x16x32_bf16 v[44:47], v[132:135], v[208:211], v[44:47]
	v_mfma_f32_16x16x32_bf16 v[100:103], v[124:127], v[216:219], v[100:103]
	v_mfma_f32_16x16x32_bf16 v[36:39], v[132:135], v[216:219], v[36:39]
	s_setprio 0
	s_setprio 1
	v_mfma_f32_16x16x32_bf16 v[152:155], v[136:139], v[168:171], v[152:155]
	v_mfma_f32_16x16x32_bf16 v[56:59], v[144:147], v[168:171], v[56:59]
	v_mfma_f32_16x16x32_bf16 v[112:115], v[136:139], v[176:179], v[112:115]
	v_mfma_f32_16x16x32_bf16 v[48:51], v[144:147], v[176:179], v[48:51]
	v_mfma_f32_16x16x32_bf16 v[104:107], v[136:139], v[184:187], v[104:107]
	v_mfma_f32_16x16x32_bf16 v[40:43], v[144:147], v[184:187], v[40:43]
	v_mfma_f32_16x16x32_bf16 v[96:99], v[136:139], v[212:215], v[96:99]
	v_mfma_f32_16x16x32_bf16 v[32:35], v[144:147], v[212:215], v[32:35]
	v_mfma_f32_16x16x32_bf16 v[152:155], v[140:143], v[172:175], v[152:155]
	v_mfma_f32_16x16x32_bf16 v[56:59], v[148:151], v[172:175], v[56:59]
	v_mfma_f32_16x16x32_bf16 v[112:115], v[140:143], v[180:183], v[112:115]
	v_mfma_f32_16x16x32_bf16 v[48:51], v[148:151], v[180:183], v[48:51]
	v_mfma_f32_16x16x32_bf16 v[104:107], v[140:143], v[208:211], v[104:107]
	v_mfma_f32_16x16x32_bf16 v[40:43], v[148:151], v[208:211], v[40:43]
	v_mfma_f32_16x16x32_bf16 v[96:99], v[140:143], v[216:219], v[96:99]
	v_mfma_f32_16x16x32_bf16 v[32:35], v[148:151], v[216:219], v[32:35]
	s_setprio 0
	s_barrier
; #define PG8_STAGE(bufoff, gbase, voff) do { _Pragma("unroll") for (int _i = 0; _i < 2; ++_i) \
;         __builtin_amdgcn_global_load_lds((const unsigned*)((const char*)(gbase) + (voff)[_i]), (LAS unsigned*)(lds + (bufoff) + ldsw + _i * 8192), 16, 0, 0); } while (0)
; #define PG8_LDA(dst, b, h) do { _Pragma("unroll") for (int m = 0; m < 4; ++m) _Pragma("unroll") for (int k = 0; k < 2; ++k) dst[m][k] = *(const LAS bf16x8*)(lds + PG8_SA(b, h) + aoff + m * 2048 + k * 1024); } while (0)
; #define PG8_LDB(dst, b, h) do { _Pragma("unroll") for (int n = 0; n < 2; ++n) _Pragma("unroll") for (int k = 0; k < 2; ++k) dst[n][k] = *(const LAS bf16x8*)(lds + PG8_SB(b, h) + boff + n * 2048 + k * 1024); } while (0)
; #define PG8_MMA(ai, bj, At, Bt) do { __builtin_amdgcn_s_setprio(1); _Pragma("unroll") for (int m = 0; m < 4; ++m) _Pragma("unroll") for (int n = 0; n < 2; ++n) _Pragma("unroll") for (int k = 0; k < 2; ++k) \
;         acc[ai][bj][m][n] = __builtin_amdgcn_mfma_f32_16x16x32_bf16(Bt[n][k], At[m][k], acc[ai][bj][m][n], 0, 0, 0); __builtin_amdgcn_s_setprio(0); } while (0)
; #define PG8_WAIT_V(n) asm volatile("s_waitcnt vmcnt(" #n ")" ::: "memory")
; #define PG8_WAIT_L(n) asm volatile("s_waitcnt lgkmcnt(" #n ")" ::: "memory")
; #define PG8_BAR __builtin_amdgcn_s_barrier()
; #define PG8_SCHED __builtin_amdgcn_sched_barrier(0)
; template <class Epi, class Sched, bool DEFER>
; __device__ __forceinline__ void gemm_fast_core(LAS unsigned char* lds, const GemmP g, const Sched& S, const Epi& E, f32x4 (&acc)[2][2][4][2], Unit& cur) {
;     ...
;             PG8_LDB(B0, 0, 0); PG8_LDB(B1, 0, 1); PG8_SCHED; PG8_LDA(At, 0, 0); PG8_STAGE(PG8_SA(1, 1), a1 + hstepA, voffA);
;             PG8_WAIT_V(8); PG8_WAIT_L(0); PG8_BAR; PG8_MMA(0, 0, At, B0); PG8_MMA(0, 1, At, B1); PG8_BAR; PG8_SCHED;
;     ...
;             PG8_LDA(At, 1, 1); PG8_STAGE(PG8_SB(1, 0), b3, voffB); PG8_STAGE(PG8_SB(1, 1), b3 + hstepB, voffB); PG8_STAGE(PG8_SA(1, 0), a3, voffA);
;             PG8_WAIT_V(8); PG8_WAIT_L(0); PG8_BAR; PG8_MMA(1, 0, At, B0); PG8_MMA(1, 1, At, B1); PG8_BAR; PG8_SCHED;
	s_add_i32 s34, s52, s36
	v_lshl_add_u64 v[220:221], v[220:221], 0, s[8:9]
	s_mov_b32 m0, s34
	ds_read_b128 v[168:171], v207 offset:49152
	ds_read_b128 v[172:175], v207 offset:50176
	ds_read_b128 v[176:179], v207 offset:51200
	ds_read_b128 v[180:183], v207 offset:52224
	ds_read_b128 v[184:187], v207 offset:53248
	ds_read_b128 v[208:211], v207 offset:54272
	ds_read_b128 v[212:215], v207 offset:55296
	ds_read_b128 v[216:219], v207 offset:56320
	global_load_lds_dwordx4 v[220:221], off
	s_add_i32 m0, s34, 0x2000
	s_add_u32 s30, s30, 0x80080
	v_lshl_add_u64 v[220:221], v[222:223], 0, s[8:9]
	s_addc_u32 s31, s31, 0
	s_add_i32 s34, s53, s36
	global_load_lds_dwordx4 v[220:221], off
	v_lshl_add_u64 v[220:221], s[30:31], 0, v[162:163]
	s_mov_b32 m0, s34
	s_nop 0
	global_load_lds_dwordx4 v[220:221], off
	v_lshl_add_u64 v[220:221], s[30:31], 0, v[160:161]
	s_add_i32 m0, s34, 0x2000
	s_nop 0
	global_load_lds_dwordx4 v[220:221], off
	v_lshl_add_u64 v[220:221], v[224:225], 0, s[8:9]
	s_mov_b32 m0, s42
	s_nop 0
	global_load_lds_dwordx4 v[220:221], off
	v_lshl_add_u64 v[220:221], v[226:227], 0, s[8:9]
	s_mov_b32 m0, s43
	s_nop 0
	global_load_lds_dwordx4 v[220:221], off
	s_waitcnt vmcnt(8)
	s_waitcnt lgkmcnt(0)
	s_barrier
	s_setprio 1
	s_waitcnt lgkmcnt(0)
	v_mfma_f32_16x16x32_bf16 v[92:95], v[120:123], v[168:171], v[92:95]
	v_mfma_f32_16x16x32_bf16 v[28:31], v[128:131], v[168:171], v[28:31]
	v_mfma_f32_16x16x32_bf16 v[84:87], v[120:123], v[176:179], v[84:87]
	v_mfma_f32_16x16x32_bf16 v[20:23], v[128:131], v[176:179], v[20:23]
	v_mfma_f32_16x16x32_bf16 v[76:79], v[120:123], v[184:187], v[76:79]
	v_mfma_f32_16x16x32_bf16 v[12:15], v[128:131], v[184:187], v[12:15]
	v_mfma_f32_16x16x32_bf16 v[68:71], v[120:123], v[212:215], v[68:71]
	v_mfma_f32_16x16x32_bf16 v[4:7], v[128:131], v[212:215], v[4:7]
	v_mfma_f32_16x16x32_bf16 v[92:95], v[124:127], v[172:175], v[92:95]
	v_mfma_f32_16x16x32_bf16 v[28:31], v[132:135], v[172:175], v[28:31]
	v_mfma_f32_16x16x32_bf16 v[84:87], v[124:127], v[180:183], v[84:87]
	v_mfma_f32_16x16x32_bf16 v[20:23], v[132:135], v[180:183], v[20:23]
	v_mfma_f32_16x16x32_bf16 v[76:79], v[124:127], v[208:211], v[76:79]
	v_mfma_f32_16x16x32_bf16 v[12:15], v[132:135], v[208:211], v[12:15]
	v_mfma_f32_16x16x32_bf16 v[68:71], v[124:127], v[216:219], v[68:71]
	v_mfma_f32_16x16x32_bf16 v[4:7], v[132:135], v[216:219], v[4:7]
	s_setprio 0
	s_setprio 1
	v_mfma_f32_16x16x32_bf16 v[88:91], v[136:139], v[168:171], v[88:91]
	v_mfma_f32_16x16x32_bf16 v[24:27], v[144:147], v[168:171], v[24:27]
	v_mfma_f32_16x16x32_bf16 v[80:83], v[136:139], v[176:179], v[80:83]
	v_mfma_f32_16x16x32_bf16 v[16:19], v[144:147], v[176:179], v[16:19]
	v_mfma_f32_16x16x32_bf16 v[72:75], v[136:139], v[184:187], v[72:75]
	v_mfma_f32_16x16x32_bf16 v[8:11], v[144:147], v[184:187], v[8:11]
	v_mfma_f32_16x16x32_bf16 v[64:67], v[136:139], v[212:215], v[64:67]
	v_mfma_f32_16x16x32_bf16 v[0:3], v[144:147], v[212:215], v[0:3]
	v_mfma_f32_16x16x32_bf16 v[88:91], v[140:143], v[172:175], v[88:91]
	v_mfma_f32_16x16x32_bf16 v[24:27], v[148:151], v[172:175], v[24:27]
	v_mfma_f32_16x16x32_bf16 v[80:83], v[140:143], v[180:183], v[80:83]
	v_mfma_f32_16x16x32_bf16 v[16:19], v[148:151], v[180:183], v[16:19]
	v_mfma_f32_16x16x32_bf16 v[72:75], v[140:143], v[208:211], v[72:75]
	v_mfma_f32_16x16x32_bf16 v[8:11], v[148:151], v[208:211], v[8:11]
	v_mfma_f32_16x16x32_bf16 v[64:67], v[140:143], v[216:219], v[64:67]
	v_mfma_f32_16x16x32_bf16 v[0:3], v[148:151], v[216:219], v[0:3]
	s_setprio 0
	s_barrier
	s_add_i32 s51, s51, 2
	s_add_u32 s28, s28, 0x100
	s_addc_u32 s29, s29, 0
	s_add_u32 s49, s49, 0x100
	s_addc_u32 s50, s50, 0
	s_cmp_gt_u32 s51, 29
	s_cbranch_scc0 .LBB0_1799
	s_branch .Lp9h_join
	.p2align 6
.Lp9h_A:
	ds_read_b128 v[120:123], v205
	ds_read_b128 v[124:127], v205 offset:1024
	ds_read_b128 v[128:131], v205 offset:2048
	ds_read_b128 v[132:135], v205 offset:3072
	ds_read_b128 v[136:139], v206
	ds_read_b128 v[140:143], v206 offset:1024
	ds_read_b128 v[144:147], v206 offset:2048
	ds_read_b128 v[148:151], v206 offset:3072
	s_add_u32 s30, s28, 0xfff80080
	s_addc_u32 s31, s29, -1
	s_cmp_eq_u32 s51, 28
	s_cselect_b32 s35, s19, s31
	s_cselect_b32 s34, s47, s30
	s_cselect_b32 s31, s17, s50
	s_cselect_b32 s30, s48, s49
	v_lshl_add_u64 v[220:221], s[28:29], 0, v[164:165]
	s_add_i32 m0, s27, 0xc000
	ds_read_b128 v[168:171], v207
	ds_read_b128 v[172:175], v207 offset:1024
	ds_read_b128 v[176:179], v207 offset:2048
	ds_read_b128 v[180:183], v207 offset:3072
	ds_read_b128 v[184:187], v207 offset:4096
	ds_read_b128 v[208:211], v207 offset:5120
	ds_read_b128 v[212:215], v207 offset:6144
	ds_read_b128 v[216:219], v207 offset:7168
	global_load_lds_dwordx4 v[220:221], off
	v_lshl_add_u64 v[220:221], s[28:29], 0, v[166:167]
	s_add_i32 m0, s27, 0xe000
	s_nop 0
	global_load_lds_dwordx4 v[220:221], off
	s_waitcnt vmcnt(8)
	s_waitcnt lgkmcnt(0)
	s_barrier
; #define PG8_STAGE(bufoff, gbase, voff) do { _Pragma("unroll") for (int _i = 0; _i < 2; ++_i) \
;         __builtin_amdgcn_global_load_lds((const unsigned*)((const char*)(gbase) + (voff)[_i]), (LAS unsigned*)(lds + (bufoff) + ldsw + _i * 8192), 16, 0, 0); } while (0)
; #define PG8_LDA(dst, b, h) do { _Pragma("unroll") for (int m = 0; m < 4; ++m) _Pragma("unroll") for (int k = 0; k < 2; ++k) dst[m][k] = *(const LAS bf16x8*)(lds + PG8_SA(b, h) + aoff + m * 2048 + k * 1024); } while (0)
; #define PG8_LDB(dst, b, h) do { _Pragma("unroll") for (int n = 0; n < 2; ++n) _Pragma("unroll") for (int k = 0; k < 2; ++k) dst[n][k] = *(const LAS bf16x8*)(lds + PG8_SB(b, h) + boff + n * 2048 + k * 1024); } while (0)
; #define PG8_MMA(ai, bj, At, Bt) do { __builtin_amdgcn_s_setprio(1); _Pragma("unroll") for (int m = 0; m < 4; ++m) _Pragma("unroll") for (int n = 0; n < 2; ++n) _Pragma("unroll") for (int k = 0; k < 2; ++k) \
;         acc[ai][bj][m][n] = __builtin_amdgcn_mfma_f32_16x16x32_bf16(Bt[n][k], At[m][k], acc[ai][bj][m][n], 0, 0, 0); __builtin_amdgcn_s_setprio(0); } while (0)
; #define PG8_WAIT_V(n) asm volatile("s_waitcnt vmcnt(" #n ")" ::: "memory")
; #define PG8_WAIT_L(n) asm volatile("s_waitcnt lgkmcnt(" #n ")" ::: "memory")
; #define PG8_BAR __builtin_amdgcn_s_barrier()
; #define PG8_SCHED __builtin_amdgcn_sched_barrier(0)
; template <class Epi, class Sched, bool DEFER>
; __device__ __forceinline__ void gemm_fast_core(LAS unsigned char* lds, const GemmP g, const Sched& S, const Epi& E, f32x4 (&acc)[2][2][4][2], Unit& cur) {
;     ...
;             PG8_LDB(B0, 0, 0); PG8_LDB(B1, 0, 1); PG8_SCHED; PG8_LDA(At, 0, 0); PG8_STAGE(PG8_SA(1, 1), a1 + hstepA, voffA);
;             PG8_WAIT_V(8); PG8_WAIT_L(0); PG8_BAR; PG8_MMA(0, 0, At, B0); PG8_MMA(0, 1, At, B1); PG8_BAR; PG8_SCHED;
;             PG8_LDA(At, 0, 1); PG8_STAGE(PG8_SB(0, 0), b2, voffB); PG8_STAGE(PG8_SB(0, 1), b2 + hstepB, voffB); PG8_STAGE(PG8_SA(0, 0), a2, voffA);
;             PG8_WAIT_V(8); PG8_WAIT_L(0); PG8_BAR; PG8_MMA(1, 0, At, B0); PG8_MMA(1, 1, At, B1); PG8_BAR; PG8_SCHED;
;             PG8_LDB(B0, 1, 0); PG8_LDB(B1, 1, 1); PG8_SCHED; PG8_LDA(At, 1, 0); PG8_STAGE(PG8_SA(0, 1), a2 + hstepA, voffA);
;             PG8_WAIT_V(8); PG8_WAIT_L(0); PG8_BAR; PG8_MMA(0, 0, At, B0); PG8_MMA(0, 1, At, B1); PG8_BAR; PG8_SCHED;
	s_setprio 1
	s_waitcnt lgkmcnt(0)
	v_mfma_f32_16x16x32_bf16 v[156:159], v[120:123], v[168:171], v[156:159]
	v_mfma_f32_16x16x32_bf16 v[60:63], v[128:131], v[168:171], v[60:63]
	v_mfma_f32_16x16x32_bf16 v[116:119], v[120:123], v[176:179], v[116:119]
	v_mfma_f32_16x16x32_bf16 v[52:55], v[128:131], v[176:179], v[52:55]
	v_mfma_f32_16x16x32_bf16 v[108:111], v[120:123], v[184:187], v[108:111]
	v_mfma_f32_16x16x32_bf16 v[44:47], v[128:131], v[184:187], v[44:47]
	v_mfma_f32_16x16x32_bf16 v[100:103], v[120:123], v[212:215], v[100:103]
	v_mfma_f32_16x16x32_bf16 v[36:39], v[128:131], v[212:215], v[36:39]
	v_mfma_f32_16x16x32_bf16 v[156:159], v[124:127], v[172:175], v[156:159]
	v_mfma_f32_16x16x32_bf16 v[60:63], v[132:135], v[172:175], v[60:63]
	v_mfma_f32_16x16x32_bf16 v[116:119], v[124:127], v[180:183], v[116:119]
	v_mfma_f32_16x16x32_bf16 v[52:55], v[132:135], v[180:183], v[52:55]
	v_mfma_f32_16x16x32_bf16 v[108:111], v[124:127], v[208:211], v[108:111]
	v_mfma_f32_16x16x32_bf16 v[44:47], v[132:135], v[208:211], v[44:47]
	v_mfma_f32_16x16x32_bf16 v[100:103], v[124:127], v[216:219], v[100:103]
	v_mfma_f32_16x16x32_bf16 v[36:39], v[132:135], v[216:219], v[36:39]
	s_setprio 0
	s_setprio 1
	v_mfma_f32_16x16x32_bf16 v[152:155], v[136:139], v[168:171], v[152:155]
	v_mfma_f32_16x16x32_bf16 v[56:59], v[144:147], v[168:171], v[56:59]
	v_mfma_f32_16x16x32_bf16 v[112:115], v[136:139], v[176:179], v[112:115]
	v_mfma_f32_16x16x32_bf16 v[48:51], v[144:147], v[176:179], v[48:51]
	v_mfma_f32_16x16x32_bf16 v[104:107], v[136:139], v[184:187], v[104:107]
	v_mfma_f32_16x16x32_bf16 v[40:43], v[144:147], v[184:187], v[40:43]
	v_mfma_f32_16x16x32_bf16 v[96:99], v[136:139], v[212:215], v[96:99]
	v_mfma_f32_16x16x32_bf16 v[32:35], v[144:147], v[212:215], v[32:35]
	v_mfma_f32_16x16x32_bf16 v[152:155], v[140:143], v[172:175], v[152:155]
	v_mfma_f32_16x16x32_bf16 v[56:59], v[148:151], v[172:175], v[56:59]
	v_mfma_f32_16x16x32_bf16 v[112:115], v[140:143], v[180:183], v[112:115]
	v_mfma_f32_16x16x32_bf16 v[48:51], v[148:151], v[180:183], v[48:51]
	v_mfma_f32_16x16x32_bf16 v[104:107], v[140:143], v[208:211], v[104:107]
	v_mfma_f32_16x16x32_bf16 v[40:43], v[148:151], v[208:211], v[40:43]
	v_mfma_f32_16x16x32_bf16 v[96:99], v[140:143], v[216:219], v[96:99]
	v_mfma_f32_16x16x32_bf16 v[32:35], v[148:151], v[216:219], v[32:35]
	s_setprio 0
	s_barrier
	s_add_i32 s52, s44, s36
	v_lshl_add_u64 v[220:221], s[30:31], 0, v[162:163]
	s_mov_b32 m0, s52
	ds_read_b128 v[168:171], v207 offset:16384
	ds_read_b128 v[172:175], v207 offset:17408
	ds_read_b128 v[176:179], v207 offset:18432
	ds_read_b128 v[180:183], v207 offset:19456
	ds_read_b128 v[184:187], v207 offset:20480
	ds_read_b128 v[208:211], v207 offset:21504
	ds_read_b128 v[212:215], v207 offset:22528
	ds_read_b128 v[216:219], v207 offset:23552
	global_load_lds_dwordx4 v[220:221], off
	s_add_i32 m0, s52, 0x2000
	s_add_u32 s52, s30, 0x80000
	v_lshl_add_u64 v[222:223], s[30:31], 0, v[160:161]
	s_addc_u32 s53, s31, 0
	s_add_i32 s54, s45, s36
	global_load_lds_dwordx4 v[222:223], off
	v_lshl_add_u64 v[224:225], s[52:53], 0, v[162:163]
	s_mov_b32 m0, s54
	v_lshl_add_u64 v[226:227], s[34:35], 0, v[160:161]
	global_load_lds_dwordx4 v[224:225], off
	v_lshl_add_u64 v[224:225], s[52:53], 0, v[160:161]
	s_add_i32 m0, s54, 0x2000
	s_nop 0
	global_load_lds_dwordx4 v[224:225], off
	v_lshl_add_u64 v[224:225], s[34:35], 0, v[162:163]
	s_mov_b32 m0, s27
	s_nop 0
	global_load_lds_dwordx4 v[224:225], off
	s_mov_b32 m0, s38
	s_nop 0
	global_load_lds_dwordx4 v[226:227], off
	s_waitcnt vmcnt(8)
	s_waitcnt lgkmcnt(0)
	s_barrier
	s_waitcnt lgkmcnt(0)
	s_barrier
	s_add_i32 s52, 0, 0x18000
	s_add_i32 s53, 0, 0x1c000
	v_add_u32_e32 v132, s52, v196
	v_add_u32_e32 v148, s53, v196
	ds_read_b128 v[120:123], v132
	ds_read_b128 v[124:127], v132 offset:1024
	ds_read_b128 v[128:131], v132 offset:2048
	ds_read_b128 v[132:135], v132 offset:3072
	ds_read_b128 v[136:139], v148
	ds_read_b128 v[140:143], v148 offset:1024
	ds_read_b128 v[144:147], v148 offset:2048
	ds_read_b128 v[148:151], v148 offset:3072
	s_add_u32 s34, s34, 0x80000
	s_addc_u32 s35, s35, 0
	s_mov_b32 m0, s39
	v_lshl_add_u64 v[228:229], s[34:35], 0, v[162:163]
	ds_read_b128 v[168:171], v207 offset:32768
	ds_read_b128 v[172:175], v207 offset:33792
	ds_read_b128 v[176:179], v207 offset:34816
	ds_read_b128 v[180:183], v207 offset:35840
	ds_read_b128 v[184:187], v207 offset:36864
	ds_read_b128 v[208:211], v207 offset:37888
	ds_read_b128 v[212:215], v207 offset:38912
	ds_read_b128 v[216:219], v207 offset:39936
	global_load_lds_dwordx4 v[228:229], off
	v_lshl_add_u64 v[228:229], s[34:35], 0, v[160:161]
	s_mov_b32 m0, s40
	s_nop 0
	global_load_lds_dwordx4 v[228:229], off
	s_waitcnt vmcnt(8)
	s_waitcnt lgkmcnt(0)
	s_barrier
; #define PG8_STAGE(bufoff, gbase, voff) do { _Pragma("unroll") for (int _i = 0; _i < 2; ++_i) \
;         __builtin_amdgcn_global_load_lds((const unsigned*)((const char*)(gbase) + (voff)[_i]), (LAS unsigned*)(lds + (bufoff) + ldsw + _i * 8192), 16, 0, 0); } while (0)
; #define PG8_LDA(dst, b, h) do { _Pragma("unroll") for (int m = 0; m < 4; ++m) _Pragma("unroll") for (int k = 0; k < 2; ++k) dst[m][k] = *(const LAS bf16x8*)(lds + PG8_SA(b, h) + aoff + m * 2048 + k * 1024); } while (0)
; #define PG8_LDB(dst, b, h) do { _Pragma("unroll") for (int n = 0; n < 2; ++n) _Pragma("unroll") for (int k = 0; k < 2; ++k) dst[n][k] = *(const LAS bf16x8*)(lds + PG8_SB(b, h) + boff + n * 2048 + k * 1024); } while (0)
; #define PG8_MMA(ai, bj, At, Bt) do { __builtin_amdgcn_s_setprio(1); _Pragma("unroll") for (int m = 0; m < 4; ++m) _Pragma("unroll") for (int n = 0; n < 2; ++n) _Pragma("unroll") for (int k = 0; k < 2; ++k) \
;         acc[ai][bj][m][n] = __builtin_amdgcn_mfma_f32_16x16x32_bf16(Bt[n][k], At[m][k], acc[ai][bj][m][n], 0, 0, 0); __builtin_amdgcn_s_setprio(0); } while (0)
; #define PG8_WAIT_V(n) asm volatile("s_waitcnt vmcnt(" #n ")" ::: "memory")
; #define PG8_WAIT_L(n) asm volatile("s_waitcnt lgkmcnt(" #n ")" ::: "memory")
; template <class Epi, class Sched, bool DEFER>
; __device__ __forceinline__ void gemm_fast_core(LAS unsigned char* lds, const GemmP g, const Sched& S, const Epi& E, f32x4 (&acc)[2][2][4][2], Unit& cur) {
;     ...
;             PG8_LDB(B0, 0, 0); PG8_LDB(B1, 0, 1); PG8_SCHED; PG8_LDA(At, 0, 0); PG8_STAGE(PG8_SA(1, 1), a1 + hstepA, voffA);
;             PG8_WAIT_V(8); PG8_WAIT_L(0); PG8_BAR; PG8_MMA(0, 0, At, B0); PG8_MMA(0, 1, At, B1); PG8_BAR; PG8_SCHED;
;             PG8_LDA(At, 0, 1); PG8_STAGE(PG8_SB(0, 0), b2, voffB); PG8_STAGE(PG8_SB(0, 1), b2 + hstepB, voffB); PG8_STAGE(PG8_SA(0, 0), a2, voffA);
;     ...
;             PG8_LDB(B0, 1, 0); PG8_LDB(B1, 1, 1); PG8_SCHED; PG8_LDA(At, 1, 0); PG8_STAGE(PG8_SA(0, 1), a2 + hstepA, voffA);
;             PG8_WAIT_V(8); PG8_WAIT_L(0); PG8_BAR; PG8_MMA(0, 0, At, B0); PG8_MMA(0, 1, At, B1); PG8_BAR; PG8_SCHED;
;             PG8_LDA(At, 1, 1); PG8_STAGE(PG8_SB(1, 0), b3, voffB); PG8_STAGE(PG8_SB(1, 1), b3 + hstepB, voffB); PG8_STAGE(PG8_SA(1, 0), a3, voffA);
;             PG8_WAIT_V(8); PG8_WAIT_L(0); PG8_BAR; PG8_MMA(1, 0, At, B0); PG8_MMA(1, 1, At, B1); PG8_BAR; PG8_SCHED;
	s_setprio 1
	s_waitcnt lgkmcnt(0)
	v_mfma_f32_16x16x32_bf16 v[156:159], v[120:123], v[168:171], v[156:159]
	v_mfma_f32_16x16x32_bf16 v[60:63], v[128:131], v[168:171], v[60:63]
	v_mfma_f32_16x16x32_bf16 v[116:119], v[120:123], v[176:179], v[116:119]
	v_mfma_f32_16x16x32_bf16 v[52:55], v[128:131], v[176:179], v[52:55]
	v_mfma_f32_16x16x32_bf16 v[108:111], v[120:123], v[184:187], v[108:111]
	v_mfma_f32_16x16x32_bf16 v[44:47], v[128:131], v[184:187], v[44:47]
	v_mfma_f32_16x16x32_bf16 v[100:103], v[120:123], v[212:215], v[100:103]
	v_mfma_f32_16x16x32_bf16 v[36:39], v[128:131], v[212:215], v[36:39]
	v_mfma_f32_16x16x32_bf16 v[156:159], v[124:127], v[172:175], v[156:159]
	v_mfma_f32_16x16x32_bf16 v[60:63], v[132:135], v[172:175], v[60:63]
	v_mfma_f32_16x16x32_bf16 v[116:119], v[124:127], v[180:183], v[116:119]
	v_mfma_f32_16x16x32_bf16 v[52:55], v[132:135], v[180:183], v[52:55]
	v_mfma_f32_16x16x32_bf16 v[108:111], v[124:127], v[208:211], v[108:111]
	v_mfma_f32_16x16x32_bf16 v[44:47], v[132:135], v[208:211], v[44:47]
	v_mfma_f32_16x16x32_bf16 v[100:103], v[124:127], v[216:219], v[100:103]
	v_mfma_f32_16x16x32_bf16 v[36:39], v[132:135], v[216:219], v[36:39]
	s_setprio 0
	s_setprio 1
	v_mfma_f32_16x16x32_bf16 v[152:155], v[136:139], v[168:171], v[152:155]
	v_mfma_f32_16x16x32_bf16 v[56:59], v[144:147], v[168:171], v[56:59]
	v_mfma_f32_16x16x32_bf16 v[112:115], v[136:139], v[176:179], v[112:115]
	v_mfma_f32_16x16x32_bf16 v[48:51], v[144:147], v[176:179], v[48:51]
	v_mfma_f32_16x16x32_bf16 v[104:107], v[136:139], v[184:187], v[104:107]
	v_mfma_f32_16x16x32_bf16 v[40:43], v[144:147], v[184:187], v[40:43]
	v_mfma_f32_16x16x32_bf16 v[96:99], v[136:139], v[212:215], v[96:99]
	v_mfma_f32_16x16x32_bf16 v[32:35], v[144:147], v[212:215], v[32:35]
	v_mfma_f32_16x16x32_bf16 v[152:155], v[140:143], v[172:175], v[152:155]
	v_mfma_f32_16x16x32_bf16 v[56:59], v[148:151], v[172:175], v[56:59]
	v_mfma_f32_16x16x32_bf16 v[112:115], v[140:143], v[180:183], v[112:115]
	v_mfma_f32_16x16x32_bf16 v[48:51], v[148:151], v[180:183], v[48:51]
	v_mfma_f32_16x16x32_bf16 v[104:107], v[140:143], v[208:211], v[104:107]
	v_mfma_f32_16x16x32_bf16 v[40:43], v[148:151], v[208:211], v[40:43]
	v_mfma_f32_16x16x32_bf16 v[96:99], v[140:143], v[216:219], v[96:99]
	v_mfma_f32_16x16x32_bf16 v[32:35], v[148:151], v[216:219], v[32:35]
	s_setprio 0
	s_barrier
	s_add_i32 s34, s52, s36
	v_lshl_add_u64 v[220:221], v[220:221], 0, s[8:9]
	s_mov_b32 m0, s34
	ds_read_b128 v[168:171], v207 offset:49152
	ds_read_b128 v[172:175], v207 offset:50176
	ds_read_b128 v[176:179], v207 offset:51200
	ds_read_b128 v[180:183], v207 offset:52224
	ds_read_b128 v[184:187], v207 offset:53248
	ds_read_b128 v[208:211], v207 offset:54272
	ds_read_b128 v[212:215], v207 offset:55296
	ds_read_b128 v[216:219], v207 offset:56320
	global_load_lds_dwordx4 v[220:221], off
	s_add_i32 m0, s34, 0x2000
	s_add_u32 s30, s30, 0x80080
	v_lshl_add_u64 v[220:221], v[222:223], 0, s[8:9]
	s_addc_u32 s31, s31, 0
	s_add_i32 s34, s53, s36
	global_load_lds_dwordx4 v[220:221], off
	v_lshl_add_u64 v[220:221], s[30:31], 0, v[162:163]
	s_mov_b32 m0, s34
	s_nop 0
	global_load_lds_dwordx4 v[220:221], off
	v_lshl_add_u64 v[220:221], s[30:31], 0, v[160:161]
	s_add_i32 m0, s34, 0x2000
	s_nop 0
	global_load_lds_dwordx4 v[220:221], off
	v_lshl_add_u64 v[220:221], v[224:225], 0, s[8:9]
	s_mov_b32 m0, s42
	s_nop 0
	global_load_lds_dwordx4 v[220:221], off
	v_lshl_add_u64 v[220:221], v[226:227], 0, s[8:9]
	s_mov_b32 m0, s43
	s_nop 0
	global_load_lds_dwordx4 v[220:221], off
	s_waitcnt vmcnt(8)
	s_waitcnt lgkmcnt(0)
	s_barrier
	s_waitcnt lgkmcnt(0)
	s_barrier
	s_add_i32 s51, s51, 2
	s_add_u32 s28, s28, 0x100
	s_addc_u32 s29, s29, 0
	s_add_u32 s49, s49, 0x100
	s_addc_u32 s50, s50, 0
	s_cmp_gt_u32 s51, 29
	s_cbranch_scc0 .Lp9h_A
	s_branch .Lp9h_join
	.p2align 6
.Lp9h_B:
	ds_read_b128 v[120:123], v205
	ds_read_b128 v[124:127], v205 offset:1024
	ds_read_b128 v[128:131], v205 offset:2048
	ds_read_b128 v[132:135], v205 offset:3072
	ds_read_b128 v[136:139], v206
	ds_read_b128 v[140:143], v206 offset:1024
	ds_read_b128 v[144:147], v206 offset:2048
	ds_read_b128 v[148:151], v206 offset:3072
	s_add_u32 s30, s28, 0xfff80080
	s_addc_u32 s31, s29, -1
	s_cmp_eq_u32 s51, 28
	s_cselect_b32 s35, s19, s31
	s_cselect_b32 s34, s47, s30
	s_cselect_b32 s31, s17, s50
	s_cselect_b32 s30, s48, s49
	v_lshl_add_u64 v[220:221], s[28:29], 0, v[164:165]
	s_add_i32 m0, s27, 0xc000
	ds_read_b128 v[168:171], v207
	ds_read_b128 v[172:175], v207 offset:1024
	ds_read_b128 v[176:179], v207 offset:2048
	ds_read_b128 v[180:183], v207 offset:3072
	ds_read_b128 v[184:187], v207 offset:4096
	ds_read_b128 v[208:211], v207 offset:5120
	ds_read_b128 v[212:215], v207 offset:6144
	ds_read_b128 v[216:219], v207 offset:7168
	global_load_lds_dwordx4 v[220:221], off
	v_lshl_add_u64 v[220:221], s[28:29], 0, v[166:167]
	s_add_i32 m0, s27, 0xe000
	s_nop 0
	global_load_lds_dwordx4 v[220:221], off
	s_waitcnt vmcnt(8)
	s_waitcnt lgkmcnt(0)
	s_barrier
	s_waitcnt lgkmcnt(0)
	s_barrier
	s_add_i32 s52, s44, s36
	v_lshl_add_u64 v[220:221], s[30:31], 0, v[162:163]
	s_mov_b32 m0, s52
	ds_read_b128 v[168:171], v207 offset:16384
	ds_read_b128 v[172:175], v207 offset:17408
	ds_read_b128 v[176:179], v207 offset:18432
	ds_read_b128 v[180:183], v207 offset:19456
	ds_read_b128 v[184:187], v207 offset:20480
	ds_read_b128 v[208:211], v207 offset:21504
	ds_read_b128 v[212:215], v207 offset:22528
	ds_read_b128 v[216:219], v207 offset:23552
	global_load_lds_dwordx4 v[220:221], off
	s_add_i32 m0, s52, 0x2000
	s_add_u32 s52, s30, 0x80000
	v_lshl_add_u64 v[222:223], s[30:31], 0, v[160:161]
	s_addc_u32 s53, s31, 0
	s_add_i32 s54, s45, s36
	global_load_lds_dwordx4 v[222:223], off
	v_lshl_add_u64 v[224:225], s[52:53], 0, v[162:163]
	s_mov_b32 m0, s54
	v_lshl_add_u64 v[226:227], s[34:35], 0, v[160:161]
	global_load_lds_dwordx4 v[224:225], off
	v_lshl_add_u64 v[224:225], s[52:53], 0, v[160:161]
	s_add_i32 m0, s54, 0x2000
	s_nop 0
	global_load_lds_dwordx4 v[224:225], off
	v_lshl_add_u64 v[224:225], s[34:35], 0, v[162:163]
	s_mov_b32 m0, s27
	s_nop 0
	global_load_lds_dwordx4 v[224:225], off
	s_mov_b32 m0, s38
	s_nop 0
	global_load_lds_dwordx4 v[226:227], off
	s_waitcnt vmcnt(8)
	s_waitcnt lgkmcnt(0)
	s_barrier
; #define PG8_STAGE(bufoff, gbase, voff) do { _Pragma("unroll") for (int _i = 0; _i < 2; ++_i) \
;         __builtin_amdgcn_global_load_lds((const unsigned*)((const char*)(gbase) + (voff)[_i]), (LAS unsigned*)(lds + (bufoff) + ldsw + _i * 8192), 16, 0, 0); } while (0)
; #define PG8_LDA(dst, b, h) do { _Pragma("unroll") for (int m = 0; m < 4; ++m) _Pragma("unroll") for (int k = 0; k < 2; ++k) dst[m][k] = *(const LAS bf16x8*)(lds + PG8_SA(b, h) + aoff + m * 2048 + k * 1024); } while (0)
; #define PG8_LDB(dst, b, h) do { _Pragma("unroll") for (int n = 0; n < 2; ++n) _Pragma("unroll") for (int k = 0; k < 2; ++k) dst[n][k] = *(const LAS bf16x8*)(lds + PG8_SB(b, h) + boff + n * 2048 + k * 1024); } while (0)
; #define PG8_MMA(ai, bj, At, Bt) do { __builtin_amdgcn_s_setprio(1); _Pragma("unroll") for (int m = 0; m < 4; ++m) _Pragma("unroll") for (int n = 0; n < 2; ++n) _Pragma("unroll") for (int k = 0; k < 2; ++k) \
;         acc[ai][bj][m][n] = __builtin_amdgcn_mfma_f32_16x16x32_bf16(Bt[n][k], At[m][k], acc[ai][bj][m][n], 0, 0, 0); __builtin_amdgcn_s_setprio(0); } while (0)
; #define PG8_WAIT_V(n) asm volatile("s_waitcnt vmcnt(" #n ")" ::: "memory")
; #define PG8_WAIT_L(n) asm volatile("s_waitcnt lgkmcnt(" #n ")" ::: "memory")
; #define PG8_BAR __builtin_amdgcn_s_barrier()
; #define PG8_SCHED __builtin_amdgcn_sched_barrier(0)
; template <class Epi, class Sched, bool DEFER>
; __device__ __forceinline__ void gemm_fast_core(LAS unsigned char* lds, const GemmP g, const Sched& S, const Epi& E, f32x4 (&acc)[2][2][4][2], Unit& cur) {
;     ...
;             PG8_WAIT_V(8); PG8_WAIT_L(0); PG8_BAR; PG8_MMA(1, 0, At, B0); PG8_MMA(1, 1, At, B1); PG8_BAR; PG8_SCHED;
;             PG8_LDB(B0, 1, 0); PG8_LDB(B1, 1, 1); PG8_SCHED; PG8_LDA(At, 1, 0); PG8_STAGE(PG8_SA(0, 1), a2 + hstepA, voffA);
;             PG8_WAIT_V(8); PG8_WAIT_L(0); PG8_BAR; PG8_MMA(0, 0, At, B0); PG8_MMA(0, 1, At, B1); PG8_BAR; PG8_SCHED;
;             PG8_LDA(At, 1, 1); PG8_STAGE(PG8_SB(1, 0), b3, voffB); PG8_STAGE(PG8_SB(1, 1), b3 + hstepB, voffB); PG8_STAGE(PG8_SA(1, 0), a3, voffA);
;             PG8_WAIT_V(8); PG8_WAIT_L(0); PG8_BAR; PG8_MMA(1, 0, At, B0); PG8_MMA(1, 1, At, B1); PG8_BAR; PG8_SCHED;
	s_setprio 1
	s_waitcnt lgkmcnt(0)
	v_mfma_f32_16x16x32_bf16 v[92:95], v[120:123], v[168:171], v[92:95]
	v_mfma_f32_16x16x32_bf16 v[28:31], v[128:131], v[168:171], v[28:31]
	v_mfma_f32_16x16x32_bf16 v[84:87], v[120:123], v[176:179], v[84:87]
	v_mfma_f32_16x16x32_bf16 v[20:23], v[128:131], v[176:179], v[20:23]
	v_mfma_f32_16x16x32_bf16 v[76:79], v[120:123], v[184:187], v[76:79]
	v_mfma_f32_16x16x32_bf16 v[12:15], v[128:131], v[184:187], v[12:15]
	v_mfma_f32_16x16x32_bf16 v[68:71], v[120:123], v[212:215], v[68:71]
	v_mfma_f32_16x16x32_bf16 v[4:7], v[128:131], v[212:215], v[4:7]
	v_mfma_f32_16x16x32_bf16 v[92:95], v[124:127], v[172:175], v[92:95]
	v_mfma_f32_16x16x32_bf16 v[28:31], v[132:135], v[172:175], v[28:31]
	v_mfma_f32_16x16x32_bf16 v[84:87], v[124:127], v[180:183], v[84:87]
	v_mfma_f32_16x16x32_bf16 v[20:23], v[132:135], v[180:183], v[20:23]
	v_mfma_f32_16x16x32_bf16 v[76:79], v[124:127], v[208:211], v[76:79]
	v_mfma_f32_16x16x32_bf16 v[12:15], v[132:135], v[208:211], v[12:15]
	v_mfma_f32_16x16x32_bf16 v[68:71], v[124:127], v[216:219], v[68:71]
	v_mfma_f32_16x16x32_bf16 v[4:7], v[132:135], v[216:219], v[4:7]
	s_setprio 0
	s_setprio 1
	v_mfma_f32_16x16x32_bf16 v[88:91], v[136:139], v[168:171], v[88:91]
	v_mfma_f32_16x16x32_bf16 v[24:27], v[144:147], v[168:171], v[24:27]
	v_mfma_f32_16x16x32_bf16 v[80:83], v[136:139], v[176:179], v[80:83]
	v_mfma_f32_16x16x32_bf16 v[16:19], v[144:147], v[176:179], v[16:19]
	v_mfma_f32_16x16x32_bf16 v[72:75], v[136:139], v[184:187], v[72:75]
	v_mfma_f32_16x16x32_bf16 v[8:11], v[144:147], v[184:187], v[8:11]
	v_mfma_f32_16x16x32_bf16 v[64:67], v[136:139], v[212:215], v[64:67]
	v_mfma_f32_16x16x32_bf16 v[0:3], v[144:147], v[212:215], v[0:3]
	v_mfma_f32_16x16x32_bf16 v[88:91], v[140:143], v[172:175], v[88:91]
	v_mfma_f32_16x16x32_bf16 v[24:27], v[148:151], v[172:175], v[24:27]
	v_mfma_f32_16x16x32_bf16 v[80:83], v[140:143], v[180:183], v[80:83]
	v_mfma_f32_16x16x32_bf16 v[16:19], v[148:151], v[180:183], v[16:19]
	v_mfma_f32_16x16x32_bf16 v[72:75], v[140:143], v[208:211], v[72:75]
	v_mfma_f32_16x16x32_bf16 v[8:11], v[148:151], v[208:211], v[8:11]
	v_mfma_f32_16x16x32_bf16 v[64:67], v[140:143], v[216:219], v[64:67]
	v_mfma_f32_16x16x32_bf16 v[0:3], v[148:151], v[216:219], v[0:3]
	s_setprio 0
	s_barrier
	s_add_i32 s52, 0, 0x18000
	s_add_i32 s53, 0, 0x1c000
	v_add_u32_e32 v132, s52, v196
	v_add_u32_e32 v148, s53, v196
	ds_read_b128 v[120:123], v132
	ds_read_b128 v[124:127], v132 offset:1024
	ds_read_b128 v[128:131], v132 offset:2048
	ds_read_b128 v[132:135], v132 offset:3072
	ds_read_b128 v[136:139], v148
	ds_read_b128 v[140:143], v148 offset:1024
	ds_read_b128 v[144:147], v148 offset:2048
	ds_read_b128 v[148:151], v148 offset:3072
	s_add_u32 s34, s34, 0x80000
	s_addc_u32 s35, s35, 0
	s_mov_b32 m0, s39
	v_lshl_add_u64 v[228:229], s[34:35], 0, v[162:163]
	ds_read_b128 v[168:171], v207 offset:32768
	ds_read_b128 v[172:175], v207 offset:33792
	ds_read_b128 v[176:179], v207 offset:34816
	ds_read_b128 v[180:183], v207 offset:35840
	ds_read_b128 v[184:187], v207 offset:36864
	ds_read_b128 v[208:211], v207 offset:37888
	ds_read_b128 v[212:215], v207 offset:38912
	ds_read_b128 v[216:219], v207 offset:39936
	global_load_lds_dwordx4 v[228:229], off
	v_lshl_add_u64 v[228:229], s[34:35], 0, v[160:161]
	s_mov_b32 m0, s40
	s_nop 0
	global_load_lds_dwordx4 v[228:229], off
	s_waitcnt vmcnt(8)
	s_waitcnt lgkmcnt(0)
	s_barrier
	s_waitcnt lgkmcnt(0)
	s_barrier
	s_add_i32 s34, s52, s36
	v_lshl_add_u64 v[220:221], v[220:221], 0, s[8:9]
	s_mov_b32 m0, s34
	ds_read_b128 v[168:171], v207 offset:49152
	ds_read_b128 v[172:175], v207 offset:50176
	ds_read_b128 v[176:179], v207 offset:51200
	ds_read_b128 v[180:183], v207 offset:52224
	ds_read_b128 v[184:187], v207 offset:53248
	ds_read_b128 v[208:211], v207 offset:54272
	ds_read_b128 v[212:215], v207 offset:55296
	ds_read_b128 v[216:219], v207 offset:56320
	global_load_lds_dwordx4 v[220:221], off
	s_add_i32 m0, s34, 0x2000
	s_add_u32 s30, s30, 0x80080
	v_lshl_add_u64 v[220:221], v[222:223], 0, s[8:9]
	s_addc_u32 s31, s31, 0
	s_add_i32 s34, s53, s36
	global_load_lds_dwordx4 v[220:221], off
	v_lshl_add_u64 v[220:221], s[30:31], 0, v[162:163]
	s_mov_b32 m0, s34
	s_nop 0
	global_load_lds_dwordx4 v[220:221], off
	v_lshl_add_u64 v[220:221], s[30:31], 0, v[160:161]
	s_add_i32 m0, s34, 0x2000
	s_nop 0
	global_load_lds_dwordx4 v[220:221], off
	v_lshl_add_u64 v[220:221], v[224:225], 0, s[8:9]
	s_mov_b32 m0, s42
	s_nop 0
	global_load_lds_dwordx4 v[220:221], off
	v_lshl_add_u64 v[220:221], v[226:227], 0, s[8:9]
	s_mov_b32 m0, s43
	s_nop 0
	global_load_lds_dwordx4 v[220:221], off
	s_waitcnt vmcnt(8)
	s_waitcnt lgkmcnt(0)
	s_barrier
; #define PG8_MMA(ai, bj, At, Bt) do { __builtin_amdgcn_s_setprio(1); _Pragma("unroll") for (int m = 0; m < 4; ++m) _Pragma("unroll") for (int n = 0; n < 2; ++n) _Pragma("unroll") for (int k = 0; k < 2; ++k) \
;         acc[ai][bj][m][n] = __builtin_amdgcn_mfma_f32_16x16x32_bf16(Bt[n][k], At[m][k], acc[ai][bj][m][n], 0, 0, 0); __builtin_amdgcn_s_setprio(0); } while (0)
; #define PG8_WAIT_V(n) asm volatile("s_waitcnt vmcnt(" #n ")" ::: "memory")
; #define PG8_WAIT_L(n) asm volatile("s_waitcnt lgkmcnt(" #n ")" ::: "memory")
; #define PG8_BAR __builtin_amdgcn_s_barrier()
; #define PG8_SCHED __builtin_amdgcn_sched_barrier(0)
;     __device__ __forceinline__ void tile(const f32x4 (&acc)[2][2][4][2], const Unit& u, int wr, int wc, int fr, int fq) const {
; #pragma unroll
;         for (int n = 0; n < 2; ++n) {
;             const int cv = 128 * u.pn + 32 * wc + 16 * n + 4 * fq, cg = FF + cv;
;             const f32x4 wv0 = *(const f32x4*)(cw + cv), wv1 = *(const f32x4*)(cw + F2 + cv), wv2 = *(const f32x4*)(cw + 2 * F2 + cv), bv = *(const f32x4*)(cb + cv);
;             const f32x4 wg0 = *(const f32x4*)(cw + cg), wg1 = *(const f32x4*)(cw + F2 + cg), wg2 = *(const f32x4*)(cw + 2 * F2 + cg), bg = *(const f32x4*)(cb + cg);
; template <class Epi, class Sched, bool DEFER>
; __device__ __forceinline__ void gemm_fast_core(LAS unsigned char* lds, const GemmP g, const Sched& S, const Epi& E, f32x4 (&acc)[2][2][4][2], Unit& cur) {
;     ...
;             PG8_WAIT_V(8); PG8_WAIT_L(0); PG8_BAR; PG8_MMA(1, 0, At, B0); PG8_MMA(1, 1, At, B1); PG8_BAR; PG8_SCHED;
;         }
;         if (wr == 0) PG8_BAR;
	s_setprio 1
	s_waitcnt lgkmcnt(0)
	v_mfma_f32_16x16x32_bf16 v[92:95], v[120:123], v[168:171], v[92:95]
	v_mfma_f32_16x16x32_bf16 v[28:31], v[128:131], v[168:171], v[28:31]
	v_mfma_f32_16x16x32_bf16 v[84:87], v[120:123], v[176:179], v[84:87]
	v_mfma_f32_16x16x32_bf16 v[20:23], v[128:131], v[176:179], v[20:23]
	v_mfma_f32_16x16x32_bf16 v[76:79], v[120:123], v[184:187], v[76:79]
	v_mfma_f32_16x16x32_bf16 v[12:15], v[128:131], v[184:187], v[12:15]
	v_mfma_f32_16x16x32_bf16 v[68:71], v[120:123], v[212:215], v[68:71]
	v_mfma_f32_16x16x32_bf16 v[4:7], v[128:131], v[212:215], v[4:7]
	v_mfma_f32_16x16x32_bf16 v[92:95], v[124:127], v[172:175], v[92:95]
	v_mfma_f32_16x16x32_bf16 v[28:31], v[132:135], v[172:175], v[28:31]
	v_mfma_f32_16x16x32_bf16 v[84:87], v[124:127], v[180:183], v[84:87]
	v_mfma_f32_16x16x32_bf16 v[20:23], v[132:135], v[180:183], v[20:23]
	v_mfma_f32_16x16x32_bf16 v[76:79], v[124:127], v[208:211], v[76:79]
	v_mfma_f32_16x16x32_bf16 v[12:15], v[132:135], v[208:211], v[12:15]
	v_mfma_f32_16x16x32_bf16 v[68:71], v[124:127], v[216:219], v[68:71]
	v_mfma_f32_16x16x32_bf16 v[4:7], v[132:135], v[216:219], v[4:7]
	s_setprio 0
	s_setprio 1
	v_mfma_f32_16x16x32_bf16 v[88:91], v[136:139], v[168:171], v[88:91]
	v_mfma_f32_16x16x32_bf16 v[24:27], v[144:147], v[168:171], v[24:27]
	v_mfma_f32_16x16x32_bf16 v[80:83], v[136:139], v[176:179], v[80:83]
	v_mfma_f32_16x16x32_bf16 v[16:19], v[144:147], v[176:179], v[16:19]
	v_mfma_f32_16x16x32_bf16 v[72:75], v[136:139], v[184:187], v[72:75]
	v_mfma_f32_16x16x32_bf16 v[8:11], v[144:147], v[184:187], v[8:11]
	v_mfma_f32_16x16x32_bf16 v[64:67], v[136:139], v[212:215], v[64:67]
	v_mfma_f32_16x16x32_bf16 v[0:3], v[144:147], v[212:215], v[0:3]
	v_mfma_f32_16x16x32_bf16 v[88:91], v[140:143], v[172:175], v[88:91]
	v_mfma_f32_16x16x32_bf16 v[24:27], v[148:151], v[172:175], v[24:27]
	v_mfma_f32_16x16x32_bf16 v[80:83], v[140:143], v[180:183], v[80:83]
	v_mfma_f32_16x16x32_bf16 v[16:19], v[148:151], v[180:183], v[16:19]
	v_mfma_f32_16x16x32_bf16 v[72:75], v[140:143], v[208:211], v[72:75]
	v_mfma_f32_16x16x32_bf16 v[8:11], v[148:151], v[208:211], v[8:11]
	v_mfma_f32_16x16x32_bf16 v[64:67], v[140:143], v[216:219], v[64:67]
	v_mfma_f32_16x16x32_bf16 v[0:3], v[148:151], v[216:219], v[0:3]
	s_setprio 0
	s_barrier
	s_add_i32 s51, s51, 2
	s_add_u32 s28, s28, 0x100
	s_addc_u32 s29, s29, 0
	s_add_u32 s49, s49, 0x100
	s_addc_u32 s50, s50, 0
	s_cmp_gt_u32 s51, 29
	s_cbranch_scc0 .Lp9h_B
.Lp9h_join:
	s_and_b64 vcc, exec, s[10:11]
	s_cbranch_vccz .LBB0_1802
	s_barrier
.LBB0_1802:
	v_lshl_or_b32 v170, s33, 7, v204
	v_ashrrev_i32_e32 v171, 31, v170
	v_lshlrev_b64 v[120:121], 2, v[170:171]
	v_lshl_add_u64 v[172:173], s[56:57], 0, v[120:121]
	v_add_co_u32_e32 v176, vcc, 0x5000, v172
	v_lshl_add_u64 v[122:123], s[12:13], 0, v[120:121]
	s_nop 0
	v_addc_co_u32_e32 v177, vcc, 0, v173, vcc
	v_add_co_u32_e32 v178, vcc, 0x5000, v122
	v_lshl_add_u64 v[124:125], s[14:15], 0, v[120:121]
	s_nop 0
	v_addc_co_u32_e32 v179, vcc, 0, v123, vcc
	global_load_dwordx4 v[132:135], v[176:177], off offset:2048
	global_load_dwordx4 v[148:151], v[178:179], off offset:2048
	v_add_co_u32_e32 v180, vcc, 0x5000, v124
	v_lshl_add_u64 v[174:175], s[58:59], 0, v[120:121]
	s_nop 0
	v_addc_co_u32_e32 v181, vcc, 0, v125, vcc
	global_load_dwordx4 v[136:139], v[180:181], off offset:2048
	v_add_co_u32_e32 v182, vcc, 0x5000, v174
	v_cndmask_b32_e64 v168, v156, 0, s[4:5]
	s_nop 0
	v_addc_co_u32_e32 v183, vcc, 0, v175, vcc
	global_load_dwordx4 v[140:143], v[182:183], off offset:2048
	global_load_dwordx4 v[144:147], v[122:123], off
	s_nop 0
	global_load_dwordx4 v[120:123], v[172:173], off
	s_nop 0
	global_load_dwordx4 v[124:127], v[124:125], off
	s_nop 0
	global_load_dwordx4 v[128:131], v[174:175], off
	v_cndmask_b32_e64 v169, v152, 0, s[4:5]
	v_mov_b32_dpp v208, v168 row_ror:1 row_mask:0xf bank_mask:0xf
	s_nop 0
	v_mov_b32_dpp v168, v169 row_ror:1 row_mask:0xf bank_mask:0xf
	v_cndmask_b32_e64 v169, v156, v116, s[6:7]
	v_cndmask_b32_e64 v184, v153, 0, s[4:5]
	s_nop 0
	v_mov_b32_dpp v210, v169 row_ror:15 row_mask:0xf bank_mask:0xf
	v_cndmask_b32_e64 v169, v152, v112, s[6:7]
	s_nop 1
	v_mov_b32_dpp v186, v169 row_ror:15 row_mask:0xf bank_mask:0xf
	v_cndmask_b32_e64 v169, v157, 0, s[4:5]
	s_nop 1
	v_mov_b32_dpp v209, v169 row_ror:1 row_mask:0xf bank_mask:0xf
	v_mov_b32_dpp v169, v184 row_ror:1 row_mask:0xf bank_mask:0xf
	v_cndmask_b32_e64 v184, v157, v117, s[6:7]
	s_nop 1
	v_mov_b32_dpp v211, v184 row_ror:15 row_mask:0xf bank_mask:0xf
	v_cndmask_b32_e64 v184, v153, v113, s[6:7]
	s_lshl_b32 s17, s26, 8
	s_nop 0
	v_mov_b32_dpp v187, v184 row_ror:15 row_mask:0xf bank_mask:0xf
	v_cndmask_b32_e64 v184, v158, 0, s[4:5]
	v_add_u32_e32 v220, s17, v195
	s_andn2_b64 vcc, exec, s[20:21]
	v_mov_b32_dpp v212, v184 row_ror:1 row_mask:0xf bank_mask:0xf
	v_cndmask_b32_e64 v184, v154, 0, s[4:5]
	s_mov_b64 s[20:21], -1
	s_waitcnt vmcnt(0)
; __device__ __forceinline__ void st_bf4(bf16_t* p, f32x4 v) { u32x2 w; w.x = pk2(v[0], v[1]); w.y = pk2(v[2], v[3]); *(u32x2*)p = w; }
; __device__ __forceinline__ float sigmoidf_(float x) { return __builtin_amdgcn_rcpf(1.f + __expf(-x)); }
; __device__ __forceinline__ float dpp_ror1(float v) { return __int_as_float(__builtin_amdgcn_update_dpp(0, __float_as_int(v), 0x121, 0xf, 0xf, false)); }
; __device__ __forceinline__ float dpp_rol1(float v) { return __int_as_float(__builtin_amdgcn_update_dpp(0, __float_as_int(v), 0x12F, 0xf, 0xf, false)); }
;     __device__ __forceinline__ void tile(const f32x4 (&acc)[2][2][4][2], const Unit& u, int wr, int wc, int fr, int fq) const {
;     ...
;                     for (int i = 0; i < 4; ++i) {
;                         const float xv = acc[ai][0][m][n][i], xg = acc[ai][1][m][n][i];
;                         const float uv = m > 0 ? acc[ai][0][m > 0 ? m - 1 : 0][n][i] : 0.f, ug = m > 0 ? acc[ai][1][m > 0 ? m - 1 : 0][n][i] : 0.f;
;                         const float dv = m < 3 ? acc[ai][0][m < 3 ? m + 1 : 3][n][i] : 0.f, dg = m < 3 ? acc[ai][1][m < 3 ? m + 1 : 3][n][i] : 0.f;
;                         const float pv = dpp_ror1(fr == 15 ? uv : xv), pg = dpp_ror1(fr == 15 ? ug : xg);
;                         const float nv = dpp_rol1(fr == 0 ? dv : xv), ng = dpp_rol1(fr == 0 ? dg : xg);
;                         const float yv = wv0[i] * pv + wv1[i] * xv + wv2[i] * nv + bv[i];
;                         const float yg = wg0[i] * pg + wg1[i] * xg + wg2[i] * ng + bg[i];
;                         r[i] = yg * sigmoidf_(yg) * yv;
;                     }
;                     st_bf4(ACT + (size_t)(u.pm * BM + ai * HALF + wr * 64 + m * 16 + fr) * FF + cv, r);
	v_pk_mul_f32 v[222:223], v[152:153], v[148:149]
	s_nop 0
	v_pk_fma_f32 v[168:169], v[132:133], v[168:169], v[222:223]
	v_mov_b32_dpp v214, v184 row_ror:1 row_mask:0xf bank_mask:0xf
	v_cndmask_b32_e64 v184, v158, v118, s[6:7]
	v_pk_fma_f32 v[168:169], v[136:137], v[186:187], v[168:169]
	v_lshlrev_b64 v[186:187], 1, v[170:171]
	v_pk_add_f32 v[222:223], v[140:141], v[168:169]
	v_mov_b32_dpp v216, v184 row_ror:15 row_mask:0xf bank_mask:0xf
	v_mul_f32_e32 v168, 0xbfb8aa3b, v222
	v_exp_f32_e32 v224, v168
	v_cndmask_b32_e64 v184, v154, v114, s[6:7]
	v_pk_mul_f32 v[228:229], v[156:157], v[144:145]
	v_pk_mul_f32 v[226:227], v[158:159], v[146:147]
	v_add_f32_e32 v171, 1.0, v224
	v_mul_f32_e32 v224, 0xbfb8aa3b, v223
	v_exp_f32_e32 v225, v224
	v_mov_b32_dpp v218, v184 row_ror:15 row_mask:0xf bank_mask:0xf
	v_cndmask_b32_e64 v184, v159, 0, s[4:5]
	v_rcp_f32_e32 v224, v171
	v_add_f32_e32 v171, 1.0, v225
	v_mov_b32_dpp v213, v184 row_ror:1 row_mask:0xf bank_mask:0xf
	v_cndmask_b32_e64 v184, v155, 0, s[4:5]
	v_rcp_f32_e32 v225, v171
	v_pk_fma_f32 v[208:209], v[120:121], v[208:209], v[228:229]
	v_mov_b32_dpp v215, v184 row_ror:1 row_mask:0xf bank_mask:0xf
	v_cndmask_b32_e64 v184, v159, v119, s[6:7]
	v_pk_fma_f32 v[208:209], v[124:125], v[210:211], v[208:209]
	v_pk_mul_f32 v[210:211], v[222:223], v[224:225]
	v_mov_b32_dpp v217, v184 row_ror:15 row_mask:0xf bank_mask:0xf
	v_cndmask_b32_e64 v184, v155, v115, s[6:7]
	v_pk_add_f32 v[208:209], v[128:129], v[208:209]
	v_pk_fma_f32 v[212:213], v[122:123], v[212:213], v[226:227]
	v_mov_b32_dpp v219, v184 row_ror:15 row_mask:0xf bank_mask:0xf
	v_mov_b64_e32 v[184:185], s[0:1]
	v_mad_i64_i32 v[220:221], s[28:29], v220, s46, v[184:185]
	v_lshl_add_u64 v[168:169], v[220:221], 0, v[186:187]
	v_pk_mul_f32 v[220:221], v[154:155], v[150:151]
	v_pk_mul_f32 v[208:209], v[208:209], v[210:211]
	v_pk_fma_f32 v[210:211], v[134:135], v[214:215], v[220:221]
	v_pk_fma_f32 v[212:213], v[126:127], v[216:217], v[212:213]
	v_pk_fma_f32 v[210:211], v[138:139], v[218:219], v[210:211]
	v_pk_add_f32 v[212:213], v[130:131], v[212:213]
	v_pk_add_f32 v[210:211], v[142:143], v[210:211]
	v_cvt_pk_bf16_f32 v208, v208, v209
	v_mul_f32_e32 v171, 0xbfb8aa3b, v210
	v_exp_f32_e32 v171, v171
	v_mul_f32_e32 v214, 0xbfb8aa3b, v211
	v_exp_f32_e32 v215, v214
	v_pk_mul_f32 v[216:217], v[112:113], v[148:149]
	v_add_f32_e32 v171, 1.0, v171
	v_rcp_f32_e32 v214, v171
	v_add_f32_e32 v171, 1.0, v215
	v_rcp_f32_e32 v215, v171
	v_cndmask_b32_e64 v171, v116, v156, s[4:5]
	v_pk_mul_f32 v[222:223], v[116:117], v[144:145]
	v_pk_mul_f32 v[210:211], v[210:211], v[214:215]
	v_mov_b32_dpp v156, v171 row_ror:1 row_mask:0xf bank_mask:0xf
	v_pk_mul_f32 v[210:211], v[212:213], v[210:211]
	v_cndmask_b32_e64 v171, v112, v152, s[4:5]
	v_cvt_pk_bf16_f32 v209, v210, v211
	s_cmp_eq_u32 s98, 2
	s_cbranch_scc1 .Lp9h_st0
	global_store_dwordx2 v[168:169], v[208:209], off
.Lp9h_st0:
	v_mov_b32_dpp v152, v171 row_ror:1 row_mask:0xf bank_mask:0xf
	v_cndmask_b32_e64 v171, v116, v108, s[6:7]
	s_nop 1
	v_mov_b32_dpp v208, v171 row_ror:15 row_mask:0xf bank_mask:0xf
	v_cndmask_b32_e64 v171, v112, v104, s[6:7]
	s_nop 1
	v_mov_b32_dpp v210, v171 row_ror:15 row_mask:0xf bank_mask:0xf
	v_cndmask_b32_e64 v171, v117, v157, s[4:5]
	s_nop 1
	v_mov_b32_dpp v157, v171 row_ror:1 row_mask:0xf bank_mask:0xf
	v_cndmask_b32_e64 v171, v113, v153, s[4:5]
	v_pk_fma_f32 v[156:157], v[120:121], v[156:157], v[222:223]
	s_nop 0
	v_mov_b32_dpp v153, v171 row_ror:1 row_mask:0xf bank_mask:0xf
	v_cndmask_b32_e64 v171, v117, v109, s[6:7]
	v_pk_fma_f32 v[152:153], v[132:133], v[152:153], v[216:217]
	v_pk_mul_f32 v[216:217], v[114:115], v[150:151]
	v_mov_b32_dpp v209, v171 row_ror:15 row_mask:0xf bank_mask:0xf
	v_cndmask_b32_e64 v171, v113, v105, s[6:7]
	v_pk_fma_f32 v[156:157], v[124:125], v[208:209], v[156:157]
	v_pk_mul_f32 v[220:221], v[118:119], v[146:147]
	v_mov_b32_dpp v211, v171 row_ror:15 row_mask:0xf bank_mask:0xf
	v_cndmask_b32_e64 v171, v118, v158, s[4:5]
	v_pk_fma_f32 v[152:153], v[136:137], v[210:211], v[152:153]
	v_pk_add_f32 v[156:157], v[128:129], v[156:157]
	v_mov_b32_dpp v158, v171 row_ror:1 row_mask:0xf bank_mask:0xf
	v_cndmask_b32_e64 v171, v114, v154, s[4:5]
	v_pk_add_f32 v[210:211], v[140:141], v[152:153]
	s_nop 0
	v_mov_b32_dpp v154, v171 row_ror:1 row_mask:0xf bank_mask:0xf
	v_cndmask_b32_e64 v171, v118, v110, s[6:7]
	v_mul_f32_e32 v152, 0xbfb8aa3b, v210
	v_exp_f32_e32 v218, v152
	v_mov_b32_dpp v212, v171 row_ror:15 row_mask:0xf bank_mask:0xf
	v_cndmask_b32_e64 v171, v114, v106, s[6:7]
	s_nop 1
	v_mov_b32_dpp v214, v171 row_ror:15 row_mask:0xf bank_mask:0xf
	v_cndmask_b32_e64 v171, v119, v159, s[4:5]
	s_nop 1
	v_mov_b32_dpp v159, v171 row_ror:1 row_mask:0xf bank_mask:0xf
	v_cndmask_b32_e64 v171, v115, v155, s[4:5]
	v_pk_fma_f32 v[158:159], v[122:123], v[158:159], v[220:221]
	s_nop 0
	v_mov_b32_dpp v155, v171 row_ror:1 row_mask:0xf bank_mask:0xf
	v_cndmask_b32_e64 v171, v119, v111, s[6:7]
	v_pk_fma_f32 v[154:155], v[134:135], v[154:155], v[216:217]
	v_pk_mul_f32 v[216:217], v[108:109], v[144:145]
	v_mov_b32_dpp v213, v171 row_ror:15 row_mask:0xf bank_mask:0xf
	v_cndmask_b32_e64 v171, v115, v107, s[6:7]
	v_pk_fma_f32 v[158:159], v[126:127], v[212:213], v[158:159]
	s_nop 0
	v_mov_b32_dpp v215, v171 row_ror:15 row_mask:0xf bank_mask:0xf
	v_add_u32_e32 v171, s17, v197
	v_mad_i64_i32 v[152:153], s[28:29], v171, s46, v[184:185]
	v_add_f32_e32 v171, 1.0, v218
	v_mul_f32_e32 v218, 0xbfb8aa3b, v211
	v_exp_f32_e32 v219, v218
	v_rcp_f32_e32 v218, v171
	v_pk_fma_f32 v[154:155], v[138:139], v[214:215], v[154:155]
	v_pk_add_f32 v[158:159], v[130:131], v[158:159]
	v_add_f32_e32 v171, 1.0, v219
	v_rcp_f32_e32 v219, v171
	v_pk_add_f32 v[154:155], v[142:143], v[154:155]
	v_lshl_add_u64 v[152:153], v[152:153], 0, v[186:187]
	v_mul_f32_e32 v171, 0xbfb8aa3b, v154
	v_pk_mul_f32 v[208:209], v[210:211], v[218:219]
	v_exp_f32_e32 v171, v171
	v_pk_mul_f32 v[156:157], v[156:157], v[208:209]
	v_mul_f32_e32 v208, 0xbfb8aa3b, v155
	v_exp_f32_e32 v209, v208
	v_cvt_pk_bf16_f32 v156, v156, v157
	v_add_f32_e32 v157, 1.0, v171
	v_rcp_f32_e32 v208, v157
	v_add_f32_e32 v157, 1.0, v209
	v_rcp_f32_e32 v209, v157
	v_pk_mul_f32 v[210:211], v[104:105], v[148:149]
	v_cndmask_b32_e64 v171, v111, v103, s[6:7]
	v_pk_mul_f32 v[214:215], v[110:111], v[146:147]
	v_pk_mul_f32 v[154:155], v[154:155], v[208:209]
	s_nop 0
	v_pk_mul_f32 v[154:155], v[158:159], v[154:155]
	v_cndmask_b32_e64 v158, v105, v97, s[6:7]
	v_cvt_pk_bf16_f32 v157, v154, v155
	v_cndmask_b32_e64 v154, v108, v116, s[4:5]
	v_cndmask_b32_e64 v155, v108, v100, s[6:7]
	s_cmp_eq_u32 s98, 2
	s_cbranch_scc1 .Lp9h_st1
	global_store_dwordx2 v[152:153], v[156:157], off
; __device__ __forceinline__ void st_bf4(bf16_t* p, f32x4 v) { u32x2 w; w.x = pk2(v[0], v[1]); w.y = pk2(v[2], v[3]); *(u32x2*)p = w; }
; __device__ __forceinline__ float sigmoidf_(float x) { return __builtin_amdgcn_rcpf(1.f + __expf(-x)); }
; __device__ __forceinline__ float dpp_ror1(float v) { return __int_as_float(__builtin_amdgcn_update_dpp(0, __float_as_int(v), 0x121, 0xf, 0xf, false)); }
; __device__ __forceinline__ float dpp_rol1(float v) { return __int_as_float(__builtin_amdgcn_update_dpp(0, __float_as_int(v), 0x12F, 0xf, 0xf, false)); }
;     __device__ __forceinline__ void tile(const f32x4 (&acc)[2][2][4][2], const Unit& u, int wr, int wc, int fr, int fq) const {
;     ...
;             const int cv = 128 * u.pn + 32 * wc + 16 * n + 4 * fq, cg = FF + cv;
;             const f32x4 wv0 = *(const f32x4*)(cw + cv), wv1 = *(const f32x4*)(cw + F2 + cv), wv2 = *(const f32x4*)(cw + 2 * F2 + cv), bv = *(const f32x4*)(cb + cv);
;             const f32x4 wg0 = *(const f32x4*)(cw + cg), wg1 = *(const f32x4*)(cw + F2 + cg), wg2 = *(const f32x4*)(cw + 2 * F2 + cg), bg = *(const f32x4*)(cb + cg);
; #pragma unroll
;             for (int ai = 0; ai < 2; ++ai)
; #pragma unroll
;                 for (int m = 0; m < 4; ++m) {
;                     f32x4 r;
; #pragma unroll
;                     for (int i = 0; i < 4; ++i) {
;                         const float xv = acc[ai][0][m][n][i], xg = acc[ai][1][m][n][i];
;                         const float uv = m > 0 ? acc[ai][0][m > 0 ? m - 1 : 0][n][i] : 0.f, ug = m > 0 ? acc[ai][1][m > 0 ? m - 1 : 0][n][i] : 0.f;
;                         const float dv = m < 3 ? acc[ai][0][m < 3 ? m + 1 : 3][n][i] : 0.f, dg = m < 3 ? acc[ai][1][m < 3 ? m + 1 : 3][n][i] : 0.f;
;                         const float pv = dpp_ror1(fr == 15 ? uv : xv), pg = dpp_ror1(fr == 15 ? ug : xg);
;                         const float nv = dpp_rol1(fr == 0 ? dv : xv), ng = dpp_rol1(fr == 0 ? dg : xg);
;                         const float yv = wv0[i] * pv + wv1[i] * xv + wv2[i] * nv + bv[i];
;                         const float yg = wg0[i] * pg + wg1[i] * xg + wg2[i] * ng + bg[i];
;                         r[i] = yg * sigmoidf_(yg) * yv;
;                     }
;                     st_bf4(ACT + (size_t)(u.pm * BM + ai * HALF + wr * 64 + m * 16 + fr) * FF + cv, r);
.Lp9h_st1:
	v_mov_b32_dpp v116, v154 row_ror:1 row_mask:0xf bank_mask:0xf
	v_cndmask_b32_e64 v154, v104, v112, s[4:5]
	v_cndmask_b32_e64 v157, v109, v101, s[6:7]
	s_nop 0
	v_mov_b32_dpp v112, v154 row_ror:1 row_mask:0xf bank_mask:0xf
	v_cndmask_b32_e64 v159, v110, v102, s[6:7]
	v_mov_b32_dpp v154, v155 row_ror:15 row_mask:0xf bank_mask:0xf
	v_cndmask_b32_e64 v155, v104, v96, s[6:7]
	s_nop 1
	v_mov_b32_dpp v156, v155 row_ror:15 row_mask:0xf bank_mask:0xf
	v_cndmask_b32_e64 v155, v109, v117, s[4:5]
	s_nop 1
	v_mov_b32_dpp v117, v155 row_ror:1 row_mask:0xf bank_mask:0xf
	v_cndmask_b32_e64 v155, v105, v113, s[4:5]
	v_pk_fma_f32 v[116:117], v[120:121], v[116:117], v[216:217]
	s_nop 0
	v_mov_b32_dpp v113, v155 row_ror:1 row_mask:0xf bank_mask:0xf
	v_pk_fma_f32 v[112:113], v[132:133], v[112:113], v[210:211]
	v_pk_mul_f32 v[210:211], v[106:107], v[150:151]
	v_mov_b32_dpp v155, v157 row_ror:15 row_mask:0xf bank_mask:0xf
	v_pk_fma_f32 v[116:117], v[124:125], v[154:155], v[116:117]
	s_nop 0
	v_mov_b32_dpp v157, v158 row_ror:15 row_mask:0xf bank_mask:0xf
	v_cndmask_b32_e64 v158, v110, v118, s[4:5]
	v_pk_fma_f32 v[112:113], v[136:137], v[156:157], v[112:113]
	v_pk_add_f32 v[116:117], v[128:129], v[116:117]
	v_mov_b32_dpp v118, v158 row_ror:1 row_mask:0xf bank_mask:0xf
	v_cndmask_b32_e64 v158, v106, v114, s[4:5]
	v_pk_add_f32 v[156:157], v[140:141], v[112:113]
	s_nop 0
	v_mov_b32_dpp v114, v158 row_ror:1 row_mask:0xf bank_mask:0xf
	v_mul_f32_e32 v112, 0xbfb8aa3b, v156
	v_exp_f32_e32 v212, v112
	v_mov_b32_dpp v158, v159 row_ror:15 row_mask:0xf bank_mask:0xf
	v_cndmask_b32_e64 v159, v106, v98, s[6:7]
	s_nop 1
	v_mov_b32_dpp v208, v159 row_ror:15 row_mask:0xf bank_mask:0xf
	v_cndmask_b32_e64 v159, v111, v119, s[4:5]
	s_nop 1
	v_mov_b32_dpp v119, v159 row_ror:1 row_mask:0xf bank_mask:0xf
	v_cndmask_b32_e64 v159, v107, v115, s[4:5]
	v_pk_fma_f32 v[118:119], v[122:123], v[118:119], v[214:215]
	s_nop 0
	v_mov_b32_dpp v115, v159 row_ror:1 row_mask:0xf bank_mask:0xf
	v_pk_fma_f32 v[114:115], v[134:135], v[114:115], v[210:211]
	s_nop 0
	v_mov_b32_dpp v159, v171 row_ror:15 row_mask:0xf bank_mask:0xf
	v_cndmask_b32_e64 v171, v107, v99, s[6:7]
	v_pk_fma_f32 v[118:119], v[126:127], v[158:159], v[118:119]
	s_nop 0
	v_mov_b32_dpp v209, v171 row_ror:15 row_mask:0xf bank_mask:0xf
	v_add_u32_e32 v171, s17, v198
	v_mad_i64_i32 v[112:113], s[28:29], v171, s46, v[184:185]
	v_add_f32_e32 v171, 1.0, v212
	v_mul_f32_e32 v212, 0xbfb8aa3b, v157
	v_exp_f32_e32 v213, v212
	v_rcp_f32_e32 v212, v171
	v_pk_fma_f32 v[114:115], v[138:139], v[208:209], v[114:115]
	v_pk_add_f32 v[118:119], v[130:131], v[118:119]
	v_add_f32_e32 v171, 1.0, v213
	v_rcp_f32_e32 v213, v171
	v_pk_add_f32 v[114:115], v[142:143], v[114:115]
	v_lshl_add_u64 v[112:113], v[112:113], 0, v[186:187]
	v_pk_mul_f32 v[154:155], v[156:157], v[212:213]
	s_nop 0
	v_pk_mul_f32 v[116:117], v[116:117], v[154:155]
	v_mul_f32_e32 v154, 0xbfb8aa3b, v114
	v_exp_f32_e32 v154, v154
	v_mul_f32_e32 v155, 0xbfb8aa3b, v115
	v_exp_f32_e32 v155, v155
	v_cvt_pk_bf16_f32 v116, v116, v117
	v_add_f32_e32 v117, 1.0, v154
	v_rcp_f32_e32 v154, v117
	v_add_f32_e32 v117, 1.0, v155
	v_rcp_f32_e32 v155, v117
	v_cndmask_b32_e64 v156, v99, 0, s[6:7]
	v_pk_mul_f32 v[114:115], v[114:115], v[154:155]
	s_nop 0
	v_pk_mul_f32 v[114:115], v[118:119], v[114:115]
	v_cndmask_b32_e64 v118, v97, 0, s[6:7]
	v_cvt_pk_bf16_f32 v117, v114, v115
	v_cndmask_b32_e64 v114, v100, v108, s[4:5]
	v_cndmask_b32_e64 v115, v100, 0, s[6:7]
	s_cmp_eq_u32 s98, 2
	s_cbranch_scc1 .Lp9h_st2
	global_store_dwordx2 v[112:113], v[116:117], off
.Lp9h_st2:
	v_mov_b32_dpp v108, v114 row_ror:1 row_mask:0xf bank_mask:0xf
	v_cndmask_b32_e64 v114, v96, v104, s[4:5]
	v_cndmask_b32_e64 v117, v101, 0, s[6:7]
	s_nop 0
	v_mov_b32_dpp v104, v114 row_ror:1 row_mask:0xf bank_mask:0xf
	v_cndmask_b32_e64 v119, v102, 0, s[6:7]
	v_mov_b32_dpp v114, v115 row_ror:15 row_mask:0xf bank_mask:0xf
	v_cndmask_b32_e64 v115, v96, 0, s[6:7]
	v_cndmask_b32_e64 v155, v103, 0, s[6:7]
	s_nop 0
	v_mov_b32_dpp v116, v115 row_ror:15 row_mask:0xf bank_mask:0xf
	v_cndmask_b32_e64 v115, v101, v109, s[4:5]
	v_pk_mul_f32 v[100:101], v[100:101], v[144:145]
	s_nop 0
	v_mov_b32_dpp v109, v115 row_ror:1 row_mask:0xf bank_mask:0xf
	v_cndmask_b32_e64 v115, v97, v105, s[4:5]
	v_pk_mul_f32 v[96:97], v[96:97], v[148:149]
	v_pk_fma_f32 v[100:101], v[120:121], v[108:109], v[100:101]
	v_mov_b32_dpp v105, v115 row_ror:1 row_mask:0xf bank_mask:0xf
	v_pk_fma_f32 v[96:97], v[132:133], v[104:105], v[96:97]
	v_mov_b32_dpp v115, v117 row_ror:15 row_mask:0xf bank_mask:0xf
	v_pk_fma_f32 v[100:101], v[124:125], v[114:115], v[100:101]
	v_mov_b32_dpp v117, v118 row_ror:15 row_mask:0xf bank_mask:0xf
	v_pk_fma_f32 v[96:97], v[136:137], v[116:117], v[96:97]
	v_cndmask_b32_e64 v118, v102, v110, s[4:5]
	v_pk_add_f32 v[104:105], v[140:141], v[96:97]
	s_nop 0
	v_mul_f32_e32 v96, 0xbfb8aa3b, v104
	v_mul_f32_e32 v117, 0xbfb8aa3b, v105
	v_mov_b32_dpp v110, v118 row_ror:1 row_mask:0xf bank_mask:0xf
	v_cndmask_b32_e64 v118, v98, v106, s[4:5]
	v_exp_f32_e32 v116, v96
	v_exp_f32_e32 v117, v117
	v_mov_b32_dpp v106, v118 row_ror:1 row_mask:0xf bank_mask:0xf
	v_add_f32_e32 v116, 1.0, v116
	v_add_f32_e32 v117, 1.0, v117
	v_mov_b32_dpp v118, v119 row_ror:15 row_mask:0xf bank_mask:0xf
	v_cndmask_b32_e64 v119, v98, 0, s[6:7]
	v_rcp_f32_e32 v116, v116
	v_rcp_f32_e32 v117, v117
	v_mov_b32_dpp v154, v119 row_ror:15 row_mask:0xf bank_mask:0xf
	v_cndmask_b32_e64 v119, v103, v111, s[4:5]
	v_pk_add_f32 v[100:101], v[128:129], v[100:101]
	v_pk_mul_f32 v[104:105], v[104:105], v[116:117]
	v_mov_b32_dpp v111, v119 row_ror:1 row_mask:0xf bank_mask:0xf
	v_cndmask_b32_e64 v119, v99, v107, s[4:5]
	v_pk_mul_f32 v[98:99], v[98:99], v[150:151]
	v_pk_mul_f32 v[100:101], v[100:101], v[104:105]
	v_mov_b32_dpp v107, v119 row_ror:1 row_mask:0xf bank_mask:0xf
	v_pk_fma_f32 v[98:99], v[134:135], v[106:107], v[98:99]
	v_cvt_pk_bf16_f32 v100, v100, v101
	v_mov_b32_dpp v119, v155 row_ror:15 row_mask:0xf bank_mask:0xf
	v_pk_mul_f32 v[102:103], v[102:103], v[146:147]
	v_cndmask_b32_e64 v106, v89, v81, s[6:7]
	v_mov_b32_dpp v155, v156 row_ror:15 row_mask:0xf bank_mask:0xf
	v_pk_fma_f32 v[98:99], v[138:139], v[154:155], v[98:99]
	v_pk_fma_f32 v[102:103], v[122:123], v[110:111], v[102:103]
	v_pk_add_f32 v[98:99], v[142:143], v[98:99]
	v_pk_fma_f32 v[102:103], v[126:127], v[118:119], v[102:103]
	v_mul_f32_e32 v104, 0xbfb8aa3b, v98
	v_exp_f32_e32 v104, v104
	v_mul_f32_e32 v105, 0xbfb8aa3b, v99
	v_exp_f32_e32 v105, v105
	v_add_u32_e32 v156, s17, v199
	v_add_f32_e32 v101, 1.0, v104
	v_rcp_f32_e32 v104, v101
	v_add_f32_e32 v101, 1.0, v105
	v_rcp_f32_e32 v105, v101
	v_pk_add_f32 v[102:103], v[130:131], v[102:103]
	v_mad_i64_i32 v[96:97], s[28:29], v156, s46, v[184:185]
	v_pk_mul_f32 v[98:99], v[98:99], v[104:105]
	v_lshl_add_u64 v[96:97], v[96:97], 0, v[186:187]
	v_pk_mul_f32 v[98:99], v[102:103], v[98:99]
	s_nop 0
	v_cvt_pk_bf16_f32 v101, v98, v99
	s_cmp_eq_u32 s98, 2
	s_cbranch_scc1 .Lp9h_st3
	global_store_dwordx2 v[96:97], v[100:101], off
; __device__ __forceinline__ void st_bf4(bf16_t* p, f32x4 v) { u32x2 w; w.x = pk2(v[0], v[1]); w.y = pk2(v[2], v[3]); *(u32x2*)p = w; }
; __device__ __forceinline__ float sigmoidf_(float x) { return __builtin_amdgcn_rcpf(1.f + __expf(-x)); }
; __device__ __forceinline__ float dpp_ror1(float v) { return __int_as_float(__builtin_amdgcn_update_dpp(0, __float_as_int(v), 0x121, 0xf, 0xf, false)); }
; __device__ __forceinline__ float dpp_rol1(float v) { return __int_as_float(__builtin_amdgcn_update_dpp(0, __float_as_int(v), 0x12F, 0xf, 0xf, false)); }
;     __device__ __forceinline__ void tile(const f32x4 (&acc)[2][2][4][2], const Unit& u, int wr, int wc, int fr, int fq) const {
;     ...
;             const int cv = 128 * u.pn + 32 * wc + 16 * n + 4 * fq, cg = FF + cv;
;             const f32x4 wv0 = *(const f32x4*)(cw + cv), wv1 = *(const f32x4*)(cw + F2 + cv), wv2 = *(const f32x4*)(cw + 2 * F2 + cv), bv = *(const f32x4*)(cb + cv);
;             const f32x4 wg0 = *(const f32x4*)(cw + cg), wg1 = *(const f32x4*)(cw + F2 + cg), wg2 = *(const f32x4*)(cw + 2 * F2 + cg), bg = *(const f32x4*)(cb + cg);
; #pragma unroll
;             for (int ai = 0; ai < 2; ++ai)
; #pragma unroll
;                 for (int m = 0; m < 4; ++m) {
;                     f32x4 r;
; #pragma unroll
;                     for (int i = 0; i < 4; ++i) {
;                         const float xv = acc[ai][0][m][n][i], xg = acc[ai][1][m][n][i];
;                         const float uv = m > 0 ? acc[ai][0][m > 0 ? m - 1 : 0][n][i] : 0.f, ug = m > 0 ? acc[ai][1][m > 0 ? m - 1 : 0][n][i] : 0.f;
;                         const float dv = m < 3 ? acc[ai][0][m < 3 ? m + 1 : 3][n][i] : 0.f, dg = m < 3 ? acc[ai][1][m < 3 ? m + 1 : 3][n][i] : 0.f;
;                         const float pv = dpp_ror1(fr == 15 ? uv : xv), pg = dpp_ror1(fr == 15 ? ug : xg);
;                         const float nv = dpp_rol1(fr == 0 ? dv : xv), ng = dpp_rol1(fr == 0 ? dg : xg);
;                         const float yv = wv0[i] * pv + wv1[i] * xv + wv2[i] * nv + bv[i];
;                         const float yg = wg0[i] * pg + wg1[i] * xg + wg2[i] * ng + bg[i];
;                         r[i] = yg * sigmoidf_(yg) * yv;
;                     }
;                     st_bf4(ACT + (size_t)(u.pm * BM + ai * HALF + wr * 64 + m * 16 + fr) * FF + cv, r);
.Lp9h_st3:
	v_cndmask_b32_e64 v98, v92, 0, s[4:5]
	v_cndmask_b32_e64 v99, v88, 0, s[4:5]
	s_nop 0
	v_mov_b32_dpp v100, v98 row_ror:1 row_mask:0xf bank_mask:0xf
	v_cndmask_b32_e64 v103, v89, 0, s[4:5]
	v_mov_b32_dpp v98, v99 row_ror:1 row_mask:0xf bank_mask:0xf
	v_cndmask_b32_e64 v99, v92, v84, s[6:7]
	v_cndmask_b32_e64 v105, v93, v85, s[6:7]
	v_cndmask_b32_e64 v107, v94, 0, s[4:5]
	v_mov_b32_dpp v102, v99 row_ror:15 row_mask:0xf bank_mask:0xf
	v_cndmask_b32_e64 v99, v88, v80, s[6:7]
	v_cndmask_b32_e64 v109, v95, 0, s[4:5]
	s_nop 0
	v_mov_b32_dpp v104, v99 row_ror:15 row_mask:0xf bank_mask:0xf
	v_cndmask_b32_e64 v99, v93, 0, s[4:5]
	v_cndmask_b32_e64 v111, v91, 0, s[4:5]
	v_cndmask_b32_e64 v115, v95, v87, s[6:7]
	v_mov_b32_dpp v101, v99 row_ror:1 row_mask:0xf bank_mask:0xf
	v_cndmask_b32_e64 v116, v91, v83, s[6:7]
	v_add_u32_e32 v118, s17, v200
	v_mov_b32_dpp v99, v103 row_ror:1 row_mask:0xf bank_mask:0xf
	v_pk_mul_f32 v[156:157], v[92:93], v[144:145]
	v_pk_mul_f32 v[154:155], v[94:95], v[146:147]
	v_mov_b32_dpp v103, v105 row_ror:15 row_mask:0xf bank_mask:0xf
	v_pk_fma_f32 v[100:101], v[120:121], v[100:101], v[156:157]
	s_nop 0
	v_mov_b32_dpp v105, v106 row_ror:15 row_mask:0xf bank_mask:0xf
	v_pk_fma_f32 v[100:101], v[124:125], v[102:103], v[100:101]
	s_nop 0
	v_mov_b32_dpp v106, v107 row_ror:1 row_mask:0xf bank_mask:0xf
	v_cndmask_b32_e64 v107, v90, 0, s[4:5]
	v_pk_add_f32 v[100:101], v[128:129], v[100:101]
	s_nop 0
	v_mov_b32_dpp v108, v107 row_ror:1 row_mask:0xf bank_mask:0xf
	v_cndmask_b32_e64 v107, v94, v86, s[6:7]
	s_nop 1
	v_mov_b32_dpp v110, v107 row_ror:15 row_mask:0xf bank_mask:0xf
	v_cndmask_b32_e64 v107, v90, v82, s[6:7]
	s_nop 1
	v_mov_b32_dpp v114, v107 row_ror:15 row_mask:0xf bank_mask:0xf
	s_nop 1
	v_mov_b32_dpp v107, v109 row_ror:1 row_mask:0xf bank_mask:0xf
	v_pk_fma_f32 v[106:107], v[122:123], v[106:107], v[154:155]
	s_nop 0
	v_mov_b32_dpp v109, v111 row_ror:1 row_mask:0xf bank_mask:0xf
	s_nop 1
	v_mov_b32_dpp v111, v115 row_ror:15 row_mask:0xf bank_mask:0xf
	v_pk_fma_f32 v[106:107], v[126:127], v[110:111], v[106:107]
	v_add_u32_e32 v110, s17, v201
	v_mov_b32_dpp v115, v116 row_ror:15 row_mask:0xf bank_mask:0xf
	v_pk_mul_f32 v[116:117], v[88:89], v[148:149]
	v_pk_add_f32 v[106:107], v[130:131], v[106:107]
	v_pk_fma_f32 v[98:99], v[132:133], v[98:99], v[116:117]
	v_pk_mul_f32 v[116:117], v[90:91], v[150:151]
	v_pk_fma_f32 v[98:99], v[136:137], v[104:105], v[98:99]
	s_nop 0
	v_pk_add_f32 v[104:105], v[140:141], v[98:99]
	s_nop 0
	v_mul_f32_e32 v98, 0xbfb8aa3b, v104
	v_exp_f32_e32 v119, v98
	v_mad_i64_i32 v[98:99], s[28:29], v118, s46, v[184:185]
	v_lshl_add_u64 v[98:99], v[98:99], 0, v[186:187]
	v_add_f32_e32 v118, 1.0, v119
	v_mul_f32_e32 v119, 0xbfb8aa3b, v105
	v_exp_f32_e32 v119, v119
	v_rcp_f32_e32 v118, v118
	v_add_f32_e32 v119, 1.0, v119
	v_rcp_f32_e32 v119, v119
	s_nop 0
	v_pk_mul_f32 v[102:103], v[104:105], v[118:119]
	s_nop 0
	v_pk_mul_f32 v[100:101], v[100:101], v[102:103]
	v_pk_fma_f32 v[102:103], v[134:135], v[108:109], v[116:117]
	v_cvt_pk_bf16_f32 v100, v100, v101
	v_pk_fma_f32 v[102:103], v[138:139], v[114:115], v[102:103]
	v_cndmask_b32_e64 v108, v83, v75, s[6:7]
	v_pk_add_f32 v[102:103], v[142:143], v[102:103]
	v_pk_mul_f32 v[116:117], v[84:85], v[144:145]
	v_mul_f32_e32 v104, 0xbfb8aa3b, v102
	v_exp_f32_e32 v104, v104
	v_mul_f32_e32 v105, 0xbfb8aa3b, v103
	v_exp_f32_e32 v105, v105
	v_pk_mul_f32 v[114:115], v[86:87], v[146:147]
	v_add_f32_e32 v101, 1.0, v104
	v_rcp_f32_e32 v104, v101
	v_add_f32_e32 v101, 1.0, v105
	v_rcp_f32_e32 v105, v101
	v_cndmask_b32_e64 v119, v63, 0, s[4:5]
	v_pk_mul_f32 v[102:103], v[102:103], v[104:105]
	s_nop 0
	v_pk_mul_f32 v[102:103], v[106:107], v[102:103]
	v_cndmask_b32_e64 v104, v81, v73, s[6:7]
	v_cvt_pk_bf16_f32 v101, v102, v103
	s_cmp_eq_u32 s98, 1
	s_cbranch_scc1 .Lp9h_st8
	global_store_dwordx2 v[98:99], v[100:101], off
.Lp9h_st8:
	v_cndmask_b32_e64 v100, v84, v92, s[4:5]
	v_cndmask_b32_e64 v101, v80, v72, s[6:7]
	s_nop 0
	v_mov_b32_dpp v92, v100 row_ror:1 row_mask:0xf bank_mask:0xf
	v_cndmask_b32_e64 v100, v80, v88, s[4:5]
	v_cndmask_b32_e64 v105, v86, v78, s[6:7]
	s_nop 0
	v_mov_b32_dpp v88, v100 row_ror:1 row_mask:0xf bank_mask:0xf
	v_cndmask_b32_e64 v100, v84, v76, s[6:7]
	v_cndmask_b32_e64 v107, v87, v79, s[6:7]
	s_nop 0
	v_mov_b32_dpp v102, v100 row_ror:15 row_mask:0xf bank_mask:0xf
	s_nop 1
	v_mov_b32_dpp v100, v101 row_ror:15 row_mask:0xf bank_mask:0xf
	v_cndmask_b32_e64 v101, v85, v93, s[4:5]
	s_nop 1
	v_mov_b32_dpp v93, v101 row_ror:1 row_mask:0xf bank_mask:0xf
	v_cndmask_b32_e64 v101, v81, v89, s[4:5]
	v_pk_fma_f32 v[92:93], v[120:121], v[92:93], v[116:117]
	v_cndmask_b32_e64 v116, v57, v49, s[6:7]
	v_mov_b32_dpp v89, v101 row_ror:1 row_mask:0xf bank_mask:0xf
	v_cndmask_b32_e64 v101, v85, v77, s[6:7]
	v_cndmask_b32_e64 v117, v62, 0, s[4:5]
	s_nop 0
	v_mov_b32_dpp v103, v101 row_ror:15 row_mask:0xf bank_mask:0xf
	v_pk_fma_f32 v[92:93], v[124:125], v[102:103], v[92:93]
	v_cndmask_b32_e64 v102, v75, v67, s[6:7]
	v_mov_b32_dpp v101, v104 row_ror:15 row_mask:0xf bank_mask:0xf
	v_cndmask_b32_e64 v104, v86, v94, s[4:5]
	v_pk_add_f32 v[92:93], v[128:129], v[92:93]
	s_nop 0
	v_mov_b32_dpp v94, v104 row_ror:1 row_mask:0xf bank_mask:0xf
	v_cndmask_b32_e64 v104, v82, v90, s[4:5]
	s_nop 1
	v_mov_b32_dpp v90, v104 row_ror:1 row_mask:0xf bank_mask:0xf
	s_nop 1
	v_mov_b32_dpp v104, v105 row_ror:15 row_mask:0xf bank_mask:0xf
	v_cndmask_b32_e64 v105, v82, v74, s[6:7]
	s_nop 1
	v_mov_b32_dpp v106, v105 row_ror:15 row_mask:0xf bank_mask:0xf
	v_cndmask_b32_e64 v105, v87, v95, s[4:5]
	s_nop 1
	v_mov_b32_dpp v95, v105 row_ror:1 row_mask:0xf bank_mask:0xf
	v_cndmask_b32_e64 v105, v83, v91, s[4:5]
; __device__ __forceinline__ void st_bf4(bf16_t* p, f32x4 v) { u32x2 w; w.x = pk2(v[0], v[1]); w.y = pk2(v[2], v[3]); *(u32x2*)p = w; }
; __device__ __forceinline__ float sigmoidf_(float x) { return __builtin_amdgcn_rcpf(1.f + __expf(-x)); }
; __device__ __forceinline__ float dpp_ror1(float v) { return __int_as_float(__builtin_amdgcn_update_dpp(0, __float_as_int(v), 0x121, 0xf, 0xf, false)); }
; __device__ __forceinline__ float dpp_rol1(float v) { return __int_as_float(__builtin_amdgcn_update_dpp(0, __float_as_int(v), 0x12F, 0xf, 0xf, false)); }
;     __device__ __forceinline__ void tile(const f32x4 (&acc)[2][2][4][2], const Unit& u, int wr, int wc, int fr, int fq) const {
;     ...
;             const int cv = 128 * u.pn + 32 * wc + 16 * n + 4 * fq, cg = FF + cv;
;             const f32x4 wv0 = *(const f32x4*)(cw + cv), wv1 = *(const f32x4*)(cw + F2 + cv), wv2 = *(const f32x4*)(cw + 2 * F2 + cv), bv = *(const f32x4*)(cb + cv);
;             const f32x4 wg0 = *(const f32x4*)(cw + cg), wg1 = *(const f32x4*)(cw + F2 + cg), wg2 = *(const f32x4*)(cw + 2 * F2 + cg), bg = *(const f32x4*)(cb + cg);
; #pragma unroll
;             for (int ai = 0; ai < 2; ++ai)
; #pragma unroll
;                 for (int m = 0; m < 4; ++m) {
;                     f32x4 r;
; #pragma unroll
;                     for (int i = 0; i < 4; ++i) {
;                         const float xv = acc[ai][0][m][n][i], xg = acc[ai][1][m][n][i];
;                         const float uv = m > 0 ? acc[ai][0][m > 0 ? m - 1 : 0][n][i] : 0.f, ug = m > 0 ? acc[ai][1][m > 0 ? m - 1 : 0][n][i] : 0.f;
;                         const float dv = m < 3 ? acc[ai][0][m < 3 ? m + 1 : 3][n][i] : 0.f, dg = m < 3 ? acc[ai][1][m < 3 ? m + 1 : 3][n][i] : 0.f;
;                         const float pv = dpp_ror1(fr == 15 ? uv : xv), pg = dpp_ror1(fr == 15 ? ug : xg);
;                         const float nv = dpp_rol1(fr == 0 ? dv : xv), ng = dpp_rol1(fr == 0 ? dg : xg);
;                         const float yv = wv0[i] * pv + wv1[i] * xv + wv2[i] * nv + bv[i];
;                         const float yg = wg0[i] * pg + wg1[i] * xg + wg2[i] * ng + bg[i];
;                         r[i] = yg * sigmoidf_(yg) * yv;
;                     }
;                     st_bf4(ACT + (size_t)(u.pm * BM + ai * HALF + wr * 64 + m * 16 + fr) * FF + cv, r);
	v_pk_fma_f32 v[94:95], v[122:123], v[94:95], v[114:115]
	s_nop 0
	v_mov_b32_dpp v91, v105 row_ror:1 row_mask:0xf bank_mask:0xf
	v_cndmask_b32_e64 v115, v61, v53, s[6:7]
	s_nop 0
	v_mov_b32_dpp v105, v107 row_ror:15 row_mask:0xf bank_mask:0xf
	v_pk_fma_f32 v[94:95], v[126:127], v[104:105], v[94:95]
	v_add_u32_e32 v104, s17, v202
	v_mov_b32_dpp v107, v108 row_ror:15 row_mask:0xf bank_mask:0xf
	v_pk_mul_f32 v[108:109], v[80:81], v[148:149]
	v_pk_add_f32 v[94:95], v[130:131], v[94:95]
	v_pk_fma_f32 v[88:89], v[132:133], v[88:89], v[108:109]
	v_pk_mul_f32 v[108:109], v[82:83], v[150:151]
	v_pk_fma_f32 v[88:89], v[136:137], v[100:101], v[88:89]
	v_pk_fma_f32 v[90:91], v[134:135], v[90:91], v[108:109]
	v_pk_add_f32 v[88:89], v[140:141], v[88:89]
	v_pk_fma_f32 v[90:91], v[138:139], v[106:107], v[90:91]
	v_mul_f32_e32 v100, 0xbfb8aa3b, v88
	v_exp_f32_e32 v111, v100
	v_mad_i64_i32 v[100:101], s[28:29], v110, s46, v[184:185]
	v_pk_add_f32 v[90:91], v[142:143], v[90:91]
	v_add_f32_e32 v110, 1.0, v111
	v_mul_f32_e32 v111, 0xbfb8aa3b, v89
	v_exp_f32_e32 v111, v111
	v_rcp_f32_e32 v110, v110
	v_lshl_add_u64 v[100:101], v[100:101], 0, v[186:187]
	v_pk_mul_f32 v[108:109], v[76:77], v[144:145]
	v_add_f32_e32 v111, 1.0, v111
	v_rcp_f32_e32 v111, v111
	v_pk_mul_f32 v[106:107], v[78:79], v[146:147]
	v_pk_mul_f32 v[88:89], v[88:89], v[110:111]
	s_nop 0
	v_pk_mul_f32 v[88:89], v[92:93], v[88:89]
	v_mul_f32_e32 v92, 0xbfb8aa3b, v90
	v_exp_f32_e32 v92, v92
	v_mul_f32_e32 v93, 0xbfb8aa3b, v91
	v_exp_f32_e32 v93, v93
	v_cvt_pk_bf16_f32 v88, v88, v89
	v_add_f32_e32 v89, 1.0, v92
	v_rcp_f32_e32 v92, v89
	v_add_f32_e32 v89, 1.0, v93
	v_rcp_f32_e32 v93, v89
	v_cndmask_b32_e64 v111, v57, 0, s[4:5]
	v_pk_mul_f32 v[90:91], v[90:91], v[92:93]
	s_nop 0
	v_pk_mul_f32 v[90:91], v[94:95], v[90:91]
	v_cndmask_b32_e64 v92, v73, v65, s[6:7]
	v_cvt_pk_bf16_f32 v89, v90, v91
	s_cmp_eq_u32 s98, 1
	s_cbranch_scc1 .Lp9h_st9
	global_store_dwordx2 v[100:101], v[88:89], off
.Lp9h_st9:
	v_cndmask_b32_e64 v88, v76, v84, s[4:5]
	v_cndmask_b32_e64 v89, v76, v68, s[6:7]
	s_nop 0
	v_mov_b32_dpp v84, v88 row_ror:1 row_mask:0xf bank_mask:0xf
	v_cndmask_b32_e64 v88, v72, v80, s[4:5]
	v_cndmask_b32_e64 v91, v77, v69, s[6:7]
	v_cndmask_b32_e64 v93, v78, v70, s[6:7]
	v_mov_b32_dpp v80, v88 row_ror:1 row_mask:0xf bank_mask:0xf
	v_cndmask_b32_e64 v95, v79, v71, s[6:7]
	v_mov_b32_dpp v88, v89 row_ror:15 row_mask:0xf bank_mask:0xf
	v_cndmask_b32_e64 v89, v72, v64, s[6:7]
	s_nop 1
	v_mov_b32_dpp v90, v89 row_ror:15 row_mask:0xf bank_mask:0xf
	v_cndmask_b32_e64 v89, v77, v85, s[4:5]
	s_nop 1
	v_mov_b32_dpp v85, v89 row_ror:1 row_mask:0xf bank_mask:0xf
	v_cndmask_b32_e64 v89, v73, v81, s[4:5]
	v_pk_fma_f32 v[84:85], v[120:121], v[84:85], v[108:109]
	s_nop 0
	v_mov_b32_dpp v81, v89 row_ror:1 row_mask:0xf bank_mask:0xf
	v_cndmask_b32_e64 v109, v61, 0, s[4:5]
	s_nop 0
	v_mov_b32_dpp v89, v91 row_ror:15 row_mask:0xf bank_mask:0xf
	v_pk_fma_f32 v[84:85], v[124:125], v[88:89], v[84:85]
	v_cndmask_b32_e64 v88, v67, 0, s[6:7]
	v_mov_b32_dpp v91, v92 row_ror:15 row_mask:0xf bank_mask:0xf
	v_cndmask_b32_e64 v92, v78, v86, s[4:5]
	v_pk_add_f32 v[84:85], v[128:129], v[84:85]
	s_nop 0
	v_mov_b32_dpp v86, v92 row_ror:1 row_mask:0xf bank_mask:0xf
	v_cndmask_b32_e64 v92, v74, v82, s[4:5]
	s_nop 1
	v_mov_b32_dpp v82, v92 row_ror:1 row_mask:0xf bank_mask:0xf
	s_nop 1
	v_mov_b32_dpp v92, v93 row_ror:15 row_mask:0xf bank_mask:0xf
	v_cndmask_b32_e64 v93, v74, v66, s[6:7]
	s_nop 1
	v_mov_b32_dpp v94, v93 row_ror:15 row_mask:0xf bank_mask:0xf
	v_cndmask_b32_e64 v93, v79, v87, s[4:5]
	s_nop 1
	v_mov_b32_dpp v87, v93 row_ror:1 row_mask:0xf bank_mask:0xf
	v_cndmask_b32_e64 v93, v75, v83, s[4:5]
	v_pk_fma_f32 v[86:87], v[122:123], v[86:87], v[106:107]
	v_cndmask_b32_e64 v107, v60, 0, s[4:5]
	v_mov_b32_dpp v83, v93 row_ror:1 row_mask:0xf bank_mask:0xf
	s_nop 0
	v_mov_b32_dpp v93, v95 row_ror:15 row_mask:0xf bank_mask:0xf
	v_pk_fma_f32 v[86:87], v[126:127], v[92:93], v[86:87]
	v_mov_b32_dpp v106, v107 row_ror:1 row_mask:0xf bank_mask:0xf
	v_mov_b32_dpp v95, v102 row_ror:15 row_mask:0xf bank_mask:0xf
	v_pk_mul_f32 v[102:103], v[72:73], v[148:149]
	v_pk_add_f32 v[86:87], v[130:131], v[86:87]
	v_pk_fma_f32 v[80:81], v[132:133], v[80:81], v[102:103]
	v_cndmask_b32_e64 v107, v56, 0, s[4:5]
	v_pk_fma_f32 v[80:81], v[136:137], v[90:91], v[80:81]
	s_nop 0
	v_pk_add_f32 v[80:81], v[140:141], v[80:81]
	v_mov_b32_dpp v108, v107 row_ror:1 row_mask:0xf bank_mask:0xf
	v_mul_f32_e32 v90, 0xbfb8aa3b, v80
	v_exp_f32_e32 v105, v90
	v_mad_i64_i32 v[90:91], s[28:29], v104, s46, v[184:185]
	v_lshl_add_u64 v[102:103], v[90:91], 0, v[186:187]
	v_add_f32_e32 v104, 1.0, v105
	v_mul_f32_e32 v105, 0xbfb8aa3b, v81
	v_exp_f32_e32 v105, v105
	v_rcp_f32_e32 v104, v104
	v_pk_mul_f32 v[90:91], v[74:75], v[150:151]
	v_cndmask_b32_e64 v107, v60, v52, s[6:7]
	v_add_f32_e32 v105, 1.0, v105
	v_rcp_f32_e32 v105, v105
	v_pk_fma_f32 v[82:83], v[134:135], v[82:83], v[90:91]
	v_mov_b32_dpp v110, v107 row_ror:15 row_mask:0xf bank_mask:0xf
	v_pk_fma_f32 v[82:83], v[138:139], v[94:95], v[82:83]
	v_pk_mul_f32 v[80:81], v[80:81], v[104:105]
	v_pk_add_f32 v[82:83], v[142:143], v[82:83]
	v_pk_mul_f32 v[80:81], v[84:85], v[80:81]
	v_mul_f32_e32 v84, 0xbfb8aa3b, v82
	v_exp_f32_e32 v84, v84
	v_mul_f32_e32 v85, 0xbfb8aa3b, v83
	v_exp_f32_e32 v85, v85
	v_cvt_pk_bf16_f32 v80, v80, v81
	v_add_f32_e32 v81, 1.0, v84
	v_rcp_f32_e32 v84, v81
	v_add_f32_e32 v81, 1.0, v85
	v_rcp_f32_e32 v85, v81
	v_cndmask_b32_e64 v107, v56, v48, s[6:7]
	v_pk_mul_f32 v[82:83], v[82:83], v[84:85]
	s_nop 0
	v_pk_mul_f32 v[82:83], v[86:87], v[82:83]
	v_cndmask_b32_e64 v84, v65, 0, s[6:7]
	v_cvt_pk_bf16_f32 v81, v82, v83
	s_cmp_eq_u32 s98, 1
	s_cbranch_scc1 .Lp9h_st10
	global_store_dwordx2 v[102:103], v[80:81], off
; __device__ __forceinline__ void st_bf4(bf16_t* p, f32x4 v) { u32x2 w; w.x = pk2(v[0], v[1]); w.y = pk2(v[2], v[3]); *(u32x2*)p = w; }
; __device__ __forceinline__ float sigmoidf_(float x) { return __builtin_amdgcn_rcpf(1.f + __expf(-x)); }
; __device__ __forceinline__ float dpp_ror1(float v) { return __int_as_float(__builtin_amdgcn_update_dpp(0, __float_as_int(v), 0x121, 0xf, 0xf, false)); }
; __device__ __forceinline__ float dpp_rol1(float v) { return __int_as_float(__builtin_amdgcn_update_dpp(0, __float_as_int(v), 0x12F, 0xf, 0xf, false)); }
;     __device__ __forceinline__ void tile(const f32x4 (&acc)[2][2][4][2], const Unit& u, int wr, int wc, int fr, int fq) const {
;     ...
;             const int cv = 128 * u.pn + 32 * wc + 16 * n + 4 * fq, cg = FF + cv;
;             const f32x4 wv0 = *(const f32x4*)(cw + cv), wv1 = *(const f32x4*)(cw + F2 + cv), wv2 = *(const f32x4*)(cw + 2 * F2 + cv), bv = *(const f32x4*)(cb + cv);
;             const f32x4 wg0 = *(const f32x4*)(cw + cg), wg1 = *(const f32x4*)(cw + F2 + cg), wg2 = *(const f32x4*)(cw + 2 * F2 + cg), bg = *(const f32x4*)(cb + cg);
; #pragma unroll
;             for (int ai = 0; ai < 2; ++ai)
; #pragma unroll
;                 for (int m = 0; m < 4; ++m) {
;                     f32x4 r;
; #pragma unroll
;                     for (int i = 0; i < 4; ++i) {
;                         const float xv = acc[ai][0][m][n][i], xg = acc[ai][1][m][n][i];
;                         const float uv = m > 0 ? acc[ai][0][m > 0 ? m - 1 : 0][n][i] : 0.f, ug = m > 0 ? acc[ai][1][m > 0 ? m - 1 : 0][n][i] : 0.f;
;                         const float dv = m < 3 ? acc[ai][0][m < 3 ? m + 1 : 3][n][i] : 0.f, dg = m < 3 ? acc[ai][1][m < 3 ? m + 1 : 3][n][i] : 0.f;
;                         const float pv = dpp_ror1(fr == 15 ? uv : xv), pg = dpp_ror1(fr == 15 ? ug : xg);
;                         const float nv = dpp_rol1(fr == 0 ? dv : xv), ng = dpp_rol1(fr == 0 ? dg : xg);
;                         const float yv = wv0[i] * pv + wv1[i] * xv + wv2[i] * nv + bv[i];
;                         const float yg = wg0[i] * pg + wg1[i] * xg + wg2[i] * ng + bg[i];
;                         r[i] = yg * sigmoidf_(yg) * yv;
;                     }
;                     st_bf4(ACT + (size_t)(u.pm * BM + ai * HALF + wr * 64 + m * 16 + fr) * FF + cv, r);
.Lp9h_st10:
	v_cndmask_b32_e64 v80, v68, v76, s[4:5]
	v_cndmask_b32_e64 v81, v68, 0, s[6:7]
	s_nop 0
	v_mov_b32_dpp v76, v80 row_ror:1 row_mask:0xf bank_mask:0xf
	v_cndmask_b32_e64 v80, v64, v72, s[4:5]
	v_cndmask_b32_e64 v83, v69, 0, s[6:7]
	v_cndmask_b32_e64 v85, v70, 0, s[6:7]
	v_mov_b32_dpp v72, v80 row_ror:1 row_mask:0xf bank_mask:0xf
	v_cndmask_b32_e64 v87, v71, 0, s[6:7]
	v_mov_b32_dpp v80, v81 row_ror:15 row_mask:0xf bank_mask:0xf
	v_cndmask_b32_e64 v81, v64, 0, s[6:7]
	v_mov_b32_dpp v114, v107 row_ror:15 row_mask:0xf bank_mask:0xf
	s_nop 0
	v_mov_b32_dpp v82, v81 row_ror:15 row_mask:0xf bank_mask:0xf
	v_cndmask_b32_e64 v81, v69, v77, s[4:5]
	v_pk_mul_f32 v[68:69], v[68:69], v[144:145]
	v_mov_b32_dpp v107, v109 row_ror:1 row_mask:0xf bank_mask:0xf
	v_mov_b32_dpp v77, v81 row_ror:1 row_mask:0xf bank_mask:0xf
	v_cndmask_b32_e64 v81, v65, v73, s[4:5]
	v_pk_mul_f32 v[64:65], v[64:65], v[148:149]
	v_pk_fma_f32 v[68:69], v[120:121], v[76:77], v[68:69]
	v_mov_b32_dpp v73, v81 row_ror:1 row_mask:0xf bank_mask:0xf
	v_pk_fma_f32 v[64:65], v[132:133], v[72:73], v[64:65]
	v_mov_b32_dpp v81, v83 row_ror:15 row_mask:0xf bank_mask:0xf
	v_pk_fma_f32 v[68:69], v[124:125], v[80:81], v[68:69]
	v_mov_b32_dpp v109, v111 row_ror:1 row_mask:0xf bank_mask:0xf
	v_mov_b32_dpp v83, v84 row_ror:15 row_mask:0xf bank_mask:0xf
	v_cndmask_b32_e64 v84, v70, v78, s[4:5]
	v_pk_fma_f32 v[64:65], v[136:137], v[82:83], v[64:65]
	v_pk_add_f32 v[68:69], v[128:129], v[68:69]
	v_mov_b32_dpp v78, v84 row_ror:1 row_mask:0xf bank_mask:0xf
	v_cndmask_b32_e64 v84, v66, v74, s[4:5]
	v_pk_add_f32 v[64:65], v[140:141], v[64:65]
	s_nop 0
	v_mov_b32_dpp v74, v84 row_ror:1 row_mask:0xf bank_mask:0xf
	v_mul_f32_e32 v72, 0xbfb8aa3b, v64
	v_exp_f32_e32 v82, v72
	v_mov_b32_dpp v84, v85 row_ror:15 row_mask:0xf bank_mask:0xf
	v_cndmask_b32_e64 v85, v66, 0, s[6:7]
	v_mov_b32_dpp v111, v115 row_ror:15 row_mask:0xf bank_mask:0xf
	s_nop 0
	v_mov_b32_dpp v86, v85 row_ror:15 row_mask:0xf bank_mask:0xf
	v_cndmask_b32_e64 v85, v71, v79, s[4:5]
	v_pk_mul_f32 v[70:71], v[70:71], v[146:147]
	v_mov_b32_dpp v115, v116 row_ror:15 row_mask:0xf bank_mask:0xf
	v_mov_b32_dpp v79, v85 row_ror:1 row_mask:0xf bank_mask:0xf
	v_cndmask_b32_e64 v85, v67, v75, s[4:5]
	v_pk_mul_f32 v[66:67], v[66:67], v[150:151]
	v_pk_fma_f32 v[70:71], v[122:123], v[78:79], v[70:71]
	v_mov_b32_dpp v75, v85 row_ror:1 row_mask:0xf bank_mask:0xf
	v_pk_fma_f32 v[66:67], v[134:135], v[74:75], v[66:67]
	v_mov_b32_dpp v85, v87 row_ror:15 row_mask:0xf bank_mask:0xf
	v_pk_fma_f32 v[70:71], v[126:127], v[84:85], v[70:71]
	v_mov_b32_dpp v116, v117 row_ror:1 row_mask:0xf bank_mask:0xf
	v_mov_b32_dpp v87, v88 row_ror:15 row_mask:0xf bank_mask:0xf
	v_add_u32_e32 v88, s17, v203
	v_mad_i64_i32 v[72:73], s[28:29], v88, s46, v[184:185]
	v_lshl_add_u64 v[104:105], v[72:73], 0, v[186:187]
	v_mul_f32_e32 v73, 0xbfb8aa3b, v65
	v_exp_f32_e32 v73, v73
	v_add_f32_e32 v72, 1.0, v82
	v_rcp_f32_e32 v72, v72
	v_pk_fma_f32 v[66:67], v[138:139], v[86:87], v[66:67]
	v_add_f32_e32 v73, 1.0, v73
	v_rcp_f32_e32 v73, v73
	v_pk_add_f32 v[66:67], v[142:143], v[66:67]
	v_pk_add_f32 v[70:71], v[130:131], v[70:71]
	v_cndmask_b32_e64 v117, v58, 0, s[4:5]
	v_pk_mul_f32 v[64:65], v[64:65], v[72:73]
	s_nop 0
	v_pk_mul_f32 v[64:65], v[68:69], v[64:65]
	v_mul_f32_e32 v68, 0xbfb8aa3b, v66
	v_exp_f32_e32 v68, v68
	v_mul_f32_e32 v69, 0xbfb8aa3b, v67
	v_exp_f32_e32 v69, v69
	v_cvt_pk_bf16_f32 v64, v64, v65
	v_add_f32_e32 v65, 1.0, v68
	v_rcp_f32_e32 v68, v65
	v_add_f32_e32 v65, 1.0, v69
	v_rcp_f32_e32 v69, v65
	v_mov_b32_dpp v118, v117 row_ror:1 row_mask:0xf bank_mask:0xf
	v_cndmask_b32_e64 v117, v62, v54, s[6:7]
	v_pk_mul_f32 v[66:67], v[66:67], v[68:69]
	s_nop 0
	v_mov_b32_dpp v120, v117 row_ror:15 row_mask:0xf bank_mask:0xf
	v_pk_mul_f32 v[66:67], v[70:71], v[66:67]
	v_cndmask_b32_e64 v117, v58, v50, s[6:7]
	v_cvt_pk_bf16_f32 v65, v66, v67
	s_cmp_eq_u32 s98, 1
	s_cbranch_scc1 .Lp9h_st11
	global_store_dwordx2 v[104:105], v[64:65], off
.Lp9h_st11:
	global_load_dwordx4 v[92:95], v[178:179], off offset:2112
	global_load_dwordx4 v[76:79], v[176:177], off offset:2112
	global_load_dwordx4 v[80:83], v[180:181], off offset:2112
	global_load_dwordx4 v[84:87], v[182:183], off offset:2112
	v_or_b32_e32 v64, 16, v170
	v_ashrrev_i32_e32 v65, 31, v64
	v_lshlrev_b64 v[68:69], 2, v[64:65]
	v_lshl_add_u64 v[64:65], s[12:13], 0, v[68:69]
	global_load_dwordx4 v[88:91], v[64:65], off
	s_nop 0
	global_load_dwordx4 v[64:67], v[172:173], off offset:64
	v_lshl_add_u64 v[68:69], s[14:15], 0, v[68:69]
	global_load_dwordx4 v[68:71], v[68:69], off
	s_nop 0
	global_load_dwordx4 v[72:75], v[174:175], off offset:64
	v_mov_b32_dpp v122, v117 row_ror:15 row_mask:0xf bank_mask:0xf
	v_cndmask_b32_e64 v121, v59, 0, s[4:5]
	v_cndmask_b32_e64 v123, v63, v55, s[6:7]
	v_mov_b32_dpp v117, v119 row_ror:1 row_mask:0xf bank_mask:0xf
	v_cndmask_b32_e64 v126, v59, v51, s[6:7]
	s_waitcnt vmcnt(7)
	v_pk_mul_f32 v[124:125], v[56:57], v[92:93]
	s_waitcnt vmcnt(6)
	v_pk_fma_f32 v[108:109], v[76:77], v[108:109], v[124:125]
	v_mov_b32_dpp v119, v121 row_ror:1 row_mask:0xf bank_mask:0xf
	s_waitcnt vmcnt(5)
	v_pk_fma_f32 v[108:109], v[80:81], v[114:115], v[108:109]
	s_waitcnt vmcnt(4)
	v_pk_add_f32 v[108:109], v[84:85], v[108:109]
	s_waitcnt vmcnt(3)
	v_pk_mul_f32 v[128:129], v[60:61], v[88:89]
	v_mul_f32_e32 v114, 0xbfb8aa3b, v108
	v_mul_f32_e32 v125, 0xbfb8aa3b, v109
	v_exp_f32_e32 v124, v114
	v_exp_f32_e32 v125, v125
	s_waitcnt vmcnt(2)
	v_pk_fma_f32 v[106:107], v[64:65], v[106:107], v[128:129]
	v_mov_b32_dpp v121, v123 row_ror:15 row_mask:0xf bank_mask:0xf
	v_add_f32_e32 v124, 1.0, v124
	v_add_f32_e32 v125, 1.0, v125
	v_rcp_f32_e32 v124, v124
	v_rcp_f32_e32 v125, v125
	s_waitcnt vmcnt(1)
	v_pk_fma_f32 v[106:107], v[68:69], v[110:111], v[106:107]
	v_pk_mul_f32 v[114:115], v[58:59], v[94:95]
	s_waitcnt vmcnt(0)
	v_pk_add_f32 v[106:107], v[72:73], v[106:107]
	v_pk_mul_f32 v[108:109], v[108:109], v[124:125]
	v_mov_b32_dpp v123, v126 row_ror:15 row_mask:0xf bank_mask:0xf
	v_pk_mul_f32 v[106:107], v[106:107], v[108:109]
	v_pk_fma_f32 v[108:109], v[78:79], v[118:119], v[114:115]
	v_cvt_pk_bf16_f32 v106, v106, v107
	v_pk_fma_f32 v[108:109], v[82:83], v[122:123], v[108:109]
	v_pk_mul_f32 v[126:127], v[62:63], v[90:91]
	v_pk_add_f32 v[108:109], v[86:87], v[108:109]
	v_pk_fma_f32 v[114:115], v[66:67], v[116:117], v[126:127]
	v_mul_f32_e32 v110, 0xbfb8aa3b, v108
	v_exp_f32_e32 v110, v110
	v_mul_f32_e32 v111, 0xbfb8aa3b, v109
	v_exp_f32_e32 v111, v111
	v_pk_fma_f32 v[114:115], v[70:71], v[120:121], v[114:115]
	v_add_f32_e32 v107, 1.0, v110
	v_rcp_f32_e32 v110, v107
	v_add_f32_e32 v107, 1.0, v111
	v_rcp_f32_e32 v111, v107
	v_pk_add_f32 v[114:115], v[74:75], v[114:115]
	v_pk_mul_f32 v[116:117], v[48:49], v[92:93]
	v_cndmask_b32_e64 v118, v51, v43, s[6:7]
	v_pk_mul_f32 v[108:109], v[108:109], v[110:111]
	v_cndmask_b32_e64 v110, v49, v41, s[6:7]
	v_pk_mul_f32 v[108:109], v[114:115], v[108:109]
	v_cndmask_b32_e64 v111, v54, v46, s[6:7]
	v_cvt_pk_bf16_f32 v107, v108, v109
	s_cmp_eq_u32 s98, 2
	s_cbranch_scc1 .Lp9h_st4
; __device__ __forceinline__ void st_bf4(bf16_t* p, f32x4 v) { u32x2 w; w.x = pk2(v[0], v[1]); w.y = pk2(v[2], v[3]); *(u32x2*)p = w; }
; __device__ __forceinline__ float sigmoidf_(float x) { return __builtin_amdgcn_rcpf(1.f + __expf(-x)); }
; __device__ __forceinline__ float dpp_ror1(float v) { return __int_as_float(__builtin_amdgcn_update_dpp(0, __float_as_int(v), 0x121, 0xf, 0xf, false)); }
; __device__ __forceinline__ float dpp_rol1(float v) { return __int_as_float(__builtin_amdgcn_update_dpp(0, __float_as_int(v), 0x12F, 0xf, 0xf, false)); }
;     __device__ __forceinline__ void tile(const f32x4 (&acc)[2][2][4][2], const Unit& u, int wr, int wc, int fr, int fq) const {
;     ...
;             const int cv = 128 * u.pn + 32 * wc + 16 * n + 4 * fq, cg = FF + cv;
;             const f32x4 wv0 = *(const f32x4*)(cw + cv), wv1 = *(const f32x4*)(cw + F2 + cv), wv2 = *(const f32x4*)(cw + 2 * F2 + cv), bv = *(const f32x4*)(cb + cv);
;             const f32x4 wg0 = *(const f32x4*)(cw + cg), wg1 = *(const f32x4*)(cw + F2 + cg), wg2 = *(const f32x4*)(cw + 2 * F2 + cg), bg = *(const f32x4*)(cb + cg);
; #pragma unroll
;             for (int ai = 0; ai < 2; ++ai)
; #pragma unroll
;                 for (int m = 0; m < 4; ++m) {
;                     f32x4 r;
; #pragma unroll
;                     for (int i = 0; i < 4; ++i) {
;                         const float xv = acc[ai][0][m][n][i], xg = acc[ai][1][m][n][i];
;                         const float uv = m > 0 ? acc[ai][0][m > 0 ? m - 1 : 0][n][i] : 0.f, ug = m > 0 ? acc[ai][1][m > 0 ? m - 1 : 0][n][i] : 0.f;
;                         const float dv = m < 3 ? acc[ai][0][m < 3 ? m + 1 : 3][n][i] : 0.f, dg = m < 3 ? acc[ai][1][m < 3 ? m + 1 : 3][n][i] : 0.f;
;                         const float pv = dpp_ror1(fr == 15 ? uv : xv), pg = dpp_ror1(fr == 15 ? ug : xg);
;                         const float nv = dpp_rol1(fr == 0 ? dv : xv), ng = dpp_rol1(fr == 0 ? dg : xg);
;                         const float yv = wv0[i] * pv + wv1[i] * xv + wv2[i] * nv + bv[i];
;                         const float yg = wg0[i] * pg + wg1[i] * xg + wg2[i] * ng + bg[i];
;                         r[i] = yg * sigmoidf_(yg) * yv;
;                     }
;                     st_bf4(ACT + (size_t)(u.pm * BM + ai * HALF + wr * 64 + m * 16 + fr) * FF + cv, r);
	global_store_dwordx2 v[168:169], v[106:107], off offset:32
.Lp9h_st4:
	v_cndmask_b32_e64 v106, v52, v60, s[4:5]
	v_cndmask_b32_e64 v107, v52, v44, s[6:7]
	s_nop 0
	v_mov_b32_dpp v60, v106 row_ror:1 row_mask:0xf bank_mask:0xf
	v_cndmask_b32_e64 v106, v48, v56, s[4:5]
	v_cndmask_b32_e64 v109, v53, v45, s[6:7]
	s_nop 0
	v_mov_b32_dpp v56, v106 row_ror:1 row_mask:0xf bank_mask:0xf
	v_cndmask_b32_e64 v115, v55, v47, s[6:7]
	v_pk_mul_f32 v[120:121], v[52:53], v[88:89]
	v_mov_b32_dpp v106, v107 row_ror:15 row_mask:0xf bank_mask:0xf
	v_cndmask_b32_e64 v107, v48, v40, s[6:7]
	s_nop 1
	v_mov_b32_dpp v108, v107 row_ror:15 row_mask:0xf bank_mask:0xf
	v_cndmask_b32_e64 v107, v53, v61, s[4:5]
	s_nop 1
	v_mov_b32_dpp v61, v107 row_ror:1 row_mask:0xf bank_mask:0xf
	v_cndmask_b32_e64 v107, v49, v57, s[4:5]
	v_pk_fma_f32 v[60:61], v[64:65], v[60:61], v[120:121]
	s_nop 0
	v_mov_b32_dpp v57, v107 row_ror:1 row_mask:0xf bank_mask:0xf
	v_pk_fma_f32 v[56:57], v[76:77], v[56:57], v[116:117]
	s_nop 0
	v_mov_b32_dpp v107, v109 row_ror:15 row_mask:0xf bank_mask:0xf
	v_pk_fma_f32 v[60:61], v[68:69], v[106:107], v[60:61]
	v_pk_mul_f32 v[106:107], v[40:41], v[92:93]
	v_mov_b32_dpp v109, v110 row_ror:15 row_mask:0xf bank_mask:0xf
	v_pk_fma_f32 v[56:57], v[80:81], v[108:109], v[56:57]
	v_cndmask_b32_e64 v110, v54, v62, s[4:5]
	v_pk_add_f32 v[56:57], v[84:85], v[56:57]
	s_nop 0
	v_mul_f32_e32 v108, 0xbfb8aa3b, v56
	v_mul_f32_e32 v117, 0xbfb8aa3b, v57
	v_mov_b32_dpp v62, v110 row_ror:1 row_mask:0xf bank_mask:0xf
	v_cndmask_b32_e64 v110, v50, v58, s[4:5]
	v_exp_f32_e32 v116, v108
	v_exp_f32_e32 v117, v117
	v_mov_b32_dpp v58, v110 row_ror:1 row_mask:0xf bank_mask:0xf
	v_add_f32_e32 v116, 1.0, v116
	v_add_f32_e32 v117, 1.0, v117
	v_mov_b32_dpp v110, v111 row_ror:15 row_mask:0xf bank_mask:0xf
	v_cndmask_b32_e64 v111, v50, v42, s[6:7]
	v_rcp_f32_e32 v116, v116
	v_rcp_f32_e32 v117, v117
	v_mov_b32_dpp v114, v111 row_ror:15 row_mask:0xf bank_mask:0xf
	v_cndmask_b32_e64 v111, v55, v63, s[4:5]
	v_pk_mul_f32 v[108:109], v[50:51], v[94:95]
	v_pk_add_f32 v[60:61], v[72:73], v[60:61]
	v_mov_b32_dpp v63, v111 row_ror:1 row_mask:0xf bank_mask:0xf
	v_cndmask_b32_e64 v111, v51, v59, s[4:5]
	v_pk_mul_f32 v[56:57], v[56:57], v[116:117]
	s_nop 0
	v_mov_b32_dpp v59, v111 row_ror:1 row_mask:0xf bank_mask:0xf
	v_pk_fma_f32 v[58:59], v[78:79], v[58:59], v[108:109]
	v_pk_mul_f32 v[56:57], v[60:61], v[56:57]
	v_mov_b32_dpp v111, v115 row_ror:15 row_mask:0xf bank_mask:0xf
	v_cvt_pk_bf16_f32 v56, v56, v57
	v_cndmask_b32_e64 v108, v43, v35, s[6:7]
	v_mov_b32_dpp v115, v118 row_ror:15 row_mask:0xf bank_mask:0xf
	v_pk_fma_f32 v[58:59], v[82:83], v[114:115], v[58:59]
	v_pk_mul_f32 v[118:119], v[54:55], v[90:91]
	v_pk_add_f32 v[58:59], v[86:87], v[58:59]
	v_pk_fma_f32 v[62:63], v[66:67], v[62:63], v[118:119]
	v_mul_f32_e32 v60, 0xbfb8aa3b, v58
	v_exp_f32_e32 v60, v60
	v_mul_f32_e32 v61, 0xbfb8aa3b, v59
	v_exp_f32_e32 v61, v61
	v_pk_fma_f32 v[62:63], v[70:71], v[110:111], v[62:63]
	v_add_f32_e32 v57, 1.0, v60
	v_rcp_f32_e32 v60, v57
	v_add_f32_e32 v57, 1.0, v61
	v_rcp_f32_e32 v61, v57
	v_pk_add_f32 v[62:63], v[74:75], v[62:63]
	v_pk_mul_f32 v[110:111], v[44:45], v[88:89]
	v_pk_mul_f32 v[58:59], v[58:59], v[60:61]
	s_nop 0
	v_pk_mul_f32 v[58:59], v[62:63], v[58:59]
	v_cndmask_b32_e64 v60, v41, v33, s[6:7]
	v_cvt_pk_bf16_f32 v57, v58, v59
	s_cmp_eq_u32 s98, 2
	s_cbranch_scc1 .Lp9h_st5
	global_store_dwordx2 v[152:153], v[56:57], off offset:32
.Lp9h_st5:
	v_cndmask_b32_e64 v56, v44, v52, s[4:5]
	v_cndmask_b32_e64 v57, v44, v36, s[6:7]
	s_nop 0
	v_mov_b32_dpp v52, v56 row_ror:1 row_mask:0xf bank_mask:0xf
	v_cndmask_b32_e64 v56, v40, v48, s[4:5]
	v_cndmask_b32_e64 v59, v45, v37, s[6:7]
	v_cndmask_b32_e64 v61, v46, v38, s[6:7]
	v_mov_b32_dpp v48, v56 row_ror:1 row_mask:0xf bank_mask:0xf
	v_cndmask_b32_e64 v63, v47, v39, s[6:7]
	v_mov_b32_dpp v56, v57 row_ror:15 row_mask:0xf bank_mask:0xf
	v_cndmask_b32_e64 v57, v40, v32, s[6:7]
	s_nop 1
	v_mov_b32_dpp v58, v57 row_ror:15 row_mask:0xf bank_mask:0xf
	v_cndmask_b32_e64 v57, v45, v53, s[4:5]
	s_nop 1
	v_mov_b32_dpp v53, v57 row_ror:1 row_mask:0xf bank_mask:0xf
	v_cndmask_b32_e64 v57, v41, v49, s[4:5]
	v_pk_fma_f32 v[52:53], v[64:65], v[52:53], v[110:111]
	s_nop 0
	v_mov_b32_dpp v49, v57 row_ror:1 row_mask:0xf bank_mask:0xf
	v_pk_fma_f32 v[48:49], v[76:77], v[48:49], v[106:107]
	s_nop 0
	v_mov_b32_dpp v57, v59 row_ror:15 row_mask:0xf bank_mask:0xf
	v_pk_fma_f32 v[52:53], v[68:69], v[56:57], v[52:53]
	v_cndmask_b32_e64 v56, v35, 0, s[6:7]
	v_mov_b32_dpp v59, v60 row_ror:15 row_mask:0xf bank_mask:0xf
	v_pk_fma_f32 v[48:49], v[80:81], v[58:59], v[48:49]
	v_cndmask_b32_e64 v60, v46, v54, s[4:5]
	v_pk_add_f32 v[48:49], v[84:85], v[48:49]
	s_nop 0
	v_mul_f32_e32 v58, 0xbfb8aa3b, v48
	v_mul_f32_e32 v107, 0xbfb8aa3b, v49
	v_mov_b32_dpp v54, v60 row_ror:1 row_mask:0xf bank_mask:0xf
	v_cndmask_b32_e64 v60, v42, v50, s[4:5]
	v_exp_f32_e32 v106, v58
	v_exp_f32_e32 v107, v107
	v_mov_b32_dpp v50, v60 row_ror:1 row_mask:0xf bank_mask:0xf
	v_add_f32_e32 v106, 1.0, v106
	v_add_f32_e32 v107, 1.0, v107
	v_mov_b32_dpp v60, v61 row_ror:15 row_mask:0xf bank_mask:0xf
	v_cndmask_b32_e64 v61, v42, v34, s[6:7]
	v_rcp_f32_e32 v106, v106
	v_rcp_f32_e32 v107, v107
	v_mov_b32_dpp v62, v61 row_ror:15 row_mask:0xf bank_mask:0xf
	v_cndmask_b32_e64 v61, v47, v55, s[4:5]
	v_pk_mul_f32 v[58:59], v[42:43], v[94:95]
	v_pk_add_f32 v[52:53], v[72:73], v[52:53]
	v_mov_b32_dpp v55, v61 row_ror:1 row_mask:0xf bank_mask:0xf
	v_cndmask_b32_e64 v61, v43, v51, s[4:5]
	v_pk_mul_f32 v[48:49], v[48:49], v[106:107]
	s_nop 0
	v_mov_b32_dpp v51, v61 row_ror:1 row_mask:0xf bank_mask:0xf
	v_pk_fma_f32 v[50:51], v[78:79], v[50:51], v[58:59]
	v_pk_mul_f32 v[48:49], v[52:53], v[48:49]
	v_mov_b32_dpp v61, v63 row_ror:15 row_mask:0xf bank_mask:0xf
	v_cvt_pk_bf16_f32 v48, v48, v49
	s_nop 0
	v_mov_b32_dpp v63, v108 row_ror:15 row_mask:0xf bank_mask:0xf
	v_pk_fma_f32 v[50:51], v[82:83], v[62:63], v[50:51]
	v_pk_mul_f32 v[108:109], v[46:47], v[90:91]
	v_pk_add_f32 v[50:51], v[86:87], v[50:51]
	v_pk_fma_f32 v[54:55], v[66:67], v[54:55], v[108:109]
	v_mul_f32_e32 v52, 0xbfb8aa3b, v50
	v_exp_f32_e32 v52, v52
	v_mul_f32_e32 v53, 0xbfb8aa3b, v51
	v_exp_f32_e32 v53, v53
	v_pk_fma_f32 v[54:55], v[70:71], v[60:61], v[54:55]
	v_add_f32_e32 v49, 1.0, v52
	v_rcp_f32_e32 v52, v49
	v_add_f32_e32 v49, 1.0, v53
	v_rcp_f32_e32 v53, v49
	v_pk_add_f32 v[54:55], v[74:75], v[54:55]
	v_pk_mul_f32 v[50:51], v[50:51], v[52:53]
	s_nop 0
	v_pk_mul_f32 v[50:51], v[54:55], v[50:51]
	v_cndmask_b32_e64 v52, v33, 0, s[6:7]
	v_cvt_pk_bf16_f32 v49, v50, v51
	s_cmp_eq_u32 s98, 2
	s_cbranch_scc1 .Lp9h_st6
	global_store_dwordx2 v[112:113], v[48:49], off offset:32
; __device__ __forceinline__ void st_bf4(bf16_t* p, f32x4 v) { u32x2 w; w.x = pk2(v[0], v[1]); w.y = pk2(v[2], v[3]); *(u32x2*)p = w; }
; __device__ __forceinline__ float sigmoidf_(float x) { return __builtin_amdgcn_rcpf(1.f + __expf(-x)); }
; __device__ __forceinline__ float dpp_ror1(float v) { return __int_as_float(__builtin_amdgcn_update_dpp(0, __float_as_int(v), 0x121, 0xf, 0xf, false)); }
; __device__ __forceinline__ float dpp_rol1(float v) { return __int_as_float(__builtin_amdgcn_update_dpp(0, __float_as_int(v), 0x12F, 0xf, 0xf, false)); }
;     __device__ __forceinline__ void tile(const f32x4 (&acc)[2][2][4][2], const Unit& u, int wr, int wc, int fr, int fq) const {
;     ...
;             const int cv = 128 * u.pn + 32 * wc + 16 * n + 4 * fq, cg = FF + cv;
;             const f32x4 wv0 = *(const f32x4*)(cw + cv), wv1 = *(const f32x4*)(cw + F2 + cv), wv2 = *(const f32x4*)(cw + 2 * F2 + cv), bv = *(const f32x4*)(cb + cv);
;             const f32x4 wg0 = *(const f32x4*)(cw + cg), wg1 = *(const f32x4*)(cw + F2 + cg), wg2 = *(const f32x4*)(cw + 2 * F2 + cg), bg = *(const f32x4*)(cb + cg);
; #pragma unroll
;             for (int ai = 0; ai < 2; ++ai)
; #pragma unroll
;                 for (int m = 0; m < 4; ++m) {
;                     f32x4 r;
; #pragma unroll
;                     for (int i = 0; i < 4; ++i) {
;                         const float xv = acc[ai][0][m][n][i], xg = acc[ai][1][m][n][i];
;                         const float uv = m > 0 ? acc[ai][0][m > 0 ? m - 1 : 0][n][i] : 0.f, ug = m > 0 ? acc[ai][1][m > 0 ? m - 1 : 0][n][i] : 0.f;
;                         const float dv = m < 3 ? acc[ai][0][m < 3 ? m + 1 : 3][n][i] : 0.f, dg = m < 3 ? acc[ai][1][m < 3 ? m + 1 : 3][n][i] : 0.f;
;                         const float pv = dpp_ror1(fr == 15 ? uv : xv), pg = dpp_ror1(fr == 15 ? ug : xg);
;                         const float nv = dpp_rol1(fr == 0 ? dv : xv), ng = dpp_rol1(fr == 0 ? dg : xg);
;                         const float yv = wv0[i] * pv + wv1[i] * xv + wv2[i] * nv + bv[i];
;                         const float yg = wg0[i] * pg + wg1[i] * xg + wg2[i] * ng + bg[i];
;                         r[i] = yg * sigmoidf_(yg) * yv;
;                     }
;                     st_bf4(ACT + (size_t)(u.pm * BM + ai * HALF + wr * 64 + m * 16 + fr) * FF + cv, r);
.Lp9h_st6:
	v_cndmask_b32_e64 v48, v36, v44, s[4:5]
	v_cndmask_b32_e64 v49, v36, 0, s[6:7]
	s_nop 0
	v_mov_b32_dpp v44, v48 row_ror:1 row_mask:0xf bank_mask:0xf
	v_cndmask_b32_e64 v48, v32, v40, s[4:5]
	v_cndmask_b32_e64 v51, v37, 0, s[6:7]
	v_cndmask_b32_e64 v53, v38, 0, s[6:7]
	v_mov_b32_dpp v40, v48 row_ror:1 row_mask:0xf bank_mask:0xf
	v_cndmask_b32_e64 v55, v39, 0, s[6:7]
	v_mov_b32_dpp v48, v49 row_ror:15 row_mask:0xf bank_mask:0xf
	v_cndmask_b32_e64 v49, v32, 0, s[6:7]
	s_nop 1
	v_mov_b32_dpp v50, v49 row_ror:15 row_mask:0xf bank_mask:0xf
	v_cndmask_b32_e64 v49, v37, v45, s[4:5]
	v_pk_mul_f32 v[36:37], v[36:37], v[88:89]
	s_nop 0
	v_mov_b32_dpp v45, v49 row_ror:1 row_mask:0xf bank_mask:0xf
	v_cndmask_b32_e64 v49, v33, v41, s[4:5]
	v_pk_mul_f32 v[32:33], v[32:33], v[92:93]
	v_pk_fma_f32 v[36:37], v[64:65], v[44:45], v[36:37]
	v_mov_b32_dpp v41, v49 row_ror:1 row_mask:0xf bank_mask:0xf
	v_pk_fma_f32 v[32:33], v[76:77], v[40:41], v[32:33]
	v_mov_b32_dpp v49, v51 row_ror:15 row_mask:0xf bank_mask:0xf
	v_pk_fma_f32 v[36:37], v[68:69], v[48:49], v[36:37]
	v_pk_mul_f32 v[48:49], v[24:25], v[92:93]
	v_mov_b32_dpp v51, v52 row_ror:15 row_mask:0xf bank_mask:0xf
	v_pk_fma_f32 v[32:33], v[80:81], v[50:51], v[32:33]
	v_cndmask_b32_e64 v52, v38, v46, s[4:5]
	v_pk_add_f32 v[32:33], v[84:85], v[32:33]
	s_nop 0
	v_mul_f32_e32 v40, 0xbfb8aa3b, v32
	v_mul_f32_e32 v41, 0xbfb8aa3b, v33
	v_mov_b32_dpp v46, v52 row_ror:1 row_mask:0xf bank_mask:0xf
	v_cndmask_b32_e64 v52, v34, v42, s[4:5]
	v_exp_f32_e32 v40, v40
	v_exp_f32_e32 v41, v41
	v_mov_b32_dpp v42, v52 row_ror:1 row_mask:0xf bank_mask:0xf
	v_add_f32_e32 v40, 1.0, v40
	v_add_f32_e32 v41, 1.0, v41
	v_mov_b32_dpp v52, v53 row_ror:15 row_mask:0xf bank_mask:0xf
	v_cndmask_b32_e64 v53, v34, 0, s[6:7]
	v_rcp_f32_e32 v40, v40
	v_rcp_f32_e32 v41, v41
	v_mov_b32_dpp v54, v53 row_ror:15 row_mask:0xf bank_mask:0xf
	v_cndmask_b32_e64 v53, v39, v47, s[4:5]
	v_pk_add_f32 v[36:37], v[72:73], v[36:37]
	v_pk_mul_f32 v[32:33], v[32:33], v[40:41]
	v_mov_b32_dpp v47, v53 row_ror:1 row_mask:0xf bank_mask:0xf
	v_cndmask_b32_e64 v53, v35, v43, s[4:5]
	v_pk_mul_f32 v[34:35], v[34:35], v[94:95]
	v_pk_mul_f32 v[32:33], v[36:37], v[32:33]
	v_mov_b32_dpp v43, v53 row_ror:1 row_mask:0xf bank_mask:0xf
	v_pk_fma_f32 v[34:35], v[78:79], v[42:43], v[34:35]
	v_cvt_pk_bf16_f32 v32, v32, v33
	v_mov_b32_dpp v53, v55 row_ror:15 row_mask:0xf bank_mask:0xf
	v_pk_mul_f32 v[38:39], v[38:39], v[90:91]
	v_cndmask_b32_e64 v40, v25, v17, s[6:7]
	v_mov_b32_dpp v55, v56 row_ror:15 row_mask:0xf bank_mask:0xf
	v_pk_fma_f32 v[34:35], v[82:83], v[54:55], v[34:35]
	v_pk_fma_f32 v[38:39], v[66:67], v[46:47], v[38:39]
	v_pk_add_f32 v[34:35], v[86:87], v[34:35]
	v_pk_fma_f32 v[38:39], v[70:71], v[52:53], v[38:39]
	v_mul_f32_e32 v36, 0xbfb8aa3b, v34
	v_exp_f32_e32 v36, v36
	v_mul_f32_e32 v37, 0xbfb8aa3b, v35
	v_exp_f32_e32 v37, v37
	v_pk_add_f32 v[38:39], v[74:75], v[38:39]
	v_add_f32_e32 v33, 1.0, v36
	v_rcp_f32_e32 v36, v33
	v_add_f32_e32 v33, 1.0, v37
	v_rcp_f32_e32 v37, v33
	v_cndmask_b32_e64 v41, v30, 0, s[4:5]
	v_pk_mul_f32 v[34:35], v[34:35], v[36:37]
	s_nop 0
	v_pk_mul_f32 v[34:35], v[38:39], v[34:35]
	s_nop 0
	v_cvt_pk_bf16_f32 v33, v34, v35
	s_cmp_eq_u32 s98, 2
	s_cbranch_scc1 .Lp9h_st7
	global_store_dwordx2 v[96:97], v[32:33], off offset:32
.Lp9h_st7:
	v_cndmask_b32_e64 v33, v28, 0, s[4:5]
	v_cndmask_b32_e64 v35, v29, 0, s[4:5]
	s_nop 0
	v_mov_b32_dpp v32, v33 row_ror:1 row_mask:0xf bank_mask:0xf
	v_cndmask_b32_e64 v33, v24, 0, s[4:5]
	v_cndmask_b32_e64 v37, v25, 0, s[4:5]
	v_cndmask_b32_e64 v39, v29, v21, s[6:7]
	v_mov_b32_dpp v34, v33 row_ror:1 row_mask:0xf bank_mask:0xf
	v_cndmask_b32_e64 v33, v28, v20, s[6:7]
	v_cndmask_b32_e64 v43, v31, 0, s[4:5]
	v_pk_mul_f32 v[52:53], v[28:29], v[88:89]
	v_mov_b32_dpp v36, v33 row_ror:15 row_mask:0xf bank_mask:0xf
	v_cndmask_b32_e64 v33, v24, v16, s[6:7]
	v_cndmask_b32_e64 v45, v27, 0, s[4:5]
	v_cndmask_b32_e64 v47, v31, v23, s[6:7]
	v_mov_b32_dpp v38, v33 row_ror:15 row_mask:0xf bank_mask:0xf
	v_cndmask_b32_e64 v50, v27, v19, s[6:7]
	s_nop 0
	v_mov_b32_dpp v33, v35 row_ror:1 row_mask:0xf bank_mask:0xf
	v_pk_fma_f32 v[32:33], v[64:65], v[32:33], v[52:53]
	s_nop 0
	v_mov_b32_dpp v35, v37 row_ror:1 row_mask:0xf bank_mask:0xf
	v_pk_fma_f32 v[34:35], v[76:77], v[34:35], v[48:49]
	s_nop 0
	v_mov_b32_dpp v37, v39 row_ror:15 row_mask:0xf bank_mask:0xf
	v_pk_fma_f32 v[32:33], v[68:69], v[36:37], v[32:33]
	s_nop 0
	v_mov_b32_dpp v39, v40 row_ror:15 row_mask:0xf bank_mask:0xf
	v_pk_fma_f32 v[34:35], v[80:81], v[38:39], v[34:35]
	s_nop 0
	v_pk_add_f32 v[34:35], v[84:85], v[34:35]
	v_pk_add_f32 v[32:33], v[72:73], v[32:33]
	v_mul_f32_e32 v38, 0xbfb8aa3b, v34
	v_mul_f32_e32 v49, 0xbfb8aa3b, v35
	v_exp_f32_e32 v48, v38
	v_exp_f32_e32 v49, v49
	v_mov_b32_dpp v40, v41 row_ror:1 row_mask:0xf bank_mask:0xf
	v_cndmask_b32_e64 v41, v26, 0, s[4:5]
	v_add_f32_e32 v48, 1.0, v48
	v_add_f32_e32 v49, 1.0, v49
	v_mov_b32_dpp v42, v41 row_ror:1 row_mask:0xf bank_mask:0xf
	v_cndmask_b32_e64 v41, v30, v22, s[6:7]
	v_rcp_f32_e32 v48, v48
	v_rcp_f32_e32 v49, v49
	v_mov_b32_dpp v44, v41 row_ror:15 row_mask:0xf bank_mask:0xf
	v_cndmask_b32_e64 v41, v26, v18, s[6:7]
	v_pk_mul_f32 v[38:39], v[26:27], v[94:95]
	v_pk_mul_f32 v[34:35], v[34:35], v[48:49]
	v_mov_b32_dpp v46, v41 row_ror:15 row_mask:0xf bank_mask:0xf
	v_pk_mul_f32 v[32:33], v[32:33], v[34:35]
	s_nop 0
	v_mov_b32_dpp v41, v43 row_ror:1 row_mask:0xf bank_mask:0xf
	v_cvt_pk_bf16_f32 v32, v32, v33
	s_nop 0
	v_mov_b32_dpp v43, v45 row_ror:1 row_mask:0xf bank_mask:0xf
	v_pk_fma_f32 v[34:35], v[78:79], v[42:43], v[38:39]
	v_cndmask_b32_e64 v42, v19, v11, s[6:7]
	v_mov_b32_dpp v45, v47 row_ror:15 row_mask:0xf bank_mask:0xf
	s_nop 1
	v_mov_b32_dpp v47, v50 row_ror:15 row_mask:0xf bank_mask:0xf
	v_pk_fma_f32 v[34:35], v[82:83], v[46:47], v[34:35]
	v_pk_mul_f32 v[50:51], v[30:31], v[90:91]
	v_pk_add_f32 v[34:35], v[86:87], v[34:35]
	v_pk_fma_f32 v[38:39], v[66:67], v[40:41], v[50:51]
	v_mul_f32_e32 v36, 0xbfb8aa3b, v34
	v_exp_f32_e32 v36, v36
	v_mul_f32_e32 v37, 0xbfb8aa3b, v35
	v_exp_f32_e32 v37, v37
	v_pk_fma_f32 v[38:39], v[70:71], v[44:45], v[38:39]
	v_add_f32_e32 v33, 1.0, v36
	v_rcp_f32_e32 v36, v33
	v_add_f32_e32 v33, 1.0, v37
	v_rcp_f32_e32 v37, v33
	v_pk_add_f32 v[38:39], v[74:75], v[38:39]
	v_pk_mul_f32 v[40:41], v[16:17], v[92:93]
	v_pk_mul_f32 v[44:45], v[20:21], v[88:89]
	v_pk_mul_f32 v[34:35], v[34:35], v[36:37]
	v_cndmask_b32_e64 v36, v17, v9, s[6:7]
	v_pk_mul_f32 v[34:35], v[38:39], v[34:35]
	v_cndmask_b32_e64 v37, v22, v14, s[6:7]
	v_cvt_pk_bf16_f32 v33, v34, v35
	s_cmp_eq_u32 s98, 1
	s_cbranch_scc1 .Lp9h_st12
	global_store_dwordx2 v[98:99], v[32:33], off offset:32
; __device__ __forceinline__ void st_bf4(bf16_t* p, f32x4 v) { u32x2 w; w.x = pk2(v[0], v[1]); w.y = pk2(v[2], v[3]); *(u32x2*)p = w; }
; __device__ __forceinline__ float sigmoidf_(float x) { return __builtin_amdgcn_rcpf(1.f + __expf(-x)); }
; __device__ __forceinline__ float dpp_ror1(float v) { return __int_as_float(__builtin_amdgcn_update_dpp(0, __float_as_int(v), 0x121, 0xf, 0xf, false)); }
; __device__ __forceinline__ float dpp_rol1(float v) { return __int_as_float(__builtin_amdgcn_update_dpp(0, __float_as_int(v), 0x12F, 0xf, 0xf, false)); }
;     __device__ __forceinline__ void tile(const f32x4 (&acc)[2][2][4][2], const Unit& u, int wr, int wc, int fr, int fq) const {
;     ...
;             const int cv = 128 * u.pn + 32 * wc + 16 * n + 4 * fq, cg = FF + cv;
;             const f32x4 wv0 = *(const f32x4*)(cw + cv), wv1 = *(const f32x4*)(cw + F2 + cv), wv2 = *(const f32x4*)(cw + 2 * F2 + cv), bv = *(const f32x4*)(cb + cv);
;             const f32x4 wg0 = *(const f32x4*)(cw + cg), wg1 = *(const f32x4*)(cw + F2 + cg), wg2 = *(const f32x4*)(cw + 2 * F2 + cg), bg = *(const f32x4*)(cb + cg);
; #pragma unroll
;             for (int ai = 0; ai < 2; ++ai)
; #pragma unroll
;                 for (int m = 0; m < 4; ++m) {
;                     f32x4 r;
; #pragma unroll
;                     for (int i = 0; i < 4; ++i) {
;                         const float xv = acc[ai][0][m][n][i], xg = acc[ai][1][m][n][i];
;                         const float uv = m > 0 ? acc[ai][0][m > 0 ? m - 1 : 0][n][i] : 0.f, ug = m > 0 ? acc[ai][1][m > 0 ? m - 1 : 0][n][i] : 0.f;
;                         const float dv = m < 3 ? acc[ai][0][m < 3 ? m + 1 : 3][n][i] : 0.f, dg = m < 3 ? acc[ai][1][m < 3 ? m + 1 : 3][n][i] : 0.f;
;                         const float pv = dpp_ror1(fr == 15 ? uv : xv), pg = dpp_ror1(fr == 15 ? ug : xg);
;                         const float nv = dpp_rol1(fr == 0 ? dv : xv), ng = dpp_rol1(fr == 0 ? dg : xg);
;                         const float yv = wv0[i] * pv + wv1[i] * xv + wv2[i] * nv + bv[i];
;                         const float yg = wg0[i] * pg + wg1[i] * xg + wg2[i] * ng + bg[i];
;                         r[i] = yg * sigmoidf_(yg) * yv;
;                     }
;                     st_bf4(ACT + (size_t)(u.pm * BM + ai * HALF + wr * 64 + m * 16 + fr) * FF + cv, r);
.Lp9h_st12:
	v_cndmask_b32_e64 v32, v20, v28, s[4:5]
	v_cndmask_b32_e64 v33, v20, v12, s[6:7]
	s_nop 0
	v_mov_b32_dpp v28, v32 row_ror:1 row_mask:0xf bank_mask:0xf
	v_cndmask_b32_e64 v32, v16, v24, s[4:5]
	v_cndmask_b32_e64 v35, v21, v13, s[6:7]
	s_nop 0
	v_mov_b32_dpp v24, v32 row_ror:1 row_mask:0xf bank_mask:0xf
	v_cndmask_b32_e64 v39, v23, v15, s[6:7]
	s_nop 0
	v_mov_b32_dpp v32, v33 row_ror:15 row_mask:0xf bank_mask:0xf
	v_cndmask_b32_e64 v33, v16, v8, s[6:7]
	s_nop 1
	v_mov_b32_dpp v34, v33 row_ror:15 row_mask:0xf bank_mask:0xf
	v_cndmask_b32_e64 v33, v21, v29, s[4:5]
	s_nop 1
	v_mov_b32_dpp v29, v33 row_ror:1 row_mask:0xf bank_mask:0xf
	v_cndmask_b32_e64 v33, v17, v25, s[4:5]
	v_pk_fma_f32 v[28:29], v[64:65], v[28:29], v[44:45]
	s_nop 0
	v_mov_b32_dpp v25, v33 row_ror:1 row_mask:0xf bank_mask:0xf
	v_pk_fma_f32 v[24:25], v[76:77], v[24:25], v[40:41]
	s_nop 0
	v_mov_b32_dpp v33, v35 row_ror:15 row_mask:0xf bank_mask:0xf
	v_pk_fma_f32 v[28:29], v[68:69], v[32:33], v[28:29]
	v_pk_mul_f32 v[32:33], v[8:9], v[92:93]
	v_mov_b32_dpp v35, v36 row_ror:15 row_mask:0xf bank_mask:0xf
	v_pk_fma_f32 v[24:25], v[80:81], v[34:35], v[24:25]
	v_cndmask_b32_e64 v36, v22, v30, s[4:5]
	v_pk_add_f32 v[24:25], v[84:85], v[24:25]
	s_nop 0
	v_mul_f32_e32 v34, 0xbfb8aa3b, v24
	v_mul_f32_e32 v41, 0xbfb8aa3b, v25
	v_mov_b32_dpp v30, v36 row_ror:1 row_mask:0xf bank_mask:0xf
	v_cndmask_b32_e64 v36, v18, v26, s[4:5]
	v_exp_f32_e32 v40, v34
	v_exp_f32_e32 v41, v41
	v_mov_b32_dpp v26, v36 row_ror:1 row_mask:0xf bank_mask:0xf
	v_add_f32_e32 v40, 1.0, v40
	v_add_f32_e32 v41, 1.0, v41
	v_mov_b32_dpp v36, v37 row_ror:15 row_mask:0xf bank_mask:0xf
	v_cndmask_b32_e64 v37, v18, v10, s[6:7]
	v_rcp_f32_e32 v40, v40
	v_rcp_f32_e32 v41, v41
	v_mov_b32_dpp v38, v37 row_ror:15 row_mask:0xf bank_mask:0xf
	v_cndmask_b32_e64 v37, v23, v31, s[4:5]
	v_pk_mul_f32 v[34:35], v[18:19], v[94:95]
	v_pk_add_f32 v[28:29], v[72:73], v[28:29]
	v_mov_b32_dpp v31, v37 row_ror:1 row_mask:0xf bank_mask:0xf
	v_cndmask_b32_e64 v37, v19, v27, s[4:5]
	v_pk_mul_f32 v[24:25], v[24:25], v[40:41]
	s_nop 0
	v_mov_b32_dpp v27, v37 row_ror:1 row_mask:0xf bank_mask:0xf
	v_pk_fma_f32 v[26:27], v[78:79], v[26:27], v[34:35]
	v_pk_mul_f32 v[24:25], v[28:29], v[24:25]
	v_mov_b32_dpp v37, v39 row_ror:15 row_mask:0xf bank_mask:0xf
	v_cvt_pk_bf16_f32 v24, v24, v25
	v_cndmask_b32_e64 v34, v11, v3, s[6:7]
	v_mov_b32_dpp v39, v42 row_ror:15 row_mask:0xf bank_mask:0xf
	v_pk_fma_f32 v[26:27], v[82:83], v[38:39], v[26:27]
	v_pk_mul_f32 v[42:43], v[22:23], v[90:91]
	v_pk_add_f32 v[26:27], v[86:87], v[26:27]
	v_pk_fma_f32 v[30:31], v[66:67], v[30:31], v[42:43]
	v_mul_f32_e32 v28, 0xbfb8aa3b, v26
	v_exp_f32_e32 v28, v28
	v_mul_f32_e32 v29, 0xbfb8aa3b, v27
	v_exp_f32_e32 v29, v29
	v_pk_fma_f32 v[30:31], v[70:71], v[36:37], v[30:31]
	v_add_f32_e32 v25, 1.0, v28
	v_rcp_f32_e32 v28, v25
	v_add_f32_e32 v25, 1.0, v29
	v_rcp_f32_e32 v29, v25
	v_pk_add_f32 v[30:31], v[74:75], v[30:31]
	v_pk_mul_f32 v[36:37], v[12:13], v[88:89]
	v_pk_mul_f32 v[26:27], v[26:27], v[28:29]
	s_nop 0
	v_pk_mul_f32 v[26:27], v[30:31], v[26:27]
	v_cndmask_b32_e64 v28, v9, v1, s[6:7]
	v_cvt_pk_bf16_f32 v25, v26, v27
	s_cmp_eq_u32 s98, 1
	s_cbranch_scc1 .Lp9h_st13
	global_store_dwordx2 v[100:101], v[24:25], off offset:32
;     __device__ __forceinline__ void tile(const f32x4 (&acc)[2][2][4][2], const Unit& u, int wr, int wc, int fr, int fq) const {
;     ...
;             const int cv = 128 * u.pn + 32 * wc + 16 * n + 4 * fq, cg = FF + cv;
;             const f32x4 wv0 = *(const f32x4*)(cw + cv), wv1 = *(const f32x4*)(cw + F2 + cv), wv2 = *(const f32x4*)(cw + 2 * F2 + cv), bv = *(const f32x4*)(cb + cv);
;             const f32x4 wg0 = *(const f32x4*)(cw + cg), wg1 = *(const f32x4*)(cw + F2 + cg), wg2 = *(const f32x4*)(cw + 2 * F2 + cg), bg = *(const f32x4*)(cb + cg);
; #pragma unroll
;             for (int ai = 0; ai < 2; ++ai)
; #pragma unroll
;                 for (int m = 0; m < 4; ++m) {
;                     f32x4 r;
; #pragma unroll
;                     for (int i = 0; i < 4; ++i) {
;                         const float xv = acc[ai][0][m][n][i], xg = acc[ai][1][m][n][i];
;                         const float uv = m > 0 ? acc[ai][0][m > 0 ? m - 1 : 0][n][i] : 0.f, ug = m > 0 ? acc[ai][1][m > 0 ? m - 1 : 0][n][i] : 0.f;
;                         const float dv = m < 3 ? acc[ai][0][m < 3 ? m + 1 : 3][n][i] : 0.f, dg = m < 3 ? acc[ai][1][m < 3 ? m + 1 : 3][n][i] : 0.f;
;                         const float pv = dpp_ror1(fr == 15 ? uv : xv), pg = dpp_ror1(fr == 15 ? ug : xg);
;                         const float nv = dpp_rol1(fr == 0 ? dv : xv), ng = dpp_rol1(fr == 0 ? dg : xg);
;                         const float yv = wv0[i] * pv + wv1[i] * xv + wv2[i] * nv + bv[i];
;                         const float yg = wg0[i] * pg + wg1[i] * xg + wg2[i] * ng + bg[i];
;                         r[i] = yg * sigmoidf_(yg) * yv;
;                     }
;                     st_bf4(ACT + (size_t)(u.pm * BM + ai * HALF + wr * 64 + m * 16 + fr) * FF + cv, r);
; template <class Epi, class Sched, bool DEFER>
; __device__ __forceinline__ void gemm_fast_core(LAS unsigned char* lds, const GemmP g, const Sched& S, const Epi& E, f32x4 (&acc)[2][2][4][2], Unit& cur) {
;     ...
;         if (!has_next) break;
; #pragma unroll
;         for (int a = 0; a < 2; ++a)
; #pragma unroll
;             for (int b = 0; b < 2; ++b)
; #pragma unroll
;                 for (int m = 0; m < 4; ++m)
; #pragma unroll
;                     for (int n = 0; n < 2; ++n) acc[a][b][m][n] = (f32x4){0.f, 0.f, 0.f, 0.f};
;         cur = nxt; cA = nA; cB = nB; ++ui;
;         if (wr == 1) PG8_BAR;
;     }
.Lp9h_st13:
	v_cndmask_b32_e64 v24, v12, v20, s[4:5]
	v_cndmask_b32_e64 v25, v12, v4, s[6:7]
	s_nop 0
	v_mov_b32_dpp v20, v24 row_ror:1 row_mask:0xf bank_mask:0xf
	v_cndmask_b32_e64 v24, v8, v16, s[4:5]
	v_cndmask_b32_e64 v27, v13, v5, s[6:7]
	v_cndmask_b32_e64 v29, v14, v6, s[6:7]
	v_mov_b32_dpp v16, v24 row_ror:1 row_mask:0xf bank_mask:0xf
	v_cndmask_b32_e64 v31, v15, v7, s[6:7]
	v_mov_b32_dpp v24, v25 row_ror:15 row_mask:0xf bank_mask:0xf
	v_cndmask_b32_e64 v25, v8, v0, s[6:7]
	s_nop 1
	v_mov_b32_dpp v26, v25 row_ror:15 row_mask:0xf bank_mask:0xf
	v_cndmask_b32_e64 v25, v13, v21, s[4:5]
	s_nop 1
	v_mov_b32_dpp v21, v25 row_ror:1 row_mask:0xf bank_mask:0xf
	v_cndmask_b32_e64 v25, v9, v17, s[4:5]
	v_pk_fma_f32 v[20:21], v[64:65], v[20:21], v[36:37]
	s_nop 0
	v_mov_b32_dpp v17, v25 row_ror:1 row_mask:0xf bank_mask:0xf
	v_pk_fma_f32 v[16:17], v[76:77], v[16:17], v[32:33]
	s_nop 0
	v_mov_b32_dpp v25, v27 row_ror:15 row_mask:0xf bank_mask:0xf
	v_pk_fma_f32 v[20:21], v[68:69], v[24:25], v[20:21]
	v_cndmask_b32_e64 v24, v3, 0, s[6:7]
	v_mov_b32_dpp v27, v28 row_ror:15 row_mask:0xf bank_mask:0xf
	v_pk_fma_f32 v[16:17], v[80:81], v[26:27], v[16:17]
	v_cndmask_b32_e64 v28, v14, v22, s[4:5]
	v_pk_add_f32 v[16:17], v[84:85], v[16:17]
	s_nop 0
	v_mul_f32_e32 v26, 0xbfb8aa3b, v16
	v_mul_f32_e32 v33, 0xbfb8aa3b, v17
	v_mov_b32_dpp v22, v28 row_ror:1 row_mask:0xf bank_mask:0xf
	v_cndmask_b32_e64 v28, v10, v18, s[4:5]
	v_exp_f32_e32 v32, v26
	v_exp_f32_e32 v33, v33
	v_mov_b32_dpp v18, v28 row_ror:1 row_mask:0xf bank_mask:0xf
	v_add_f32_e32 v32, 1.0, v32
	v_add_f32_e32 v33, 1.0, v33
	v_mov_b32_dpp v28, v29 row_ror:15 row_mask:0xf bank_mask:0xf
	v_cndmask_b32_e64 v29, v10, v2, s[6:7]
	v_rcp_f32_e32 v32, v32
	v_rcp_f32_e32 v33, v33
	v_mov_b32_dpp v30, v29 row_ror:15 row_mask:0xf bank_mask:0xf
	v_cndmask_b32_e64 v29, v15, v23, s[4:5]
	v_pk_mul_f32 v[26:27], v[10:11], v[94:95]
	v_pk_add_f32 v[20:21], v[72:73], v[20:21]
	v_mov_b32_dpp v23, v29 row_ror:1 row_mask:0xf bank_mask:0xf
	v_cndmask_b32_e64 v29, v11, v19, s[4:5]
	v_pk_mul_f32 v[16:17], v[16:17], v[32:33]
	s_nop 0
	v_mov_b32_dpp v19, v29 row_ror:1 row_mask:0xf bank_mask:0xf
	v_pk_fma_f32 v[18:19], v[78:79], v[18:19], v[26:27]
	v_pk_mul_f32 v[16:17], v[20:21], v[16:17]
	v_mov_b32_dpp v29, v31 row_ror:15 row_mask:0xf bank_mask:0xf
	v_cvt_pk_bf16_f32 v16, v16, v17
	s_nop 0
	v_mov_b32_dpp v31, v34 row_ror:15 row_mask:0xf bank_mask:0xf
	v_pk_fma_f32 v[18:19], v[82:83], v[30:31], v[18:19]
	v_pk_mul_f32 v[34:35], v[14:15], v[90:91]
	v_pk_add_f32 v[18:19], v[86:87], v[18:19]
	v_pk_fma_f32 v[22:23], v[66:67], v[22:23], v[34:35]
	v_mul_f32_e32 v20, 0xbfb8aa3b, v18
	v_exp_f32_e32 v20, v20
	v_mul_f32_e32 v21, 0xbfb8aa3b, v19
	v_exp_f32_e32 v21, v21
	v_pk_fma_f32 v[22:23], v[70:71], v[28:29], v[22:23]
	v_add_f32_e32 v17, 1.0, v20
	v_rcp_f32_e32 v20, v17
	v_add_f32_e32 v17, 1.0, v21
	v_rcp_f32_e32 v21, v17
	v_pk_add_f32 v[22:23], v[74:75], v[22:23]
	v_pk_mul_f32 v[18:19], v[18:19], v[20:21]
	s_nop 0
	v_pk_mul_f32 v[18:19], v[22:23], v[18:19]
	v_cndmask_b32_e64 v20, v1, 0, s[6:7]
	v_cvt_pk_bf16_f32 v17, v18, v19
	s_cmp_eq_u32 s98, 1
	s_cbranch_scc1 .Lp9h_st14
	global_store_dwordx2 v[102:103], v[16:17], off offset:32
.Lp9h_st14:
	v_cndmask_b32_e64 v16, v4, v12, s[4:5]
	v_cndmask_b32_e64 v17, v4, 0, s[6:7]
	s_nop 0
	v_mov_b32_dpp v12, v16 row_ror:1 row_mask:0xf bank_mask:0xf
	v_cndmask_b32_e64 v16, v0, v8, s[4:5]
	v_cndmask_b32_e64 v19, v5, 0, s[6:7]
	v_cndmask_b32_e64 v21, v6, 0, s[6:7]
	v_mov_b32_dpp v8, v16 row_ror:1 row_mask:0xf bank_mask:0xf
	v_cndmask_b32_e64 v23, v7, 0, s[6:7]
	v_mov_b32_dpp v16, v17 row_ror:15 row_mask:0xf bank_mask:0xf
	v_cndmask_b32_e64 v17, v0, 0, s[6:7]
	s_nop 1
	v_mov_b32_dpp v18, v17 row_ror:15 row_mask:0xf bank_mask:0xf
	v_cndmask_b32_e64 v17, v5, v13, s[4:5]
	v_pk_mul_f32 v[4:5], v[4:5], v[88:89]
	s_nop 0
	v_mov_b32_dpp v13, v17 row_ror:1 row_mask:0xf bank_mask:0xf
	v_cndmask_b32_e64 v17, v1, v9, s[4:5]
	v_pk_mul_f32 v[0:1], v[0:1], v[92:93]
	v_pk_fma_f32 v[4:5], v[64:65], v[12:13], v[4:5]
	v_mov_b32_dpp v9, v17 row_ror:1 row_mask:0xf bank_mask:0xf
	v_pk_fma_f32 v[0:1], v[76:77], v[8:9], v[0:1]
	s_nop 0
	v_mov_b32_dpp v17, v19 row_ror:15 row_mask:0xf bank_mask:0xf
	v_pk_fma_f32 v[4:5], v[68:69], v[16:17], v[4:5]
	s_nop 0
	v_mov_b32_dpp v19, v20 row_ror:15 row_mask:0xf bank_mask:0xf
	v_pk_fma_f32 v[0:1], v[80:81], v[18:19], v[0:1]
	v_cndmask_b32_e64 v20, v6, v14, s[4:5]
	v_pk_add_f32 v[0:1], v[84:85], v[0:1]
	s_nop 0
	v_mul_f32_e32 v8, 0xbfb8aa3b, v1
	v_exp_f32_e32 v8, v8
	v_mul_f32_e32 v9, 0xbfb8aa3b, v0
	v_mov_b32_dpp v14, v20 row_ror:1 row_mask:0xf bank_mask:0xf
	v_cndmask_b32_e64 v20, v2, v10, s[4:5]
	v_exp_f32_e32 v18, v9
	v_add_f32_e32 v8, 1.0, v8
	v_mov_b32_dpp v10, v20 row_ror:1 row_mask:0xf bank_mask:0xf
	v_rcp_f32_e32 v9, v8
	v_add_f32_e32 v8, 1.0, v18
	v_mov_b32_dpp v20, v21 row_ror:15 row_mask:0xf bank_mask:0xf
	v_cndmask_b32_e64 v21, v2, 0, s[6:7]
	v_rcp_f32_e32 v8, v8
	v_pk_add_f32 v[4:5], v[72:73], v[4:5]
	v_mov_b32_dpp v22, v21 row_ror:15 row_mask:0xf bank_mask:0xf
	v_cndmask_b32_e64 v21, v7, v15, s[4:5]
	v_pk_mul_f32 v[0:1], v[0:1], v[8:9]
	v_pk_mul_f32 v[6:7], v[6:7], v[90:91]
	v_mov_b32_dpp v15, v21 row_ror:1 row_mask:0xf bank_mask:0xf
	v_cndmask_b32_e64 v21, v3, v11, s[4:5]
	v_pk_mul_f32 v[2:3], v[2:3], v[94:95]
	v_pk_mul_f32 v[0:1], v[4:5], v[0:1]
	v_mov_b32_dpp v11, v21 row_ror:1 row_mask:0xf bank_mask:0xf
	v_pk_fma_f32 v[2:3], v[78:79], v[10:11], v[2:3]
	v_cvt_pk_bf16_f32 v0, v0, v1
	v_mov_b32_dpp v21, v23 row_ror:15 row_mask:0xf bank_mask:0xf
	v_pk_fma_f32 v[6:7], v[66:67], v[14:15], v[6:7]
	s_nop 0
	v_mov_b32_dpp v23, v24 row_ror:15 row_mask:0xf bank_mask:0xf
	v_pk_fma_f32 v[2:3], v[82:83], v[22:23], v[2:3]
	v_pk_fma_f32 v[6:7], v[70:71], v[20:21], v[6:7]
	v_pk_add_f32 v[2:3], v[86:87], v[2:3]
	v_pk_add_f32 v[6:7], v[74:75], v[6:7]
	v_mul_f32_e32 v4, 0xbfb8aa3b, v2
	v_exp_f32_e32 v4, v4
	v_mul_f32_e32 v5, 0xbfb8aa3b, v3
	v_exp_f32_e32 v5, v5
	v_add_f32_e32 v1, 1.0, v4
	v_rcp_f32_e32 v4, v1
	v_add_f32_e32 v1, 1.0, v5
	v_rcp_f32_e32 v5, v1
	s_nop 0
	v_pk_mul_f32 v[2:3], v[2:3], v[4:5]
	s_nop 0
	v_pk_mul_f32 v[2:3], v[6:7], v[2:3]
	s_nop 0
	v_cvt_pk_bf16_f32 v1, v2, v3
	s_cmp_eq_u32 s98, 1
	s_cbranch_scc1 .Lp9h_st15
	global_store_dwordx2 v[104:105], v[0:1], off offset:32
.Lp9h_st15:
	s_cbranch_vccnz .LBB0_1795
	s_andn2_b64 vcc, exec, s[2:3]
	s_cbranch_vccnz .LBB0_1794
	s_barrier
	s_branch .LBB0_1794

; #define LAS __attribute__((address_space(3)))
; __device__ __forceinline__ void transpose_item(const float* W, int K, int N, bf16_t* WT, int drow0, LAS float* scr, int k0, int n0, int lane) {
; #pragma unroll 8
;     for (int i = 0; i < 32; ++i) { const int kk = 2 * i + (lane >> 5); scr[kk * 33 + (lane & 31)] = W[(size_t)(k0 + kk) * N + n0 + (lane & 31)]; }
; __global__ void __launch_bounds__(NTHR, 2) fwd_kernel(Args a) {
;     ...
;     if (bx >= 128) {
;         PHASE_IDS
;         LAS float* scr = (LAS float*)(lds + wave * 16384);
;         for (int r = (bx - 128) * 8 + wave; r < 88 * 64; r += (G - 128) * 8)
;             transpose_item(a.in[I_WDN], FF, DM, WdT, (r % 64) * 32, scr, (r / 64) * 64, (r % 64) * 32, lane);
.LBB0_1806:
	s_add_u32 s4, s66, 0x5e00000
	s_addc_u32 s5, s67, 0
	v_mov_b32_e32 v1, v189
	v_readlane_b32 s3, v254, 37
	v_readfirstlane_b32 s2, v1
	s_ashr_i32 s2, s2, 6
	s_add_i32 s3, s3, s2
	s_mov_b32 s8, s3
	s_cmpk_gt_i32 s8, 0x15ff
	s_cbranch_scc1 .LBB0_1812
	s_lshl_b32 s2, s2, 14
	v_bfe_u32 v0, v1, 5, 1
	v_lshlrev_b32_e32 v2, 2, v1
	v_bfe_u32 v5, v1, 3, 3
	v_lshlrev_b32_e32 v1, 3, v1
	s_add_i32 s2, s2, 0
	v_and_b32_e32 v6, 0x7c, v2
	v_mov_b32_e32 v7, 0
	v_and_b32_e32 v1, 56, v1
	v_lshl_add_u64 v[2:3], s[60:61], 0, v[6:7]
	v_add_u32_e32 v4, s2, v6
	v_mul_u32_u24_e32 v8, 0x84, v1
	v_lshlrev_b32_e32 v6, 1, v1
	v_lshlrev_b32_e32 v1, 2, v5
	s_movk_i32 s9, 0x84
	v_lshl_add_u64 v[6:7], s[4:5], 0, v[6:7]
	v_add3_u32 v10, s2, v8, v1
	v_or_b32_e32 v11, 8, v5
	v_or_b32_e32 v12, 16, v5
	v_or_b32_e32 v13, 24, v5
	s_mov_b32 s10, s94
	v_mov_b32_e32 v1, v0
	s_movk_i32 s11, 0x1600
